# mode-3 gated-merge epilogue pipelined (3 groups of loads in flight) + packed f32 adds in attention softmax split into scalar adds
# baseline (speedup 1.0000x reference)
; #define LAS __attribute__((address_space(3)))
; DI unsigned pk2(float lo, float hi) { f32x2 v = {lo, hi}; bf16x2_t b = __builtin_convertvector(v, bf16x2_t); return __builtin_bit_cast(unsigned, b); }
; DI void att_sm_tail(f32x16 (&S)[2], bf16x8 (&pkm)[2][2], const float mrefm, float& lrunm) {
;     {
;         f32x16& s0 = S[0]; f32x16& s1 = S[1];
;         const f32x2 nm2 = {-mrefm, -mrefm};
;         f32x2 acc2 = {0.f, 0.f};
; #pragma unroll
;         for (int i = 0; i < 16; i += 2) {
;             f32x2 a = {s0[i], s0[i + 1]}, b = {s1[i], s1[i + 1]}; a += nm2; b += nm2;
;             a.x = fast_exp2(a.x); a.y = fast_exp2(a.y); b.x = fast_exp2(b.x); b.y = fast_exp2(b.y);
;             acc2 += a; acc2 += b; s0[i] = a.x; s0[i + 1] = a.y; s1[i] = b.x; s1[i + 1] = b.y;
;         }
;         lrunm += acc2.x + acc2.y;
; #pragma unroll
;         for (int s = 0; s < 2; ++s) {
;             u32x4 w0, w1;
;             w0.x = pk2(s0[8 * s + 0], s0[8 * s + 1]); w0.y = pk2(s0[8 * s + 2], s0[8 * s + 3]); w0.z = pk2(s0[8 * s + 4], s0[8 * s + 5]); w0.w = pk2(s0[8 * s + 6], s0[8 * s + 7]);
;             w1.x = pk2(s1[8 * s + 0], s1[8 * s + 1]); w1.y = pk2(s1[8 * s + 2], s1[8 * s + 3]); w1.z = pk2(s1[8 * s + 4], s1[8 * s + 5]); w1.w = pk2(s1[8 * s + 6], s1[8 * s + 7]);
;             pkm[0][s] = __builtin_bit_cast(bf16x8, w0); pkm[1][s] = __builtin_bit_cast(bf16x8, w1);
;         }
;     }
; }
; DI void att_vload(const LAS unsigned char* vb, int e, s16x4 (&lo)[4], s16x4 (&hi)[4]) {
;     constexpr int VP = 144;
; #pragma unroll
;     for (int q = 0; q < 4; ++q) { const LAS unsigned char* p = vb + (16 * q) * VP + 64 * e;
;         lo[q] = __builtin_bit_cast(s16x4, __builtin_amdgcn_ds_read_tr16_b64_v4i16((LAS s16x4*)p));
;         hi[q] = __builtin_bit_cast(s16x4, __builtin_amdgcn_ds_read_tr16_b64_v4i16((LAS s16x4*)(p + 8 * VP))); }
; }
; template <int NMAP>
; DI void att_pvmm(const s16x4 (&lo)[4], const s16x4 (&hi)[4], const bf16x8 (&pk)[NMAP][2][2], f32x16 (&o)[NMAP][2], int e) {
;     __builtin_amdgcn_s_setprio(1);
; #pragma unroll
;     for (int q = 0; q < 4; ++q) { const bf16x8 vf = (bf16x8){lo[q][0], lo[q][1], lo[q][2], lo[q][3], hi[q][0], hi[q][1], hi[q][2], hi[q][3]};
; #pragma unroll
;         for (int mp = 0; mp < NMAP; ++mp) o[mp][e] = __builtin_amdgcn_mfma_f32_32x32x16_bf16(vf, pk[mp][q >> 1][q & 1], o[mp][e], 0, 0, 0); }
;     __builtin_amdgcn_s_setprio(0);
; }
.LBB0_397:
	v_sub_f32_e32 v34, v136, v132
	v_sub_f32_e32 v35, v137, v132
	v_sub_f32_e32 v36, v134, v132
	v_sub_f32_e32 v37, v135, v132
	v_exp_f32_e32 v34, v34
	v_exp_f32_e32 v35, v35
	v_exp_f32_e32 v38, v36
	v_exp_f32_e32 v39, v37
	v_sub_f32_e32 v36, v50, v132
	v_sub_f32_e32 v37, v51, v132
	v_sub_f32_e32 v40, v138, v132
	v_sub_f32_e32 v41, v139, v132
	v_exp_f32_e32 v36, v36
	v_exp_f32_e32 v37, v37
	v_exp_f32_e32 v40, v40
	v_exp_f32_e32 v41, v41
	v_sub_f32_e32 v44, v52, v132
	v_sub_f32_e32 v45, v53, v132
	v_add_f32_e32 v42, 0, v34
	v_add_f32_e32 v43, 0, v35
	v_sub_f32_e32 v46, v140, v132
	v_sub_f32_e32 v47, v141, v132
	v_exp_f32_e32 v44, v44
	v_exp_f32_e32 v45, v45
	v_add_f32_e32 v42, v38, v42
	v_add_f32_e32 v43, v39, v43
	v_exp_f32_e32 v46, v46
	v_exp_f32_e32 v47, v47
	v_sub_f32_e32 v48, v54, v132
	v_sub_f32_e32 v49, v55, v132
	v_add_f32_e32 v42, v36, v42
	v_add_f32_e32 v43, v37, v43
	v_sub_f32_e32 v50, v142, v132
	v_sub_f32_e32 v51, v143, v132
	v_exp_f32_e32 v48, v48
	v_exp_f32_e32 v49, v49
	v_add_f32_e32 v42, v40, v42
	v_add_f32_e32 v43, v41, v43
	v_exp_f32_e32 v50, v50
	v_exp_f32_e32 v51, v51
	v_sub_f32_e32 v52, v56, v132
	v_sub_f32_e32 v53, v57, v132
	v_add_f32_e32 v42, v44, v42
	v_add_f32_e32 v43, v45, v43
	v_sub_f32_e32 v54, v148, v132
	v_sub_f32_e32 v55, v149, v132
	v_exp_f32_e32 v52, v52
	v_exp_f32_e32 v53, v53
	v_add_f32_e32 v42, v46, v42
	v_add_f32_e32 v43, v47, v43
	v_exp_f32_e32 v54, v54
	v_exp_f32_e32 v55, v55
	v_sub_f32_e32 v56, v58, v132
	v_sub_f32_e32 v57, v59, v132
	v_add_f32_e32 v42, v48, v42
	v_add_f32_e32 v43, v49, v43
	v_sub_f32_e32 v58, v150, v132
	v_sub_f32_e32 v59, v151, v132
	v_exp_f32_e32 v56, v56
	v_exp_f32_e32 v57, v57
	v_add_f32_e32 v42, v50, v42
	v_add_f32_e32 v43, v51, v43
	v_exp_f32_e32 v58, v58
	v_exp_f32_e32 v59, v59
	v_sub_f32_e32 v60, v60, v132
	v_sub_f32_e32 v61, v61, v132
	v_add_f32_e32 v42, v52, v42
	v_add_f32_e32 v43, v53, v43
	v_sub_f32_e32 v64, v152, v132
	v_sub_f32_e32 v65, v153, v132
	v_exp_f32_e32 v60, v60
	v_exp_f32_e32 v61, v61
	v_add_f32_e32 v42, v54, v42
	v_add_f32_e32 v43, v55, v43
	v_exp_f32_e32 v64, v64
	v_exp_f32_e32 v65, v65
	v_sub_f32_e32 v62, v62, v132
	v_sub_f32_e32 v63, v63, v132
	v_add_f32_e32 v42, v56, v42
	v_add_f32_e32 v43, v57, v43
	v_sub_f32_e32 v134, v154, v132
	v_sub_f32_e32 v135, v155, v132
	v_exp_f32_e32 v62, v62
	v_exp_f32_e32 v63, v63
	v_add_f32_e32 v42, v58, v42
	v_add_f32_e32 v43, v59, v43
	v_exp_f32_e32 v134, v134
	v_exp_f32_e32 v135, v135
	v_add_f32_e32 v42, v60, v42
	v_add_f32_e32 v43, v61, v43
	v_cvt_pk_bf16_f32 v34, v34, v35
	v_add_f32_e32 v42, v64, v42
	v_add_f32_e32 v43, v65, v43
	v_cvt_pk_bf16_f32 v35, v36, v37
	v_add_f32_e32 v42, v62, v42
	v_add_f32_e32 v43, v63, v43
	v_cvt_pk_bf16_f32 v36, v44, v45
	v_add_f32_e32 v42, v134, v42
	v_add_f32_e32 v43, v135, v43
	v_cvt_pk_bf16_f32 v37, v48, v49
	v_add_f32_e32 v42, v42, v43
	v_add_f32_e32 v163, v163, v42
	v_cvt_pk_bf16_f32 v38, v38, v39
	v_cvt_pk_bf16_f32 v39, v40, v41
	v_cvt_pk_bf16_f32 v40, v46, v47
	v_cvt_pk_bf16_f32 v41, v50, v51
	v_cvt_pk_bf16_f32 v42, v52, v53
	v_cvt_pk_bf16_f32 v43, v56, v57
	v_cvt_pk_bf16_f32 v44, v60, v61
	v_cvt_pk_bf16_f32 v45, v62, v63
	v_cvt_pk_bf16_f32 v46, v54, v55
	v_cvt_pk_bf16_f32 v47, v58, v59
	v_cvt_pk_bf16_f32 v48, v64, v65
	v_cvt_pk_bf16_f32 v49, v134, v135
	s_setprio 1
	s_waitcnt lgkmcnt(6)
	v_mfma_f32_32x32x16_bf16 v[18:33], v[118:121], v[34:37], v[18:33]
	s_waitcnt lgkmcnt(4)
	v_mfma_f32_32x32x16_bf16 v[18:33], v[114:117], v[42:45], v[18:33]
	s_waitcnt lgkmcnt(2)
	v_mfma_f32_32x32x16_bf16 v[18:33], v[110:113], v[38:41], v[18:33]
	s_waitcnt lgkmcnt(0)
	v_mfma_f32_32x32x16_bf16 v[18:33], v[106:109], v[46:49], v[18:33]
	s_setprio 0
	ds_read_b64_tr_b16 v[50:51], v165 offset:18496
	ds_read_b64_tr_b16 v[52:53], v165 offset:19648
	ds_read_b64_tr_b16 v[54:55], v165 offset:20800
	ds_read_b64_tr_b16 v[56:57], v165 offset:21952
	ds_read_b64_tr_b16 v[58:59], v165 offset:23104
	ds_read_b64_tr_b16 v[60:61], v165 offset:24256
	ds_read_b64_tr_b16 v[62:63], v165 offset:25408
	ds_read_b64_tr_b16 v[64:65], v165 offset:26560
	s_setprio 1
	s_waitcnt lgkmcnt(6)
	v_mfma_f32_32x32x16_bf16 v[2:17], v[50:53], v[34:37], v[2:17]
	s_waitcnt lgkmcnt(4)
	v_mfma_f32_32x32x16_bf16 v[2:17], v[54:57], v[42:45], v[2:17]
	s_waitcnt lgkmcnt(2)
	v_mfma_f32_32x32x16_bf16 v[2:17], v[58:61], v[38:41], v[2:17]
	s_waitcnt lgkmcnt(0)
	v_mfma_f32_32x32x16_bf16 v[2:17], v[62:65], v[46:49], v[2:17]
	s_setprio 0

; #define LAS __attribute__((address_space(3)))
; DI unsigned pk2(float lo, float hi) { f32x2 v = {lo, hi}; bf16x2_t b = __builtin_convertvector(v, bf16x2_t); return __builtin_bit_cast(unsigned, b); }
; DI void att_sm_tail(f32x16 (&S)[2], bf16x8 (&pkm)[2][2], const float mrefm, float& lrunm) {
;     {
;         f32x16& s0 = S[0]; f32x16& s1 = S[1];
;         const f32x2 nm2 = {-mrefm, -mrefm};
;         f32x2 acc2 = {0.f, 0.f};
; #pragma unroll
;         for (int i = 0; i < 16; i += 2) {
;             f32x2 a = {s0[i], s0[i + 1]}, b = {s1[i], s1[i + 1]}; a += nm2; b += nm2;
;             a.x = fast_exp2(a.x); a.y = fast_exp2(a.y); b.x = fast_exp2(b.x); b.y = fast_exp2(b.y);
;             acc2 += a; acc2 += b; s0[i] = a.x; s0[i + 1] = a.y; s1[i] = b.x; s1[i + 1] = b.y;
;         }
;         lrunm += acc2.x + acc2.y;
; #pragma unroll
;         for (int s = 0; s < 2; ++s) {
;             u32x4 w0, w1;
;             w0.x = pk2(s0[8 * s + 0], s0[8 * s + 1]); w0.y = pk2(s0[8 * s + 2], s0[8 * s + 3]); w0.z = pk2(s0[8 * s + 4], s0[8 * s + 5]); w0.w = pk2(s0[8 * s + 6], s0[8 * s + 7]);
;             w1.x = pk2(s1[8 * s + 0], s1[8 * s + 1]); w1.y = pk2(s1[8 * s + 2], s1[8 * s + 3]); w1.z = pk2(s1[8 * s + 4], s1[8 * s + 5]); w1.w = pk2(s1[8 * s + 6], s1[8 * s + 7]);
;             pkm[0][s] = __builtin_bit_cast(bf16x8, w0); pkm[1][s] = __builtin_bit_cast(bf16x8, w1);
;         }
;     }
; }
; DI void att_vload(const LAS unsigned char* vb, int e, s16x4 (&lo)[4], s16x4 (&hi)[4]) {
;     constexpr int VP = 144;
; #pragma unroll
;     for (int q = 0; q < 4; ++q) { const LAS unsigned char* p = vb + (16 * q) * VP + 64 * e;
;         lo[q] = __builtin_bit_cast(s16x4, __builtin_amdgcn_ds_read_tr16_b64_v4i16((LAS s16x4*)p));
;         hi[q] = __builtin_bit_cast(s16x4, __builtin_amdgcn_ds_read_tr16_b64_v4i16((LAS s16x4*)(p + 8 * VP))); }
; }
; template <int NMAP>
; DI void att_pvmm(const s16x4 (&lo)[4], const s16x4 (&hi)[4], const bf16x8 (&pk)[NMAP][2][2], f32x16 (&o)[NMAP][2], int e) {
;     __builtin_amdgcn_s_setprio(1);
; #pragma unroll
;     for (int q = 0; q < 4; ++q) { const bf16x8 vf = (bf16x8){lo[q][0], lo[q][1], lo[q][2], lo[q][3], hi[q][0], hi[q][1], hi[q][2], hi[q][3]};
; #pragma unroll
;         for (int mp = 0; mp < NMAP; ++mp) o[mp][e] = __builtin_amdgcn_mfma_f32_32x32x16_bf16(vf, pk[mp][q >> 1][q & 1], o[mp][e], 0, 0, 0); }
;     __builtin_amdgcn_s_setprio(0);
; }
.LBB0_471:
	v_sub_f32_e32 v34, v136, v132
	v_sub_f32_e32 v35, v137, v132
	v_sub_f32_e32 v36, v134, v132
	v_sub_f32_e32 v37, v135, v132
	v_exp_f32_e32 v34, v34
	v_exp_f32_e32 v35, v35
	v_exp_f32_e32 v38, v36
	v_exp_f32_e32 v39, v37
	v_sub_f32_e32 v36, v50, v132
	v_sub_f32_e32 v37, v51, v132
	v_sub_f32_e32 v40, v138, v132
	v_sub_f32_e32 v41, v139, v132
	v_exp_f32_e32 v36, v36
	v_exp_f32_e32 v37, v37
	v_exp_f32_e32 v40, v40
	v_exp_f32_e32 v41, v41
	v_sub_f32_e32 v44, v52, v132
	v_sub_f32_e32 v45, v53, v132
	v_add_f32_e32 v42, 0, v34
	v_add_f32_e32 v43, 0, v35
	v_sub_f32_e32 v46, v140, v132
	v_sub_f32_e32 v47, v141, v132
	v_exp_f32_e32 v44, v44
	v_exp_f32_e32 v45, v45
	v_add_f32_e32 v42, v38, v42
	v_add_f32_e32 v43, v39, v43
	v_exp_f32_e32 v46, v46
	v_exp_f32_e32 v47, v47
	v_sub_f32_e32 v48, v54, v132
	v_sub_f32_e32 v49, v55, v132
	v_add_f32_e32 v42, v36, v42
	v_add_f32_e32 v43, v37, v43
	v_sub_f32_e32 v50, v142, v132
	v_sub_f32_e32 v51, v143, v132
	v_exp_f32_e32 v48, v48
	v_exp_f32_e32 v49, v49
	v_add_f32_e32 v42, v40, v42
	v_add_f32_e32 v43, v41, v43
	v_exp_f32_e32 v50, v50
	v_exp_f32_e32 v51, v51
	v_sub_f32_e32 v52, v56, v132
	v_sub_f32_e32 v53, v57, v132
	v_add_f32_e32 v42, v44, v42
	v_add_f32_e32 v43, v45, v43
	v_sub_f32_e32 v54, v148, v132
	v_sub_f32_e32 v55, v149, v132
	v_exp_f32_e32 v52, v52
	v_exp_f32_e32 v53, v53
	v_add_f32_e32 v42, v46, v42
	v_add_f32_e32 v43, v47, v43
	v_exp_f32_e32 v54, v54
	v_exp_f32_e32 v55, v55
	v_sub_f32_e32 v56, v58, v132
	v_sub_f32_e32 v57, v59, v132
	v_add_f32_e32 v42, v48, v42
	v_add_f32_e32 v43, v49, v43
	v_sub_f32_e32 v58, v150, v132
	v_sub_f32_e32 v59, v151, v132
	v_exp_f32_e32 v56, v56
	v_exp_f32_e32 v57, v57
	v_add_f32_e32 v42, v50, v42
	v_add_f32_e32 v43, v51, v43
	v_exp_f32_e32 v58, v58
	v_exp_f32_e32 v59, v59
	v_sub_f32_e32 v60, v60, v132
	v_sub_f32_e32 v61, v61, v132
	v_add_f32_e32 v42, v52, v42
	v_add_f32_e32 v43, v53, v43
	v_sub_f32_e32 v64, v152, v132
	v_sub_f32_e32 v65, v153, v132
	v_exp_f32_e32 v60, v60
	v_exp_f32_e32 v61, v61
	v_add_f32_e32 v42, v54, v42
	v_add_f32_e32 v43, v55, v43
	v_exp_f32_e32 v64, v64
	v_exp_f32_e32 v65, v65
	v_sub_f32_e32 v62, v62, v132
	v_sub_f32_e32 v63, v63, v132
	v_add_f32_e32 v42, v56, v42
	v_add_f32_e32 v43, v57, v43
	v_sub_f32_e32 v134, v154, v132
	v_sub_f32_e32 v135, v155, v132
	v_exp_f32_e32 v62, v62
	v_exp_f32_e32 v63, v63
	v_add_f32_e32 v42, v58, v42
	v_add_f32_e32 v43, v59, v43
	v_exp_f32_e32 v134, v134
	v_exp_f32_e32 v135, v135
	v_add_f32_e32 v42, v60, v42
	v_add_f32_e32 v43, v61, v43
	v_cvt_pk_bf16_f32 v34, v34, v35
	v_add_f32_e32 v42, v64, v42
	v_add_f32_e32 v43, v65, v43
	v_cvt_pk_bf16_f32 v35, v36, v37
	v_add_f32_e32 v42, v62, v42
	v_add_f32_e32 v43, v63, v43
	v_cvt_pk_bf16_f32 v36, v44, v45
	v_add_f32_e32 v42, v134, v42
	v_add_f32_e32 v43, v135, v43
	v_cvt_pk_bf16_f32 v37, v48, v49
	v_add_f32_e32 v42, v42, v43
	v_add_f32_e32 v163, v163, v42
	v_cvt_pk_bf16_f32 v38, v38, v39
	v_cvt_pk_bf16_f32 v39, v40, v41
	v_cvt_pk_bf16_f32 v40, v46, v47
	v_cvt_pk_bf16_f32 v41, v50, v51
	v_cvt_pk_bf16_f32 v42, v52, v53
	v_cvt_pk_bf16_f32 v43, v56, v57
	v_cvt_pk_bf16_f32 v44, v60, v61
	v_cvt_pk_bf16_f32 v45, v62, v63
	v_cvt_pk_bf16_f32 v46, v54, v55
	v_cvt_pk_bf16_f32 v47, v58, v59
	v_cvt_pk_bf16_f32 v48, v64, v65
	v_cvt_pk_bf16_f32 v49, v134, v135
	s_setprio 1
	s_waitcnt lgkmcnt(3)
	v_mfma_f32_32x32x16_bf16 v[18:33], v[118:121], v[34:37], v[18:33]
	v_mfma_f32_32x32x16_bf16 v[18:33], v[114:117], v[42:45], v[18:33]
	s_waitcnt lgkmcnt(2)
	v_mfma_f32_32x32x16_bf16 v[18:33], v[110:113], v[38:41], v[18:33]
	s_waitcnt lgkmcnt(0)
	v_mfma_f32_32x32x16_bf16 v[18:33], v[106:109], v[46:49], v[18:33]
	s_setprio 0
	ds_read_b64_tr_b16 v[52:53], v165 offset:28864
	ds_read_b64_tr_b16 v[54:55], v165 offset:30016
	ds_read_b64_tr_b16 v[56:57], v165 offset:31168
	ds_read_b64_tr_b16 v[58:59], v165 offset:32320
	ds_read_b64_tr_b16 v[50:51], v165 offset:27712
	ds_read_b64_tr_b16 v[60:61], v165 offset:33472
	ds_read_b64_tr_b16 v[62:63], v165 offset:34624
	ds_read_b64_tr_b16 v[64:65], v165 offset:35776
	s_setprio 1
	s_waitcnt lgkmcnt(3)
	v_mfma_f32_32x32x16_bf16 v[2:17], v[50:53], v[34:37], v[2:17]
	v_mfma_f32_32x32x16_bf16 v[2:17], v[54:57], v[42:45], v[2:17]
	s_waitcnt lgkmcnt(2)
	v_mfma_f32_32x32x16_bf16 v[2:17], v[58:61], v[38:41], v[2:17]
	s_waitcnt lgkmcnt(0)
	v_mfma_f32_32x32x16_bf16 v[2:17], v[62:65], v[46:49], v[2:17]
	s_setprio 0

; #define LAS __attribute__((address_space(3)))
; DI unsigned pk2(float lo, float hi) { f32x2 v = {lo, hi}; bf16x2_t b = __builtin_convertvector(v, bf16x2_t); return __builtin_bit_cast(unsigned, b); }
; DI void att_sm_tail(f32x16 (&S)[2], bf16x8 (&pkm)[2][2], const float mrefm, float& lrunm) {
;     {
;         f32x16& s0 = S[0]; f32x16& s1 = S[1];
;         const f32x2 nm2 = {-mrefm, -mrefm};
;         f32x2 acc2 = {0.f, 0.f};
; #pragma unroll
;         for (int i = 0; i < 16; i += 2) {
;             f32x2 a = {s0[i], s0[i + 1]}, b = {s1[i], s1[i + 1]}; a += nm2; b += nm2;
;             a.x = fast_exp2(a.x); a.y = fast_exp2(a.y); b.x = fast_exp2(b.x); b.y = fast_exp2(b.y);
;             acc2 += a; acc2 += b; s0[i] = a.x; s0[i + 1] = a.y; s1[i] = b.x; s1[i + 1] = b.y;
;         }
;         lrunm += acc2.x + acc2.y;
; #pragma unroll
;         for (int s = 0; s < 2; ++s) {
;             u32x4 w0, w1;
;             w0.x = pk2(s0[8 * s + 0], s0[8 * s + 1]); w0.y = pk2(s0[8 * s + 2], s0[8 * s + 3]); w0.z = pk2(s0[8 * s + 4], s0[8 * s + 5]); w0.w = pk2(s0[8 * s + 6], s0[8 * s + 7]);
;             w1.x = pk2(s1[8 * s + 0], s1[8 * s + 1]); w1.y = pk2(s1[8 * s + 2], s1[8 * s + 3]); w1.z = pk2(s1[8 * s + 4], s1[8 * s + 5]); w1.w = pk2(s1[8 * s + 6], s1[8 * s + 7]);
;             pkm[0][s] = __builtin_bit_cast(bf16x8, w0); pkm[1][s] = __builtin_bit_cast(bf16x8, w1);
;         }
;     }
; }
; DI void att_vload(const LAS unsigned char* vb, int e, s16x4 (&lo)[4], s16x4 (&hi)[4]) {
;     constexpr int VP = 144;
; #pragma unroll
;     for (int q = 0; q < 4; ++q) { const LAS unsigned char* p = vb + (16 * q) * VP + 64 * e;
;         lo[q] = __builtin_bit_cast(s16x4, __builtin_amdgcn_ds_read_tr16_b64_v4i16((LAS s16x4*)p));
;         hi[q] = __builtin_bit_cast(s16x4, __builtin_amdgcn_ds_read_tr16_b64_v4i16((LAS s16x4*)(p + 8 * VP))); }
; }
; template <int NMAP>
; DI void att_pvmm(const s16x4 (&lo)[4], const s16x4 (&hi)[4], const bf16x8 (&pk)[NMAP][2][2], f32x16 (&o)[NMAP][2], int e) {
;     __builtin_amdgcn_s_setprio(1);
; #pragma unroll
;     for (int q = 0; q < 4; ++q) { const bf16x8 vf = (bf16x8){lo[q][0], lo[q][1], lo[q][2], lo[q][3], hi[q][0], hi[q][1], hi[q][2], hi[q][3]};
; #pragma unroll
;         for (int mp = 0; mp < NMAP; ++mp) o[mp][e] = __builtin_amdgcn_mfma_f32_32x32x16_bf16(vf, pk[mp][q >> 1][q & 1], o[mp][e], 0, 0, 0); }
;     __builtin_amdgcn_s_setprio(0);
; }
.LBB0_545:
	v_sub_f32_e32 v34, v136, v132
	v_sub_f32_e32 v35, v137, v132
	v_sub_f32_e32 v36, v134, v132
	v_sub_f32_e32 v37, v135, v132
	v_exp_f32_e32 v34, v34
	v_exp_f32_e32 v35, v35
	v_exp_f32_e32 v38, v36
	v_exp_f32_e32 v39, v37
	v_sub_f32_e32 v36, v50, v132
	v_sub_f32_e32 v37, v51, v132
	v_sub_f32_e32 v40, v138, v132
	v_sub_f32_e32 v41, v139, v132
	v_exp_f32_e32 v36, v36
	v_exp_f32_e32 v37, v37
	v_exp_f32_e32 v40, v40
	v_exp_f32_e32 v41, v41
	v_sub_f32_e32 v44, v52, v132
	v_sub_f32_e32 v45, v53, v132
	v_add_f32_e32 v42, 0, v34
	v_add_f32_e32 v43, 0, v35
	v_sub_f32_e32 v46, v140, v132
	v_sub_f32_e32 v47, v141, v132
	v_exp_f32_e32 v44, v44
	v_exp_f32_e32 v45, v45
	v_add_f32_e32 v42, v38, v42
	v_add_f32_e32 v43, v39, v43
	v_exp_f32_e32 v46, v46
	v_exp_f32_e32 v47, v47
	v_sub_f32_e32 v48, v54, v132
	v_sub_f32_e32 v49, v55, v132
	v_add_f32_e32 v42, v36, v42
	v_add_f32_e32 v43, v37, v43
	v_sub_f32_e32 v50, v142, v132
	v_sub_f32_e32 v51, v143, v132
	v_exp_f32_e32 v48, v48
	v_exp_f32_e32 v49, v49
	v_add_f32_e32 v42, v40, v42
	v_add_f32_e32 v43, v41, v43
	v_exp_f32_e32 v50, v50
	v_exp_f32_e32 v51, v51
	v_sub_f32_e32 v52, v56, v132
	v_sub_f32_e32 v53, v57, v132
	v_add_f32_e32 v42, v44, v42
	v_add_f32_e32 v43, v45, v43
	v_sub_f32_e32 v54, v148, v132
	v_sub_f32_e32 v55, v149, v132
	v_exp_f32_e32 v52, v52
	v_exp_f32_e32 v53, v53
	v_add_f32_e32 v42, v46, v42
	v_add_f32_e32 v43, v47, v43
	v_exp_f32_e32 v54, v54
	v_exp_f32_e32 v55, v55
	v_sub_f32_e32 v56, v58, v132
	v_sub_f32_e32 v57, v59, v132
	v_add_f32_e32 v42, v48, v42
	v_add_f32_e32 v43, v49, v43
	v_sub_f32_e32 v58, v150, v132
	v_sub_f32_e32 v59, v151, v132
	v_exp_f32_e32 v56, v56
	v_exp_f32_e32 v57, v57
	v_add_f32_e32 v42, v50, v42
	v_add_f32_e32 v43, v51, v43
	v_exp_f32_e32 v58, v58
	v_exp_f32_e32 v59, v59
	v_sub_f32_e32 v60, v60, v132
	v_sub_f32_e32 v61, v61, v132
	v_add_f32_e32 v42, v52, v42
	v_add_f32_e32 v43, v53, v43
	v_sub_f32_e32 v64, v152, v132
	v_sub_f32_e32 v65, v153, v132
	v_exp_f32_e32 v60, v60
	v_exp_f32_e32 v61, v61
	v_add_f32_e32 v42, v54, v42
	v_add_f32_e32 v43, v55, v43
	v_exp_f32_e32 v64, v64
	v_exp_f32_e32 v65, v65
	v_sub_f32_e32 v62, v62, v132
	v_sub_f32_e32 v63, v63, v132
	v_add_f32_e32 v42, v56, v42
	v_add_f32_e32 v43, v57, v43
	v_sub_f32_e32 v134, v154, v132
	v_sub_f32_e32 v135, v155, v132
	v_exp_f32_e32 v62, v62
	v_exp_f32_e32 v63, v63
	v_add_f32_e32 v42, v58, v42
	v_add_f32_e32 v43, v59, v43
	v_exp_f32_e32 v134, v134
	v_exp_f32_e32 v135, v135
	v_add_f32_e32 v42, v60, v42
	v_add_f32_e32 v43, v61, v43
	v_cvt_pk_bf16_f32 v34, v34, v35
	v_add_f32_e32 v42, v64, v42
	v_add_f32_e32 v43, v65, v43
	v_cvt_pk_bf16_f32 v35, v36, v37
	v_add_f32_e32 v42, v62, v42
	v_add_f32_e32 v43, v63, v43
	v_cvt_pk_bf16_f32 v36, v44, v45
	v_add_f32_e32 v42, v134, v42
	v_add_f32_e32 v43, v135, v43
	v_cvt_pk_bf16_f32 v37, v48, v49
	v_add_f32_e32 v42, v42, v43
	v_add_f32_e32 v163, v163, v42
	v_cvt_pk_bf16_f32 v38, v38, v39
	v_cvt_pk_bf16_f32 v39, v40, v41
	v_cvt_pk_bf16_f32 v40, v46, v47
	v_cvt_pk_bf16_f32 v41, v50, v51
	v_cvt_pk_bf16_f32 v42, v52, v53
	v_cvt_pk_bf16_f32 v43, v56, v57
	v_cvt_pk_bf16_f32 v44, v60, v61
	v_cvt_pk_bf16_f32 v45, v62, v63
	v_cvt_pk_bf16_f32 v46, v54, v55
	v_cvt_pk_bf16_f32 v47, v58, v59
	v_cvt_pk_bf16_f32 v48, v64, v65
	v_cvt_pk_bf16_f32 v49, v134, v135
	s_setprio 1
	s_waitcnt lgkmcnt(6)
	v_mfma_f32_32x32x16_bf16 v[18:33], v[118:121], v[34:37], v[18:33]
	s_waitcnt lgkmcnt(4)
	v_mfma_f32_32x32x16_bf16 v[18:33], v[114:117], v[42:45], v[18:33]
	s_waitcnt lgkmcnt(2)
	v_mfma_f32_32x32x16_bf16 v[18:33], v[110:113], v[38:41], v[18:33]
	s_waitcnt lgkmcnt(0)
	v_mfma_f32_32x32x16_bf16 v[18:33], v[106:109], v[46:49], v[18:33]
	s_setprio 0
	ds_read_b64_tr_b16 v[50:51], v165 offset:36928
	ds_read_b64_tr_b16 v[52:53], v165 offset:38080
	ds_read_b64_tr_b16 v[54:55], v165 offset:39232
	ds_read_b64_tr_b16 v[56:57], v165 offset:40384
	ds_read_b64_tr_b16 v[58:59], v165 offset:41536
	ds_read_b64_tr_b16 v[60:61], v165 offset:42688
	ds_read_b64_tr_b16 v[62:63], v165 offset:43840
	ds_read_b64_tr_b16 v[64:65], v165 offset:44992
	s_setprio 1
	s_waitcnt lgkmcnt(6)
	v_mfma_f32_32x32x16_bf16 v[2:17], v[50:53], v[34:37], v[2:17]
	s_waitcnt lgkmcnt(4)
	v_mfma_f32_32x32x16_bf16 v[2:17], v[54:57], v[42:45], v[2:17]
	s_waitcnt lgkmcnt(2)
	v_mfma_f32_32x32x16_bf16 v[2:17], v[58:61], v[38:41], v[2:17]
	s_waitcnt lgkmcnt(0)
	v_mfma_f32_32x32x16_bf16 v[2:17], v[62:65], v[46:49], v[2:17]
	s_setprio 0

; #define LAS __attribute__((address_space(3)))
; DI unsigned pk2(float lo, float hi) { f32x2 v = {lo, hi}; bf16x2_t b = __builtin_convertvector(v, bf16x2_t); return __builtin_bit_cast(unsigned, b); }
; DI void att_sm_tail(f32x16 (&S)[2], bf16x8 (&pkm)[2][2], const float mrefm, float& lrunm) {
;     {
;         f32x16& s0 = S[0]; f32x16& s1 = S[1];
;         const f32x2 nm2 = {-mrefm, -mrefm};
;         f32x2 acc2 = {0.f, 0.f};
; #pragma unroll
;         for (int i = 0; i < 16; i += 2) {
;             f32x2 a = {s0[i], s0[i + 1]}, b = {s1[i], s1[i + 1]}; a += nm2; b += nm2;
;             a.x = fast_exp2(a.x); a.y = fast_exp2(a.y); b.x = fast_exp2(b.x); b.y = fast_exp2(b.y);
;             acc2 += a; acc2 += b; s0[i] = a.x; s0[i + 1] = a.y; s1[i] = b.x; s1[i + 1] = b.y;
;         }
;         lrunm += acc2.x + acc2.y;
; #pragma unroll
;         for (int s = 0; s < 2; ++s) {
;             u32x4 w0, w1;
;             w0.x = pk2(s0[8 * s + 0], s0[8 * s + 1]); w0.y = pk2(s0[8 * s + 2], s0[8 * s + 3]); w0.z = pk2(s0[8 * s + 4], s0[8 * s + 5]); w0.w = pk2(s0[8 * s + 6], s0[8 * s + 7]);
;             w1.x = pk2(s1[8 * s + 0], s1[8 * s + 1]); w1.y = pk2(s1[8 * s + 2], s1[8 * s + 3]); w1.z = pk2(s1[8 * s + 4], s1[8 * s + 5]); w1.w = pk2(s1[8 * s + 6], s1[8 * s + 7]);
;             pkm[0][s] = __builtin_bit_cast(bf16x8, w0); pkm[1][s] = __builtin_bit_cast(bf16x8, w1);
;         }
;     }
; }
; DI void att_vload(const LAS unsigned char* vb, int e, s16x4 (&lo)[4], s16x4 (&hi)[4]) {
;     constexpr int VP = 144;
; #pragma unroll
;     for (int q = 0; q < 4; ++q) { const LAS unsigned char* p = vb + (16 * q) * VP + 64 * e;
;         lo[q] = __builtin_bit_cast(s16x4, __builtin_amdgcn_ds_read_tr16_b64_v4i16((LAS s16x4*)p));
;         hi[q] = __builtin_bit_cast(s16x4, __builtin_amdgcn_ds_read_tr16_b64_v4i16((LAS s16x4*)(p + 8 * VP))); }
; }
; template <int NMAP>
; DI void att_pvmm(const s16x4 (&lo)[4], const s16x4 (&hi)[4], const bf16x8 (&pk)[NMAP][2][2], f32x16 (&o)[NMAP][2], int e) {
;     __builtin_amdgcn_s_setprio(1);
; #pragma unroll
;     for (int q = 0; q < 4; ++q) { const bf16x8 vf = (bf16x8){lo[q][0], lo[q][1], lo[q][2], lo[q][3], hi[q][0], hi[q][1], hi[q][2], hi[q][3]};
; #pragma unroll
;         for (int mp = 0; mp < NMAP; ++mp) o[mp][e] = __builtin_amdgcn_mfma_f32_32x32x16_bf16(vf, pk[mp][q >> 1][q & 1], o[mp][e], 0, 0, 0); }
;     __builtin_amdgcn_s_setprio(0);
; }
.LBB0_559:
	v_sub_f32_e32 v14, v48, v138
	v_sub_f32_e32 v15, v49, v138
	v_sub_f32_e32 v48, v64, v138
	v_sub_f32_e32 v49, v65, v138
	v_exp_f32_e32 v14, v14
	v_exp_f32_e32 v15, v15
	v_exp_f32_e32 v64, v48
	v_exp_f32_e32 v65, v49
	v_sub_f32_e32 v48, v50, v138
	v_sub_f32_e32 v49, v51, v138
	v_sub_f32_e32 v50, v66, v138
	v_sub_f32_e32 v51, v67, v138
	v_exp_f32_e32 v66, v48
	v_exp_f32_e32 v67, v49
	v_exp_f32_e32 v150, v50
	v_exp_f32_e32 v151, v51
	v_sub_f32_e32 v50, v52, v138
	v_sub_f32_e32 v51, v53, v138
	v_add_f32_e32 v48, 0, v14
	v_add_f32_e32 v49, 0, v15
	v_sub_f32_e32 v52, v68, v138
	v_sub_f32_e32 v53, v69, v138
	v_exp_f32_e32 v50, v50
	v_exp_f32_e32 v51, v51
	v_add_f32_e32 v48, v64, v48
	v_add_f32_e32 v49, v65, v49
	v_exp_f32_e32 v68, v52
	v_exp_f32_e32 v69, v53
	v_sub_f32_e32 v52, v54, v138
	v_sub_f32_e32 v53, v55, v138
	v_add_f32_e32 v48, v66, v48
	v_add_f32_e32 v49, v67, v49
	v_sub_f32_e32 v54, v70, v138
	v_sub_f32_e32 v55, v71, v138
	v_exp_f32_e32 v52, v52
	v_exp_f32_e32 v53, v53
	v_add_f32_e32 v48, v150, v48
	v_add_f32_e32 v49, v151, v49
	v_exp_f32_e32 v70, v54
	v_exp_f32_e32 v71, v55
	v_sub_f32_e32 v54, v56, v138
	v_sub_f32_e32 v55, v57, v138
	v_add_f32_e32 v48, v50, v48
	v_add_f32_e32 v49, v51, v49
	v_sub_f32_e32 v56, v72, v138
	v_sub_f32_e32 v57, v73, v138
	v_exp_f32_e32 v72, v54
	v_exp_f32_e32 v73, v55
	v_add_f32_e32 v48, v68, v48
	v_add_f32_e32 v49, v69, v49
	v_exp_f32_e32 v152, v56
	v_exp_f32_e32 v153, v57
	v_sub_f32_e32 v54, v58, v138
	v_sub_f32_e32 v55, v59, v138
	v_add_f32_e32 v48, v52, v48
	v_add_f32_e32 v49, v53, v49
	v_sub_f32_e32 v56, v74, v138
	v_sub_f32_e32 v57, v75, v138
	v_exp_f32_e32 v58, v54
	v_exp_f32_e32 v59, v55
	v_add_f32_e32 v48, v70, v48
	v_add_f32_e32 v49, v71, v49
	v_exp_f32_e32 v74, v56
	v_exp_f32_e32 v75, v57
	v_sub_f32_e32 v54, v60, v138
	v_sub_f32_e32 v55, v61, v138
	v_add_f32_e32 v48, v72, v48
	v_add_f32_e32 v49, v73, v49
	v_sub_f32_e32 v56, v76, v138
	v_sub_f32_e32 v57, v77, v138
	v_exp_f32_e32 v60, v54
	v_exp_f32_e32 v61, v55
	v_add_f32_e32 v48, v152, v48
	v_add_f32_e32 v49, v153, v49
	v_exp_f32_e32 v76, v56
	v_exp_f32_e32 v77, v57
	v_sub_f32_e32 v54, v62, v138
	v_sub_f32_e32 v55, v63, v138
	v_add_f32_e32 v48, v58, v48
	v_add_f32_e32 v49, v59, v49
	v_sub_f32_e32 v56, v78, v138
	v_sub_f32_e32 v57, v79, v138
	v_exp_f32_e32 v62, v54
	v_exp_f32_e32 v63, v55
	v_add_f32_e32 v48, v74, v48
	v_add_f32_e32 v49, v75, v49
	v_exp_f32_e32 v78, v56
	v_exp_f32_e32 v79, v57
	v_add_f32_e32 v48, v60, v48
	v_add_f32_e32 v49, v61, v49
	v_cvt_pk_bf16_f32 v50, v50, v51
	v_add_f32_e32 v48, v76, v48
	v_add_f32_e32 v49, v77, v49
	v_cvt_pk_bf16_f32 v51, v52, v53
	v_add_f32_e32 v48, v62, v48
	v_add_f32_e32 v49, v63, v49
	v_cvt_pk_bf16_f32 v52, v64, v65
	v_add_f32_e32 v48, v78, v48
	v_add_f32_e32 v49, v79, v49
	v_cvt_pk_bf16_f32 v53, v150, v151
	v_add_f32_e32 v0, v48, v49
	v_add_f32_e32 v143, v143, v0
	v_cvt_pk_bf16_f32 v48, v14, v15
	v_cvt_pk_bf16_f32 v49, v66, v67
	v_cvt_pk_bf16_f32 v54, v68, v69
	v_cvt_pk_bf16_f32 v55, v70, v71
	v_cvt_pk_bf16_f32 v56, v72, v73
	v_cvt_pk_bf16_f32 v57, v58, v59
	v_cvt_pk_bf16_f32 v58, v60, v61
	v_cvt_pk_bf16_f32 v59, v62, v63
	v_cvt_pk_bf16_f32 v60, v152, v153
	v_cvt_pk_bf16_f32 v61, v74, v75
	v_cvt_pk_bf16_f32 v62, v76, v77
	v_cvt_pk_bf16_f32 v63, v78, v79
	s_setprio 1
	s_waitcnt lgkmcnt(6)
	v_mfma_f32_32x32x16_bf16 v[32:47], v[120:123], v[48:51], v[32:47]
	s_waitcnt lgkmcnt(4)
	v_mfma_f32_32x32x16_bf16 v[32:47], v[116:119], v[56:59], v[32:47]
	s_waitcnt lgkmcnt(2)
	v_mfma_f32_32x32x16_bf16 v[32:47], v[112:115], v[52:55], v[32:47]
	s_waitcnt lgkmcnt(0)
	v_mfma_f32_32x32x16_bf16 v[32:47], v[10:13], v[60:63], v[32:47]
	s_setprio 0
	ds_read_b64_tr_b16 v[10:11], v148 offset:18496
	ds_read_b64_tr_b16 v[12:13], v148 offset:19648
	ds_read_b64_tr_b16 v[64:65], v148 offset:20800
	ds_read_b64_tr_b16 v[66:67], v148 offset:21952
	ds_read_b64_tr_b16 v[68:69], v148 offset:23104
	ds_read_b64_tr_b16 v[70:71], v148 offset:24256
	ds_read_b64_tr_b16 v[72:73], v148 offset:25408
	ds_read_b64_tr_b16 v[74:75], v148 offset:26560
	s_setprio 1
	s_waitcnt lgkmcnt(6)
	v_mfma_f32_32x32x16_bf16 v[16:31], v[10:13], v[48:51], v[16:31]
	s_waitcnt lgkmcnt(4)
	v_mfma_f32_32x32x16_bf16 v[16:31], v[64:67], v[56:59], v[16:31]
	s_waitcnt lgkmcnt(2)
	v_mfma_f32_32x32x16_bf16 v[16:31], v[68:71], v[52:55], v[16:31]
	s_waitcnt lgkmcnt(0)
	v_mfma_f32_32x32x16_bf16 v[16:31], v[72:75], v[60:63], v[16:31]
	s_setprio 0

; #define LAS __attribute__((address_space(3)))
; DI unsigned pk2(float lo, float hi) { f32x2 v = {lo, hi}; bf16x2_t b = __builtin_convertvector(v, bf16x2_t); return __builtin_bit_cast(unsigned, b); }
; DI void att_sm_tail(f32x16 (&S)[2], bf16x8 (&pkm)[2][2], const float mrefm, float& lrunm) {
;     {
;         f32x16& s0 = S[0]; f32x16& s1 = S[1];
;         const f32x2 nm2 = {-mrefm, -mrefm};
;         f32x2 acc2 = {0.f, 0.f};
; #pragma unroll
;         for (int i = 0; i < 16; i += 2) {
;             f32x2 a = {s0[i], s0[i + 1]}, b = {s1[i], s1[i + 1]}; a += nm2; b += nm2;
;             a.x = fast_exp2(a.x); a.y = fast_exp2(a.y); b.x = fast_exp2(b.x); b.y = fast_exp2(b.y);
;             acc2 += a; acc2 += b; s0[i] = a.x; s0[i + 1] = a.y; s1[i] = b.x; s1[i + 1] = b.y;
;         }
;         lrunm += acc2.x + acc2.y;
; #pragma unroll
;         for (int s = 0; s < 2; ++s) {
;             u32x4 w0, w1;
;             w0.x = pk2(s0[8 * s + 0], s0[8 * s + 1]); w0.y = pk2(s0[8 * s + 2], s0[8 * s + 3]); w0.z = pk2(s0[8 * s + 4], s0[8 * s + 5]); w0.w = pk2(s0[8 * s + 6], s0[8 * s + 7]);
;             w1.x = pk2(s1[8 * s + 0], s1[8 * s + 1]); w1.y = pk2(s1[8 * s + 2], s1[8 * s + 3]); w1.z = pk2(s1[8 * s + 4], s1[8 * s + 5]); w1.w = pk2(s1[8 * s + 6], s1[8 * s + 7]);
;             pkm[0][s] = __builtin_bit_cast(bf16x8, w0); pkm[1][s] = __builtin_bit_cast(bf16x8, w1);
;         }
;     }
; }
; DI void att_vload(const LAS unsigned char* vb, int e, s16x4 (&lo)[4], s16x4 (&hi)[4]) {
;     constexpr int VP = 144;
; #pragma unroll
;     for (int q = 0; q < 4; ++q) { const LAS unsigned char* p = vb + (16 * q) * VP + 64 * e;
;         lo[q] = __builtin_bit_cast(s16x4, __builtin_amdgcn_ds_read_tr16_b64_v4i16((LAS s16x4*)p));
;         hi[q] = __builtin_bit_cast(s16x4, __builtin_amdgcn_ds_read_tr16_b64_v4i16((LAS s16x4*)(p + 8 * VP))); }
; }
; template <int NMAP>
; DI void att_pvmm(const s16x4 (&lo)[4], const s16x4 (&hi)[4], const bf16x8 (&pk)[NMAP][2][2], f32x16 (&o)[NMAP][2], int e) {
;     __builtin_amdgcn_s_setprio(1);
; #pragma unroll
;     for (int q = 0; q < 4; ++q) { const bf16x8 vf = (bf16x8){lo[q][0], lo[q][1], lo[q][2], lo[q][3], hi[q][0], hi[q][1], hi[q][2], hi[q][3]};
; #pragma unroll
;         for (int mp = 0; mp < NMAP; ++mp) o[mp][e] = __builtin_amdgcn_mfma_f32_32x32x16_bf16(vf, pk[mp][q >> 1][q & 1], o[mp][e], 0, 0, 0); }
;     __builtin_amdgcn_s_setprio(0);
; }
.LBB0_563:
	v_sub_f32_e32 v14, v48, v138
	v_sub_f32_e32 v15, v49, v138
	v_sub_f32_e32 v48, v64, v138
	v_sub_f32_e32 v49, v65, v138
	v_exp_f32_e32 v14, v14
	v_exp_f32_e32 v15, v15
	v_exp_f32_e32 v64, v48
	v_exp_f32_e32 v65, v49
	v_sub_f32_e32 v48, v50, v138
	v_sub_f32_e32 v49, v51, v138
	v_sub_f32_e32 v50, v66, v138
	v_sub_f32_e32 v51, v67, v138
	v_exp_f32_e32 v66, v48
	v_exp_f32_e32 v67, v49
	v_exp_f32_e32 v150, v50
	v_exp_f32_e32 v151, v51
	v_sub_f32_e32 v50, v52, v138
	v_sub_f32_e32 v51, v53, v138
	v_add_f32_e32 v48, 0, v14
	v_add_f32_e32 v49, 0, v15
	v_sub_f32_e32 v52, v68, v138
	v_sub_f32_e32 v53, v69, v138
	v_exp_f32_e32 v50, v50
	v_exp_f32_e32 v51, v51
	v_add_f32_e32 v48, v64, v48
	v_add_f32_e32 v49, v65, v49
	v_exp_f32_e32 v68, v52
	v_exp_f32_e32 v69, v53
	v_sub_f32_e32 v52, v54, v138
	v_sub_f32_e32 v53, v55, v138
	v_add_f32_e32 v48, v66, v48
	v_add_f32_e32 v49, v67, v49
	v_sub_f32_e32 v54, v70, v138
	v_sub_f32_e32 v55, v71, v138
	v_exp_f32_e32 v52, v52
	v_exp_f32_e32 v53, v53
	v_add_f32_e32 v48, v150, v48
	v_add_f32_e32 v49, v151, v49
	v_exp_f32_e32 v70, v54
	v_exp_f32_e32 v71, v55
	v_sub_f32_e32 v54, v56, v138
	v_sub_f32_e32 v55, v57, v138
	v_add_f32_e32 v48, v50, v48
	v_add_f32_e32 v49, v51, v49
	v_sub_f32_e32 v56, v72, v138
	v_sub_f32_e32 v57, v73, v138
	v_exp_f32_e32 v72, v54
	v_exp_f32_e32 v73, v55
	v_add_f32_e32 v48, v68, v48
	v_add_f32_e32 v49, v69, v49
	v_exp_f32_e32 v152, v56
	v_exp_f32_e32 v153, v57
	v_sub_f32_e32 v54, v58, v138
	v_sub_f32_e32 v55, v59, v138
	v_add_f32_e32 v48, v52, v48
	v_add_f32_e32 v49, v53, v49
	v_sub_f32_e32 v56, v74, v138
	v_sub_f32_e32 v57, v75, v138
	v_exp_f32_e32 v58, v54
	v_exp_f32_e32 v59, v55
	v_add_f32_e32 v48, v70, v48
	v_add_f32_e32 v49, v71, v49
	v_exp_f32_e32 v74, v56
	v_exp_f32_e32 v75, v57
	v_sub_f32_e32 v54, v60, v138
	v_sub_f32_e32 v55, v61, v138
	v_add_f32_e32 v48, v72, v48
	v_add_f32_e32 v49, v73, v49
	v_sub_f32_e32 v56, v76, v138
	v_sub_f32_e32 v57, v77, v138
	v_exp_f32_e32 v60, v54
	v_exp_f32_e32 v61, v55
	v_add_f32_e32 v48, v152, v48
	v_add_f32_e32 v49, v153, v49
	v_exp_f32_e32 v76, v56
	v_exp_f32_e32 v77, v57
	v_sub_f32_e32 v54, v62, v138
	v_sub_f32_e32 v55, v63, v138
	v_add_f32_e32 v48, v58, v48
	v_add_f32_e32 v49, v59, v49
	v_sub_f32_e32 v56, v78, v138
	v_sub_f32_e32 v57, v79, v138
	v_exp_f32_e32 v62, v54
	v_exp_f32_e32 v63, v55
	v_add_f32_e32 v48, v74, v48
	v_add_f32_e32 v49, v75, v49
	v_exp_f32_e32 v78, v56
	v_exp_f32_e32 v79, v57
	v_add_f32_e32 v48, v60, v48
	v_add_f32_e32 v49, v61, v49
	v_cvt_pk_bf16_f32 v50, v50, v51
	v_add_f32_e32 v48, v76, v48
	v_add_f32_e32 v49, v77, v49
	v_cvt_pk_bf16_f32 v51, v52, v53
	v_add_f32_e32 v48, v62, v48
	v_add_f32_e32 v49, v63, v49
	v_cvt_pk_bf16_f32 v52, v64, v65
	v_add_f32_e32 v48, v78, v48
	v_add_f32_e32 v49, v79, v49
	v_cvt_pk_bf16_f32 v53, v150, v151
	v_add_f32_e32 v0, v48, v49
	v_add_f32_e32 v143, v143, v0
	v_cvt_pk_bf16_f32 v48, v14, v15
	v_cvt_pk_bf16_f32 v49, v66, v67
	v_cvt_pk_bf16_f32 v54, v68, v69
	v_cvt_pk_bf16_f32 v55, v70, v71
	v_cvt_pk_bf16_f32 v56, v72, v73
	v_cvt_pk_bf16_f32 v57, v58, v59
	v_cvt_pk_bf16_f32 v58, v60, v61
	v_cvt_pk_bf16_f32 v59, v62, v63
	v_cvt_pk_bf16_f32 v60, v152, v153
	v_cvt_pk_bf16_f32 v61, v74, v75
	v_cvt_pk_bf16_f32 v62, v76, v77
	v_cvt_pk_bf16_f32 v63, v78, v79
	s_setprio 1
	s_waitcnt lgkmcnt(3)
	v_mfma_f32_32x32x16_bf16 v[32:47], v[120:123], v[48:51], v[32:47]
	v_mfma_f32_32x32x16_bf16 v[32:47], v[116:119], v[56:59], v[32:47]
	s_waitcnt lgkmcnt(2)
	v_mfma_f32_32x32x16_bf16 v[32:47], v[112:115], v[52:55], v[32:47]
	s_waitcnt lgkmcnt(0)
	v_mfma_f32_32x32x16_bf16 v[32:47], v[10:13], v[60:63], v[32:47]
	s_setprio 0
	ds_read_b64_tr_b16 v[12:13], v148 offset:28864
	ds_read_b64_tr_b16 v[64:65], v148 offset:30016
	ds_read_b64_tr_b16 v[66:67], v148 offset:31168
	ds_read_b64_tr_b16 v[68:69], v148 offset:32320
	ds_read_b64_tr_b16 v[10:11], v148 offset:27712
	ds_read_b64_tr_b16 v[70:71], v148 offset:33472
	ds_read_b64_tr_b16 v[72:73], v148 offset:34624
	ds_read_b64_tr_b16 v[74:75], v148 offset:35776
	s_setprio 1
	s_waitcnt lgkmcnt(3)
	v_mfma_f32_32x32x16_bf16 v[16:31], v[10:13], v[48:51], v[16:31]
	v_mfma_f32_32x32x16_bf16 v[16:31], v[64:67], v[56:59], v[16:31]
	s_waitcnt lgkmcnt(2)
	v_mfma_f32_32x32x16_bf16 v[16:31], v[68:71], v[52:55], v[16:31]
	s_waitcnt lgkmcnt(0)
	v_mfma_f32_32x32x16_bf16 v[16:31], v[72:75], v[60:63], v[16:31]
	s_setprio 0

; #define LAS __attribute__((address_space(3)))
; DI unsigned pk2(float lo, float hi) { f32x2 v = {lo, hi}; bf16x2_t b = __builtin_convertvector(v, bf16x2_t); return __builtin_bit_cast(unsigned, b); }
; DI void att_sm_tail(f32x16 (&S)[2], bf16x8 (&pkm)[2][2], const float mrefm, float& lrunm) {
;     {
;         f32x16& s0 = S[0]; f32x16& s1 = S[1];
;         const f32x2 nm2 = {-mrefm, -mrefm};
;         f32x2 acc2 = {0.f, 0.f};
; #pragma unroll
;         for (int i = 0; i < 16; i += 2) {
;             f32x2 a = {s0[i], s0[i + 1]}, b = {s1[i], s1[i + 1]}; a += nm2; b += nm2;
;             a.x = fast_exp2(a.x); a.y = fast_exp2(a.y); b.x = fast_exp2(b.x); b.y = fast_exp2(b.y);
;             acc2 += a; acc2 += b; s0[i] = a.x; s0[i + 1] = a.y; s1[i] = b.x; s1[i + 1] = b.y;
;         }
;         lrunm += acc2.x + acc2.y;
; #pragma unroll
;         for (int s = 0; s < 2; ++s) {
;             u32x4 w0, w1;
;             w0.x = pk2(s0[8 * s + 0], s0[8 * s + 1]); w0.y = pk2(s0[8 * s + 2], s0[8 * s + 3]); w0.z = pk2(s0[8 * s + 4], s0[8 * s + 5]); w0.w = pk2(s0[8 * s + 6], s0[8 * s + 7]);
;             w1.x = pk2(s1[8 * s + 0], s1[8 * s + 1]); w1.y = pk2(s1[8 * s + 2], s1[8 * s + 3]); w1.z = pk2(s1[8 * s + 4], s1[8 * s + 5]); w1.w = pk2(s1[8 * s + 6], s1[8 * s + 7]);
;             pkm[0][s] = __builtin_bit_cast(bf16x8, w0); pkm[1][s] = __builtin_bit_cast(bf16x8, w1);
;         }
;     }
; }
; DI void att_vload(const LAS unsigned char* vb, int e, s16x4 (&lo)[4], s16x4 (&hi)[4]) {
;     constexpr int VP = 144;
; #pragma unroll
;     for (int q = 0; q < 4; ++q) { const LAS unsigned char* p = vb + (16 * q) * VP + 64 * e;
;         lo[q] = __builtin_bit_cast(s16x4, __builtin_amdgcn_ds_read_tr16_b64_v4i16((LAS s16x4*)p));
;         hi[q] = __builtin_bit_cast(s16x4, __builtin_amdgcn_ds_read_tr16_b64_v4i16((LAS s16x4*)(p + 8 * VP))); }
; }
; template <int NMAP>
; DI void att_pvmm(const s16x4 (&lo)[4], const s16x4 (&hi)[4], const bf16x8 (&pk)[NMAP][2][2], f32x16 (&o)[NMAP][2], int e) {
;     __builtin_amdgcn_s_setprio(1);
; #pragma unroll
;     for (int q = 0; q < 4; ++q) { const bf16x8 vf = (bf16x8){lo[q][0], lo[q][1], lo[q][2], lo[q][3], hi[q][0], hi[q][1], hi[q][2], hi[q][3]};
; #pragma unroll
;         for (int mp = 0; mp < NMAP; ++mp) o[mp][e] = __builtin_amdgcn_mfma_f32_32x32x16_bf16(vf, pk[mp][q >> 1][q & 1], o[mp][e], 0, 0, 0); }
;     __builtin_amdgcn_s_setprio(0);
; }
.LBB0_567:
	v_sub_f32_e32 v14, v48, v138
	v_sub_f32_e32 v15, v49, v138
	v_sub_f32_e32 v48, v64, v138
	v_sub_f32_e32 v49, v65, v138
	v_exp_f32_e32 v14, v14
	v_exp_f32_e32 v15, v15
	v_exp_f32_e32 v64, v48
	v_exp_f32_e32 v65, v49
	v_sub_f32_e32 v48, v50, v138
	v_sub_f32_e32 v49, v51, v138
	v_sub_f32_e32 v50, v66, v138
	v_sub_f32_e32 v51, v67, v138
	v_exp_f32_e32 v66, v48
	v_exp_f32_e32 v67, v49
	v_exp_f32_e32 v150, v50
	v_exp_f32_e32 v151, v51
	v_sub_f32_e32 v50, v52, v138
	v_sub_f32_e32 v51, v53, v138
	v_add_f32_e32 v48, 0, v14
	v_add_f32_e32 v49, 0, v15
	v_sub_f32_e32 v52, v68, v138
	v_sub_f32_e32 v53, v69, v138
	v_exp_f32_e32 v50, v50
	v_exp_f32_e32 v51, v51
	v_add_f32_e32 v48, v64, v48
	v_add_f32_e32 v49, v65, v49
	v_exp_f32_e32 v68, v52
	v_exp_f32_e32 v69, v53
	v_sub_f32_e32 v52, v54, v138
	v_sub_f32_e32 v53, v55, v138
	v_add_f32_e32 v48, v66, v48
	v_add_f32_e32 v49, v67, v49
	v_sub_f32_e32 v54, v70, v138
	v_sub_f32_e32 v55, v71, v138
	v_exp_f32_e32 v52, v52
	v_exp_f32_e32 v53, v53
	v_add_f32_e32 v48, v150, v48
	v_add_f32_e32 v49, v151, v49
	v_exp_f32_e32 v70, v54
	v_exp_f32_e32 v71, v55
	v_sub_f32_e32 v54, v56, v138
	v_sub_f32_e32 v55, v57, v138
	v_add_f32_e32 v48, v50, v48
	v_add_f32_e32 v49, v51, v49
	v_sub_f32_e32 v56, v72, v138
	v_sub_f32_e32 v57, v73, v138
	v_exp_f32_e32 v72, v54
	v_exp_f32_e32 v73, v55
	v_add_f32_e32 v48, v68, v48
	v_add_f32_e32 v49, v69, v49
	v_exp_f32_e32 v152, v56
	v_exp_f32_e32 v153, v57
	v_sub_f32_e32 v54, v58, v138
	v_sub_f32_e32 v55, v59, v138
	v_add_f32_e32 v48, v52, v48
	v_add_f32_e32 v49, v53, v49
	v_sub_f32_e32 v56, v74, v138
	v_sub_f32_e32 v57, v75, v138
	v_exp_f32_e32 v58, v54
	v_exp_f32_e32 v59, v55
	v_add_f32_e32 v48, v70, v48
	v_add_f32_e32 v49, v71, v49
	v_exp_f32_e32 v74, v56
	v_exp_f32_e32 v75, v57
	v_sub_f32_e32 v54, v60, v138
	v_sub_f32_e32 v55, v61, v138
	v_add_f32_e32 v48, v72, v48
	v_add_f32_e32 v49, v73, v49
	v_sub_f32_e32 v56, v76, v138
	v_sub_f32_e32 v57, v77, v138
	v_exp_f32_e32 v60, v54
	v_exp_f32_e32 v61, v55
	v_add_f32_e32 v48, v152, v48
	v_add_f32_e32 v49, v153, v49
	v_exp_f32_e32 v76, v56
	v_exp_f32_e32 v77, v57
	v_sub_f32_e32 v54, v62, v138
	v_sub_f32_e32 v55, v63, v138
	v_add_f32_e32 v48, v58, v48
	v_add_f32_e32 v49, v59, v49
	v_sub_f32_e32 v56, v78, v138
	v_sub_f32_e32 v57, v79, v138
	v_exp_f32_e32 v62, v54
	v_exp_f32_e32 v63, v55
	v_add_f32_e32 v48, v74, v48
	v_add_f32_e32 v49, v75, v49
	v_exp_f32_e32 v78, v56
	v_exp_f32_e32 v79, v57
	v_add_f32_e32 v48, v60, v48
	v_add_f32_e32 v49, v61, v49
	v_cvt_pk_bf16_f32 v50, v50, v51
	v_add_f32_e32 v48, v76, v48
	v_add_f32_e32 v49, v77, v49
	v_cvt_pk_bf16_f32 v51, v52, v53
	v_add_f32_e32 v48, v62, v48
	v_add_f32_e32 v49, v63, v49
	v_cvt_pk_bf16_f32 v52, v64, v65
	v_add_f32_e32 v48, v78, v48
	v_add_f32_e32 v49, v79, v49
	v_cvt_pk_bf16_f32 v53, v150, v151
	v_add_f32_e32 v0, v48, v49
	v_add_f32_e32 v143, v143, v0
	v_cvt_pk_bf16_f32 v48, v14, v15
	v_cvt_pk_bf16_f32 v49, v66, v67
	v_cvt_pk_bf16_f32 v54, v68, v69
	v_cvt_pk_bf16_f32 v55, v70, v71
	v_cvt_pk_bf16_f32 v56, v72, v73
	v_cvt_pk_bf16_f32 v57, v58, v59
	v_cvt_pk_bf16_f32 v58, v60, v61
	v_cvt_pk_bf16_f32 v59, v62, v63
	v_cvt_pk_bf16_f32 v60, v152, v153
	v_cvt_pk_bf16_f32 v61, v74, v75
	v_cvt_pk_bf16_f32 v62, v76, v77
	v_cvt_pk_bf16_f32 v63, v78, v79
	s_setprio 1
	s_waitcnt lgkmcnt(6)
	v_mfma_f32_32x32x16_bf16 v[32:47], v[120:123], v[48:51], v[32:47]
	s_waitcnt lgkmcnt(4)
	v_mfma_f32_32x32x16_bf16 v[32:47], v[116:119], v[56:59], v[32:47]
	s_waitcnt lgkmcnt(2)
	v_mfma_f32_32x32x16_bf16 v[32:47], v[112:115], v[52:55], v[32:47]
	s_waitcnt lgkmcnt(0)
	v_mfma_f32_32x32x16_bf16 v[32:47], v[10:13], v[60:63], v[32:47]
	s_setprio 0
	ds_read_b64_tr_b16 v[10:11], v148 offset:36928
	ds_read_b64_tr_b16 v[12:13], v148 offset:38080
	ds_read_b64_tr_b16 v[64:65], v148 offset:39232
	ds_read_b64_tr_b16 v[66:67], v148 offset:40384
	ds_read_b64_tr_b16 v[68:69], v148 offset:41536
	ds_read_b64_tr_b16 v[70:71], v148 offset:42688
	ds_read_b64_tr_b16 v[72:73], v148 offset:43840
	ds_read_b64_tr_b16 v[74:75], v148 offset:44992
	s_setprio 1
	s_waitcnt lgkmcnt(6)
	v_mfma_f32_32x32x16_bf16 v[16:31], v[10:13], v[48:51], v[16:31]
	s_waitcnt lgkmcnt(4)
	v_mfma_f32_32x32x16_bf16 v[16:31], v[64:67], v[56:59], v[16:31]
	s_waitcnt lgkmcnt(2)
	v_mfma_f32_32x32x16_bf16 v[16:31], v[68:71], v[52:55], v[16:31]
	s_waitcnt lgkmcnt(0)
	v_mfma_f32_32x32x16_bf16 v[16:31], v[72:75], v[60:63], v[16:31]
	s_setprio 0

; DI unsigned pk2(float lo, float hi) { f32x2 v = {lo, hi}; bf16x2_t b = __builtin_convertvector(v, bf16x2_t); return __builtin_bit_cast(unsigned, b); }
; DI float fast_exp2(float x) { return __builtin_amdgcn_exp2f(x); }
; DI void att_sm_tail(f32x16 (&S)[2], bf16x8 (&pkm)[2][2], const float mrefm, float& lrunm) {
;     {
;         f32x16& s0 = S[0]; f32x16& s1 = S[1];
;         const f32x2 nm2 = {-mrefm, -mrefm};
;         f32x2 acc2 = {0.f, 0.f};
; #pragma unroll
;         for (int i = 0; i < 16; i += 2) {
;             f32x2 a = {s0[i], s0[i + 1]}, b = {s1[i], s1[i + 1]}; a += nm2; b += nm2;
;             a.x = fast_exp2(a.x); a.y = fast_exp2(a.y); b.x = fast_exp2(b.x); b.y = fast_exp2(b.y);
;             acc2 += a; acc2 += b; s0[i] = a.x; s0[i + 1] = a.y; s1[i] = b.x; s1[i + 1] = b.y;
;         }
;         lrunm += acc2.x + acc2.y;
; #pragma unroll
;         for (int s = 0; s < 2; ++s) {
;             u32x4 w0, w1;
;             w0.x = pk2(s0[8 * s + 0], s0[8 * s + 1]); w0.y = pk2(s0[8 * s + 2], s0[8 * s + 3]); w0.z = pk2(s0[8 * s + 4], s0[8 * s + 5]); w0.w = pk2(s0[8 * s + 6], s0[8 * s + 7]);
;             w1.x = pk2(s1[8 * s + 0], s1[8 * s + 1]); w1.y = pk2(s1[8 * s + 2], s1[8 * s + 3]); w1.z = pk2(s1[8 * s + 4], s1[8 * s + 5]); w1.w = pk2(s1[8 * s + 6], s1[8 * s + 7]);
;             pkm[0][s] = __builtin_bit_cast(bf16x8, w0); pkm[1][s] = __builtin_bit_cast(bf16x8, w1);
;         }
;     }
; }
.LBB0_579:
	v_sub_f32_e32 v14, v112, v212
	v_sub_f32_e32 v15, v113, v212
	v_sub_f32_e32 v112, v128, v212
	v_sub_f32_e32 v113, v129, v212
	v_exp_f32_e32 v14, v14
	v_exp_f32_e32 v15, v15
	v_exp_f32_e32 v112, v112
	v_exp_f32_e32 v113, v113
	v_sub_f32_e32 v114, v114, v212
	v_sub_f32_e32 v115, v115, v212
	v_sub_f32_e32 v128, v130, v212
	v_sub_f32_e32 v129, v131, v212
	v_exp_f32_e32 v114, v114
	v_exp_f32_e32 v115, v115
	v_exp_f32_e32 v128, v128
	v_exp_f32_e32 v129, v129
	v_sub_f32_e32 v116, v116, v212
	v_sub_f32_e32 v117, v117, v212
	v_add_f32_e32 v130, 0, v14
	v_add_f32_e32 v131, 0, v15
	v_sub_f32_e32 v132, v132, v212
	v_sub_f32_e32 v133, v133, v212
	v_exp_f32_e32 v116, v116
	v_exp_f32_e32 v117, v117
	v_add_f32_e32 v130, v112, v130
	v_add_f32_e32 v131, v113, v131
	v_exp_f32_e32 v132, v132
	v_exp_f32_e32 v133, v133
	v_sub_f32_e32 v118, v118, v212
	v_sub_f32_e32 v119, v119, v212
	v_add_f32_e32 v130, v114, v130
	v_add_f32_e32 v131, v115, v131
	v_sub_f32_e32 v134, v134, v212
	v_sub_f32_e32 v135, v135, v212
	v_exp_f32_e32 v118, v118
	v_exp_f32_e32 v119, v119
	v_add_f32_e32 v130, v128, v130
	v_add_f32_e32 v131, v129, v131
	v_exp_f32_e32 v134, v134
	v_exp_f32_e32 v135, v135
	v_sub_f32_e32 v120, v120, v212
	v_sub_f32_e32 v121, v121, v212
	v_add_f32_e32 v130, v116, v130
	v_add_f32_e32 v131, v117, v131
	v_sub_f32_e32 v136, v136, v212
	v_sub_f32_e32 v137, v137, v212
	v_exp_f32_e32 v246, v120
	v_exp_f32_e32 v247, v121
	v_add_f32_e32 v130, v132, v130
	v_add_f32_e32 v131, v133, v131
	v_exp_f32_e32 v136, v136
	v_exp_f32_e32 v137, v137
	v_sub_f32_e32 v120, v122, v212
	v_sub_f32_e32 v121, v123, v212
	v_add_f32_e32 v130, v118, v130
	v_add_f32_e32 v131, v119, v131
	v_sub_f32_e32 v122, v138, v212
	v_sub_f32_e32 v123, v139, v212
	v_exp_f32_e32 v138, v120
	v_exp_f32_e32 v139, v121
	v_add_f32_e32 v130, v134, v130
	v_add_f32_e32 v131, v135, v131
	v_exp_f32_e32 v248, v122
	v_exp_f32_e32 v249, v123
	v_sub_f32_e32 v122, v124, v212
	v_sub_f32_e32 v123, v125, v212
	v_add_f32_e32 v120, v246, v130
	v_add_f32_e32 v121, v247, v131
	v_sub_f32_e32 v124, v140, v212
	v_sub_f32_e32 v125, v141, v212
	v_exp_f32_e32 v130, v122
	v_exp_f32_e32 v131, v123
	v_add_f32_e32 v120, v136, v120
	v_add_f32_e32 v121, v137, v121
	v_exp_f32_e32 v140, v124
	v_exp_f32_e32 v141, v125
	v_sub_f32_e32 v122, v126, v212
	v_sub_f32_e32 v123, v127, v212
	v_add_f32_e32 v120, v138, v120
	v_add_f32_e32 v121, v139, v121
	v_sub_f32_e32 v124, v142, v212
	v_sub_f32_e32 v125, v143, v212
	v_exp_f32_e32 v142, v122
	v_exp_f32_e32 v143, v123
	v_add_f32_e32 v120, v248, v120
	v_add_f32_e32 v121, v249, v121
	v_exp_f32_e32 v250, v124
	v_exp_f32_e32 v251, v125
	v_add_f32_e32 v120, v130, v120
	v_add_f32_e32 v121, v131, v121
	v_cvt_pk_bf16_f32 v122, v116, v117
	v_add_f32_e32 v120, v140, v120
	v_add_f32_e32 v121, v141, v121
	v_cvt_pk_bf16_f32 v123, v118, v119
	v_add_f32_e32 v120, v142, v120
	v_add_f32_e32 v121, v143, v121
	v_cvt_pk_bf16_f32 v112, v112, v113
	v_add_f32_e32 v120, v250, v120
	v_add_f32_e32 v121, v251, v121
	v_cvt_pk_bf16_f32 v113, v128, v129
	v_add_f32_e32 v120, v120, v121
	v_add_f32_e32 v245, v245, v120
	v_cvt_pk_bf16_f32 v120, v14, v15
	v_cvt_pk_bf16_f32 v121, v114, v115
	v_cvt_pk_bf16_f32 v114, v132, v133
	v_cvt_pk_bf16_f32 v115, v134, v135
	v_cvt_pk_bf16_f32 v124, v246, v247
	v_cvt_pk_bf16_f32 v125, v138, v139
	v_cvt_pk_bf16_f32 v126, v130, v131
	v_cvt_pk_bf16_f32 v127, v142, v143
	v_cvt_pk_bf16_f32 v116, v136, v137
	v_cvt_pk_bf16_f32 v117, v248, v249
	v_cvt_pk_bf16_f32 v118, v140, v141
	v_cvt_pk_bf16_f32 v119, v250, v251
	s_waitcnt lgkmcnt(6)
; DI void att_sm_tail(f32x16 (&S)[2], bf16x8 (&pkm)[2][2], const float mrefm, float& lrunm) {
;     {
;         f32x16& s0 = S[0]; f32x16& s1 = S[1];
;         const f32x2 nm2 = {-mrefm, -mrefm};
;         f32x2 acc2 = {0.f, 0.f};
; #pragma unroll
;         for (int i = 0; i < 16; i += 2) {
;             f32x2 a = {s0[i], s0[i + 1]}, b = {s1[i], s1[i + 1]}; a += nm2; b += nm2;
;             a.x = fast_exp2(a.x); a.y = fast_exp2(a.y); b.x = fast_exp2(b.x); b.y = fast_exp2(b.y);
;             acc2 += a; acc2 += b; s0[i] = a.x; s0[i + 1] = a.y; s1[i] = b.x; s1[i + 1] = b.y;
;         }
;         lrunm += acc2.x + acc2.y;
; #pragma unroll
;         for (int s = 0; s < 2; ++s) {
;             u32x4 w0, w1;
;             w0.x = pk2(s0[8 * s + 0], s0[8 * s + 1]); w0.y = pk2(s0[8 * s + 2], s0[8 * s + 3]); w0.z = pk2(s0[8 * s + 4], s0[8 * s + 5]); w0.w = pk2(s0[8 * s + 6], s0[8 * s + 7]);
;             w1.x = pk2(s1[8 * s + 0], s1[8 * s + 1]); w1.y = pk2(s1[8 * s + 2], s1[8 * s + 3]); w1.z = pk2(s1[8 * s + 4], s1[8 * s + 5]); w1.w = pk2(s1[8 * s + 6], s1[8 * s + 7]);
;             pkm[0][s] = __builtin_bit_cast(bf16x8, w0); pkm[1][s] = __builtin_bit_cast(bf16x8, w1);
;         }
;     }
; }
; DI void att_pvmm1(const s16x4 (&lo)[4], const s16x4 (&hi)[4], const bf16x8 (&pkm)[2][2], f32x16& oe) {
; #pragma unroll
;     for (int q = 0; q < 4; ++q) { const bf16x8 vf = (bf16x8){lo[q][0], lo[q][1], lo[q][2], lo[q][3], hi[q][0], hi[q][1], hi[q][2], hi[q][3]};
;         oe = __builtin_amdgcn_mfma_f32_32x32x16_bf16(vf, pkm[q >> 1][q & 1], oe, 0, 0, 0); }
; }
; DI void att_vload(const LAS unsigned char* vb, int e, s16x4 (&lo)[4], s16x4 (&hi)[4]) {
;     constexpr int VP = 144;
; #pragma unroll
;     for (int q = 0; q < 4; ++q) { const LAS unsigned char* p = vb + (16 * q) * VP + 64 * e;
;         lo[q] = __builtin_bit_cast(s16x4, __builtin_amdgcn_ds_read_tr16_b64_v4i16((LAS s16x4*)p));
;         hi[q] = __builtin_bit_cast(s16x4, __builtin_amdgcn_ds_read_tr16_b64_v4i16((LAS s16x4*)(p + 8 * VP))); }
; }
; template <int NMAP>
; DI void att_pvmm(const s16x4 (&lo)[4], const s16x4 (&hi)[4], const bf16x8 (&pk)[NMAP][2][2], f32x16 (&o)[NMAP][2], int e) {
;     __builtin_amdgcn_s_setprio(1);
; #pragma unroll
;     for (int q = 0; q < 4; ++q) { const bf16x8 vf = (bf16x8){lo[q][0], lo[q][1], lo[q][2], lo[q][3], hi[q][0], hi[q][1], hi[q][2], hi[q][3]};
; #pragma unroll
	v_mfma_f32_32x32x16_bf16 v[64:79], v[188:191], v[120:123], v[64:79]
	v_add_f32_e64 v14, v80, -v210
	v_add_f32_e64 v15, v81, -v210
	v_add_f32_e64 v80, v96, -v210
	v_add_f32_e64 v81, v97, -v210
	v_exp_f32_e32 v14, v14
	v_exp_f32_e32 v15, v15
	v_exp_f32_e32 v96, v80
	v_exp_f32_e32 v97, v81
	v_sub_f32_e32 v82, v82, v210
	v_sub_f32_e32 v83, v83, v210
	v_sub_f32_e32 v98, v98, v210
	v_sub_f32_e32 v99, v99, v210
	v_exp_f32_e32 v82, v82
	v_exp_f32_e32 v83, v83
	v_exp_f32_e32 v98, v98
	v_exp_f32_e32 v99, v99
	v_sub_f32_e32 v84, v84, v210
	v_sub_f32_e32 v85, v85, v210
	v_add_f32_e32 v80, 0, v14
	v_add_f32_e32 v81, 0, v15
	v_sub_f32_e32 v100, v100, v210
	v_sub_f32_e32 v101, v101, v210
	v_exp_f32_e32 v84, v84
	v_exp_f32_e32 v85, v85
	v_add_f32_e32 v80, v96, v80
	v_add_f32_e32 v81, v97, v81
	v_exp_f32_e32 v100, v100
	v_exp_f32_e32 v101, v101
	v_sub_f32_e32 v86, v86, v210
	v_sub_f32_e32 v87, v87, v210
	v_add_f32_e32 v80, v82, v80
	v_add_f32_e32 v81, v83, v81
	v_sub_f32_e32 v102, v102, v210
	v_sub_f32_e32 v103, v103, v210
	v_exp_f32_e32 v86, v86
	v_exp_f32_e32 v87, v87
	v_add_f32_e32 v80, v98, v80
	v_add_f32_e32 v81, v99, v81
	v_exp_f32_e32 v102, v102
	v_exp_f32_e32 v103, v103
	v_sub_f32_e32 v88, v88, v210
	v_sub_f32_e32 v89, v89, v210
	v_add_f32_e32 v80, v84, v80
	v_add_f32_e32 v81, v85, v81
	v_sub_f32_e32 v104, v104, v210
	v_sub_f32_e32 v105, v105, v210
	v_exp_f32_e32 v88, v88
	v_exp_f32_e32 v89, v89
	v_add_f32_e32 v80, v100, v80
	v_add_f32_e32 v81, v101, v81
	v_exp_f32_e32 v104, v104
	v_exp_f32_e32 v105, v105
	v_add_f32_e32 v80, v86, v80
	v_add_f32_e32 v81, v87, v81
	s_nop 0
	v_add_f32_e32 v80, v102, v80
	v_add_f32_e32 v81, v103, v81
	s_nop 0
	v_add_f32_e32 v80, v88, v80
	v_add_f32_e32 v81, v89, v81
	s_nop 0
	v_add_f32_e32 v80, v104, v80
	v_add_f32_e32 v81, v105, v81
	s_waitcnt lgkmcnt(4)
	v_mfma_f32_32x32x16_bf16 v[64:79], v[184:187], v[124:127], v[64:79]
	v_add_f32_e64 v90, v90, -v210
	v_add_f32_e64 v91, v91, -v210
	v_add_f32_e64 v106, v106, -v210
	v_add_f32_e64 v107, v107, -v210
	v_exp_f32_e32 v90, v90
	v_exp_f32_e32 v91, v91
	v_exp_f32_e32 v106, v106
	v_exp_f32_e32 v107, v107
	v_sub_f32_e32 v92, v92, v210
	v_sub_f32_e32 v93, v93, v210
	v_sub_f32_e32 v108, v108, v210
	v_sub_f32_e32 v109, v109, v210
	v_exp_f32_e32 v92, v92
	v_exp_f32_e32 v93, v93
	v_exp_f32_e32 v108, v108
	v_exp_f32_e32 v109, v109
	v_sub_f32_e32 v94, v94, v210
	v_sub_f32_e32 v95, v95, v210
	v_add_f32_e32 v80, v90, v80
	v_add_f32_e32 v81, v91, v81
	v_sub_f32_e32 v110, v110, v210
	v_sub_f32_e32 v111, v111, v210
	v_exp_f32_e32 v94, v94
	v_exp_f32_e32 v95, v95
	v_add_f32_e32 v80, v106, v80
	v_add_f32_e32 v81, v107, v81
	v_exp_f32_e32 v110, v110
	v_exp_f32_e32 v111, v111
	v_add_f32_e32 v80, v92, v80
	v_add_f32_e32 v81, v93, v81
	s_nop 0
	v_add_f32_e32 v80, v108, v80
	v_add_f32_e32 v81, v109, v81
	s_nop 0
	v_add_f32_e32 v80, v94, v80
	v_add_f32_e32 v81, v95, v81
	s_nop 0
	v_add_f32_e32 v80, v110, v80
	v_add_f32_e32 v81, v111, v81
	s_nop 0
	v_add_f32_e32 v80, v80, v81
	v_add_f32_e32 v236, v236, v80
	v_cvt_pk_bf16_f32 v80, v14, v15
	v_cvt_pk_bf16_f32 v81, v82, v83
	v_cvt_pk_bf16_f32 v82, v84, v85
	v_cvt_pk_bf16_f32 v83, v86, v87
	v_cvt_pk_bf16_f32 v84, v96, v97
	v_cvt_pk_bf16_f32 v85, v98, v99
	s_waitcnt lgkmcnt(2)
	v_mfma_f32_32x32x16_bf16 v[64:79], v[180:183], v[112:115], v[64:79]
	v_cvt_pk_bf16_f32 v86, v100, v101
	v_cvt_pk_bf16_f32 v87, v102, v103
	v_cvt_pk_bf16_f32 v88, v88, v89
	v_cvt_pk_bf16_f32 v89, v90, v91
	v_cvt_pk_bf16_f32 v90, v92, v93
	v_cvt_pk_bf16_f32 v91, v94, v95
	v_cvt_pk_bf16_f32 v92, v104, v105
	v_cvt_pk_bf16_f32 v93, v106, v107
	v_cvt_pk_bf16_f32 v94, v108, v109
	v_cvt_pk_bf16_f32 v95, v110, v111
	s_waitcnt lgkmcnt(0)
	v_mfma_f32_32x32x16_bf16 v[64:79], v[10:13], v[116:119], v[64:79]
	v_mfma_f32_32x32x16_bf16 v[48:63], v[188:191], v[80:83], v[48:63]
	v_mfma_f32_32x32x16_bf16 v[48:63], v[184:187], v[88:91], v[48:63]
	v_mfma_f32_32x32x16_bf16 v[48:63], v[180:183], v[84:87], v[48:63]
	v_mfma_f32_32x32x16_bf16 v[48:63], v[10:13], v[92:95], v[48:63]
	ds_read_b64_tr_b16 v[10:11], v0 offset:18496
	ds_read_b64_tr_b16 v[12:13], v0 offset:19648
	ds_read_b64_tr_b16 v[96:97], v0 offset:20800
	ds_read_b64_tr_b16 v[98:99], v0 offset:21952
	ds_read_b64_tr_b16 v[100:101], v0 offset:23104
	ds_read_b64_tr_b16 v[102:103], v0 offset:24256
	ds_read_b64_tr_b16 v[104:105], v0 offset:25408
	ds_read_b64_tr_b16 v[106:107], v0 offset:26560
	s_setprio 1
	s_waitcnt lgkmcnt(6)
	v_mfma_f32_32x32x16_bf16 v[32:47], v[10:13], v[120:123], v[32:47]
	v_mfma_f32_32x32x16_bf16 v[16:31], v[10:13], v[80:83], v[16:31]
	s_waitcnt lgkmcnt(4)
	v_mfma_f32_32x32x16_bf16 v[32:47], v[96:99], v[124:127], v[32:47]
	v_mfma_f32_32x32x16_bf16 v[16:31], v[96:99], v[88:91], v[16:31]
	s_waitcnt lgkmcnt(2)
	v_mfma_f32_32x32x16_bf16 v[32:47], v[100:103], v[112:115], v[32:47]
	v_mfma_f32_32x32x16_bf16 v[16:31], v[100:103], v[84:87], v[16:31]
	s_waitcnt lgkmcnt(0)
	v_mfma_f32_32x32x16_bf16 v[32:47], v[104:107], v[116:119], v[32:47]
	v_mfma_f32_32x32x16_bf16 v[16:31], v[104:107], v[92:95], v[16:31]
	s_setprio 0

; DI unsigned pk2(float lo, float hi) { f32x2 v = {lo, hi}; bf16x2_t b = __builtin_convertvector(v, bf16x2_t); return __builtin_bit_cast(unsigned, b); }
; DI float fast_exp2(float x) { return __builtin_amdgcn_exp2f(x); }
; DI void att_sm_tail(f32x16 (&S)[2], bf16x8 (&pkm)[2][2], const float mrefm, float& lrunm) {
;     {
;         f32x16& s0 = S[0]; f32x16& s1 = S[1];
;         const f32x2 nm2 = {-mrefm, -mrefm};
;         f32x2 acc2 = {0.f, 0.f};
; #pragma unroll
;         for (int i = 0; i < 16; i += 2) {
;             f32x2 a = {s0[i], s0[i + 1]}, b = {s1[i], s1[i + 1]}; a += nm2; b += nm2;
;             a.x = fast_exp2(a.x); a.y = fast_exp2(a.y); b.x = fast_exp2(b.x); b.y = fast_exp2(b.y);
;             acc2 += a; acc2 += b; s0[i] = a.x; s0[i + 1] = a.y; s1[i] = b.x; s1[i + 1] = b.y;
;         }
;         lrunm += acc2.x + acc2.y;
; #pragma unroll
;         for (int s = 0; s < 2; ++s) {
;             u32x4 w0, w1;
;             w0.x = pk2(s0[8 * s + 0], s0[8 * s + 1]); w0.y = pk2(s0[8 * s + 2], s0[8 * s + 3]); w0.z = pk2(s0[8 * s + 4], s0[8 * s + 5]); w0.w = pk2(s0[8 * s + 6], s0[8 * s + 7]);
;             w1.x = pk2(s1[8 * s + 0], s1[8 * s + 1]); w1.y = pk2(s1[8 * s + 2], s1[8 * s + 3]); w1.z = pk2(s1[8 * s + 4], s1[8 * s + 5]); w1.w = pk2(s1[8 * s + 6], s1[8 * s + 7]);
;             pkm[0][s] = __builtin_bit_cast(bf16x8, w0); pkm[1][s] = __builtin_bit_cast(bf16x8, w1);
;         }
;     }
; }
.LBB0_585:
	v_sub_f32_e32 v14, v112, v212
	v_sub_f32_e32 v15, v113, v212
	v_sub_f32_e32 v112, v128, v212
	v_sub_f32_e32 v113, v129, v212
	v_exp_f32_e32 v14, v14
	v_exp_f32_e32 v15, v15
	v_exp_f32_e32 v112, v112
	v_exp_f32_e32 v113, v113
	v_sub_f32_e32 v114, v114, v212
	v_sub_f32_e32 v115, v115, v212
	v_sub_f32_e32 v128, v130, v212
	v_sub_f32_e32 v129, v131, v212
	v_exp_f32_e32 v114, v114
	v_exp_f32_e32 v115, v115
	v_exp_f32_e32 v128, v128
	v_exp_f32_e32 v129, v129
	v_sub_f32_e32 v116, v116, v212
	v_sub_f32_e32 v117, v117, v212
	v_add_f32_e32 v130, 0, v14
	v_add_f32_e32 v131, 0, v15
	v_sub_f32_e32 v132, v132, v212
	v_sub_f32_e32 v133, v133, v212
	v_exp_f32_e32 v116, v116
	v_exp_f32_e32 v117, v117
	v_add_f32_e32 v130, v112, v130
	v_add_f32_e32 v131, v113, v131
	v_exp_f32_e32 v132, v132
	v_exp_f32_e32 v133, v133
	v_sub_f32_e32 v118, v118, v212
	v_sub_f32_e32 v119, v119, v212
	v_add_f32_e32 v130, v114, v130
	v_add_f32_e32 v131, v115, v131
	v_sub_f32_e32 v134, v134, v212
	v_sub_f32_e32 v135, v135, v212
	v_exp_f32_e32 v118, v118
	v_exp_f32_e32 v119, v119
	v_add_f32_e32 v130, v128, v130
	v_add_f32_e32 v131, v129, v131
	v_exp_f32_e32 v134, v134
	v_exp_f32_e32 v135, v135
	v_sub_f32_e32 v120, v120, v212
	v_sub_f32_e32 v121, v121, v212
	v_add_f32_e32 v130, v116, v130
	v_add_f32_e32 v131, v117, v131
	v_sub_f32_e32 v136, v136, v212
	v_sub_f32_e32 v137, v137, v212
	v_exp_f32_e32 v246, v120
	v_exp_f32_e32 v247, v121
	v_add_f32_e32 v130, v132, v130
	v_add_f32_e32 v131, v133, v131
	v_exp_f32_e32 v136, v136
	v_exp_f32_e32 v137, v137
	v_sub_f32_e32 v120, v122, v212
	v_sub_f32_e32 v121, v123, v212
	v_add_f32_e32 v130, v118, v130
	v_add_f32_e32 v131, v119, v131
	v_sub_f32_e32 v122, v138, v212
	v_sub_f32_e32 v123, v139, v212
	v_exp_f32_e32 v138, v120
	v_exp_f32_e32 v139, v121
	v_add_f32_e32 v130, v134, v130
	v_add_f32_e32 v131, v135, v131
	v_exp_f32_e32 v248, v122
	v_exp_f32_e32 v249, v123
	v_sub_f32_e32 v122, v124, v212
	v_sub_f32_e32 v123, v125, v212
	v_add_f32_e32 v120, v246, v130
	v_add_f32_e32 v121, v247, v131
	v_sub_f32_e32 v124, v140, v212
	v_sub_f32_e32 v125, v141, v212
	v_exp_f32_e32 v130, v122
	v_exp_f32_e32 v131, v123
	v_add_f32_e32 v120, v136, v120
	v_add_f32_e32 v121, v137, v121
	v_exp_f32_e32 v140, v124
	v_exp_f32_e32 v141, v125
	v_sub_f32_e32 v122, v126, v212
	v_sub_f32_e32 v123, v127, v212
	v_add_f32_e32 v120, v138, v120
	v_add_f32_e32 v121, v139, v121
	v_sub_f32_e32 v124, v142, v212
	v_sub_f32_e32 v125, v143, v212
	v_exp_f32_e32 v142, v122
	v_exp_f32_e32 v143, v123
	v_add_f32_e32 v120, v248, v120
	v_add_f32_e32 v121, v249, v121
	v_exp_f32_e32 v250, v124
	v_exp_f32_e32 v251, v125
	v_add_f32_e32 v120, v130, v120
	v_add_f32_e32 v121, v131, v121
	v_cvt_pk_bf16_f32 v122, v116, v117
	v_add_f32_e32 v120, v140, v120
	v_add_f32_e32 v121, v141, v121
	v_cvt_pk_bf16_f32 v123, v118, v119
	v_add_f32_e32 v120, v142, v120
	v_add_f32_e32 v121, v143, v121
	v_cvt_pk_bf16_f32 v112, v112, v113
	v_add_f32_e32 v120, v250, v120
	v_add_f32_e32 v121, v251, v121
	v_cvt_pk_bf16_f32 v113, v128, v129
	v_add_f32_e32 v120, v120, v121
	v_add_f32_e32 v245, v245, v120
	v_cvt_pk_bf16_f32 v120, v14, v15
	v_cvt_pk_bf16_f32 v121, v114, v115
	v_cvt_pk_bf16_f32 v114, v132, v133
	v_cvt_pk_bf16_f32 v115, v134, v135
	v_cvt_pk_bf16_f32 v124, v246, v247
	v_cvt_pk_bf16_f32 v125, v138, v139
	v_cvt_pk_bf16_f32 v126, v130, v131
	v_cvt_pk_bf16_f32 v127, v142, v143
	v_cvt_pk_bf16_f32 v116, v136, v137
	v_cvt_pk_bf16_f32 v117, v248, v249
	v_cvt_pk_bf16_f32 v118, v140, v141
	v_cvt_pk_bf16_f32 v119, v250, v251
	s_waitcnt lgkmcnt(3)
; DI void att_sm_tail(f32x16 (&S)[2], bf16x8 (&pkm)[2][2], const float mrefm, float& lrunm) {
;     {
;         f32x16& s0 = S[0]; f32x16& s1 = S[1];
;         const f32x2 nm2 = {-mrefm, -mrefm};
;         f32x2 acc2 = {0.f, 0.f};
; #pragma unroll
;         for (int i = 0; i < 16; i += 2) {
;             f32x2 a = {s0[i], s0[i + 1]}, b = {s1[i], s1[i + 1]}; a += nm2; b += nm2;
;             a.x = fast_exp2(a.x); a.y = fast_exp2(a.y); b.x = fast_exp2(b.x); b.y = fast_exp2(b.y);
;             acc2 += a; acc2 += b; s0[i] = a.x; s0[i + 1] = a.y; s1[i] = b.x; s1[i + 1] = b.y;
;         }
;         lrunm += acc2.x + acc2.y;
; #pragma unroll
;         for (int s = 0; s < 2; ++s) {
;             u32x4 w0, w1;
;             w0.x = pk2(s0[8 * s + 0], s0[8 * s + 1]); w0.y = pk2(s0[8 * s + 2], s0[8 * s + 3]); w0.z = pk2(s0[8 * s + 4], s0[8 * s + 5]); w0.w = pk2(s0[8 * s + 6], s0[8 * s + 7]);
;             w1.x = pk2(s1[8 * s + 0], s1[8 * s + 1]); w1.y = pk2(s1[8 * s + 2], s1[8 * s + 3]); w1.z = pk2(s1[8 * s + 4], s1[8 * s + 5]); w1.w = pk2(s1[8 * s + 6], s1[8 * s + 7]);
;             pkm[0][s] = __builtin_bit_cast(bf16x8, w0); pkm[1][s] = __builtin_bit_cast(bf16x8, w1);
;         }
;     }
; }
; DI void att_pvmm1(const s16x4 (&lo)[4], const s16x4 (&hi)[4], const bf16x8 (&pkm)[2][2], f32x16& oe) {
; #pragma unroll
;     for (int q = 0; q < 4; ++q) { const bf16x8 vf = (bf16x8){lo[q][0], lo[q][1], lo[q][2], lo[q][3], hi[q][0], hi[q][1], hi[q][2], hi[q][3]};
;         oe = __builtin_amdgcn_mfma_f32_32x32x16_bf16(vf, pkm[q >> 1][q & 1], oe, 0, 0, 0); }
; }
; DI void att_vload(const LAS unsigned char* vb, int e, s16x4 (&lo)[4], s16x4 (&hi)[4]) {
;     constexpr int VP = 144;
; #pragma unroll
;     for (int q = 0; q < 4; ++q) { const LAS unsigned char* p = vb + (16 * q) * VP + 64 * e;
;         lo[q] = __builtin_bit_cast(s16x4, __builtin_amdgcn_ds_read_tr16_b64_v4i16((LAS s16x4*)p));
;         hi[q] = __builtin_bit_cast(s16x4, __builtin_amdgcn_ds_read_tr16_b64_v4i16((LAS s16x4*)(p + 8 * VP))); }
; }
; template <int NMAP>
; DI void att_pvmm(const s16x4 (&lo)[4], const s16x4 (&hi)[4], const bf16x8 (&pk)[NMAP][2][2], f32x16 (&o)[NMAP][2], int e) {
;     __builtin_amdgcn_s_setprio(1);
; #pragma unroll
;     for (int q = 0; q < 4; ++q) { const bf16x8 vf = (bf16x8){lo[q][0], lo[q][1], lo[q][2], lo[q][3], hi[q][0], hi[q][1], hi[q][2], hi[q][3]};
; #pragma unroll
	v_mfma_f32_32x32x16_bf16 v[64:79], v[188:191], v[120:123], v[64:79]
	v_add_f32_e64 v14, v80, -v210
	v_add_f32_e64 v15, v81, -v210
	v_add_f32_e64 v80, v96, -v210
	v_add_f32_e64 v81, v97, -v210
	v_exp_f32_e32 v14, v14
	v_exp_f32_e32 v15, v15
	v_exp_f32_e32 v96, v80
	v_exp_f32_e32 v97, v81
	v_sub_f32_e32 v82, v82, v210
	v_sub_f32_e32 v83, v83, v210
	v_sub_f32_e32 v98, v98, v210
	v_sub_f32_e32 v99, v99, v210
	v_exp_f32_e32 v82, v82
	v_exp_f32_e32 v83, v83
	v_exp_f32_e32 v98, v98
	v_exp_f32_e32 v99, v99
	v_sub_f32_e32 v84, v84, v210
	v_sub_f32_e32 v85, v85, v210
	v_add_f32_e32 v80, 0, v14
	v_add_f32_e32 v81, 0, v15
	v_sub_f32_e32 v100, v100, v210
	v_sub_f32_e32 v101, v101, v210
	v_exp_f32_e32 v84, v84
	v_exp_f32_e32 v85, v85
	v_add_f32_e32 v80, v96, v80
	v_add_f32_e32 v81, v97, v81
	v_exp_f32_e32 v100, v100
	v_exp_f32_e32 v101, v101
	v_sub_f32_e32 v86, v86, v210
	v_sub_f32_e32 v87, v87, v210
	v_add_f32_e32 v80, v82, v80
	v_add_f32_e32 v81, v83, v81
	v_sub_f32_e32 v102, v102, v210
	v_sub_f32_e32 v103, v103, v210
	v_exp_f32_e32 v86, v86
	v_exp_f32_e32 v87, v87
	v_add_f32_e32 v80, v98, v80
	v_add_f32_e32 v81, v99, v81
	v_exp_f32_e32 v102, v102
	v_exp_f32_e32 v103, v103
	v_sub_f32_e32 v88, v88, v210
	v_sub_f32_e32 v89, v89, v210
	v_add_f32_e32 v80, v84, v80
	v_add_f32_e32 v81, v85, v81
	v_sub_f32_e32 v104, v104, v210
	v_sub_f32_e32 v105, v105, v210
	v_exp_f32_e32 v88, v88
	v_exp_f32_e32 v89, v89
	v_add_f32_e32 v80, v100, v80
	v_add_f32_e32 v81, v101, v81
	v_exp_f32_e32 v104, v104
	v_exp_f32_e32 v105, v105
	v_add_f32_e32 v80, v86, v80
	v_add_f32_e32 v81, v87, v81
	s_nop 0
	v_add_f32_e32 v80, v102, v80
	v_add_f32_e32 v81, v103, v81
	s_nop 0
	v_add_f32_e32 v80, v88, v80
	v_add_f32_e32 v81, v89, v81
	s_nop 0
	v_add_f32_e32 v80, v104, v80
	v_add_f32_e32 v81, v105, v81
	v_mfma_f32_32x32x16_bf16 v[64:79], v[180:183], v[124:127], v[64:79]
	v_add_f32_e64 v90, v90, -v210
	v_add_f32_e64 v91, v91, -v210
	v_add_f32_e64 v106, v106, -v210
	v_add_f32_e64 v107, v107, -v210
	v_exp_f32_e32 v90, v90
	v_exp_f32_e32 v91, v91
	v_exp_f32_e32 v106, v106
	v_exp_f32_e32 v107, v107
	v_sub_f32_e32 v92, v92, v210
	v_sub_f32_e32 v93, v93, v210
	v_sub_f32_e32 v108, v108, v210
	v_sub_f32_e32 v109, v109, v210
	v_exp_f32_e32 v92, v92
	v_exp_f32_e32 v93, v93
	v_exp_f32_e32 v108, v108
	v_exp_f32_e32 v109, v109
	v_sub_f32_e32 v94, v94, v210
	v_sub_f32_e32 v95, v95, v210
	v_add_f32_e32 v80, v90, v80
	v_add_f32_e32 v81, v91, v81
	v_sub_f32_e32 v110, v110, v210
	v_sub_f32_e32 v111, v111, v210
	v_exp_f32_e32 v94, v94
	v_exp_f32_e32 v95, v95
	v_add_f32_e32 v80, v106, v80
	v_add_f32_e32 v81, v107, v81
	v_exp_f32_e32 v110, v110
	v_exp_f32_e32 v111, v111
	v_add_f32_e32 v80, v92, v80
	v_add_f32_e32 v81, v93, v81
	s_nop 0
	v_add_f32_e32 v80, v108, v80
	v_add_f32_e32 v81, v109, v81
	s_nop 0
	v_add_f32_e32 v80, v94, v80
	v_add_f32_e32 v81, v95, v81
	s_nop 0
	v_add_f32_e32 v80, v110, v80
	v_add_f32_e32 v81, v111, v81
	s_nop 0
	v_add_f32_e32 v80, v80, v81
	v_add_f32_e32 v236, v236, v80
	v_cvt_pk_bf16_f32 v80, v14, v15
	v_cvt_pk_bf16_f32 v81, v82, v83
	v_cvt_pk_bf16_f32 v82, v84, v85
	v_cvt_pk_bf16_f32 v83, v86, v87
	v_cvt_pk_bf16_f32 v84, v96, v97
	v_cvt_pk_bf16_f32 v85, v98, v99
	s_waitcnt lgkmcnt(2)
	v_mfma_f32_32x32x16_bf16 v[64:79], v[10:13], v[112:115], v[64:79]
	v_cvt_pk_bf16_f32 v86, v100, v101
	v_cvt_pk_bf16_f32 v87, v102, v103
	v_cvt_pk_bf16_f32 v88, v88, v89
	v_cvt_pk_bf16_f32 v89, v90, v91
	v_cvt_pk_bf16_f32 v90, v92, v93
	v_cvt_pk_bf16_f32 v91, v94, v95
	v_cvt_pk_bf16_f32 v92, v104, v105
	v_cvt_pk_bf16_f32 v93, v106, v107
	v_cvt_pk_bf16_f32 v94, v108, v109
	v_cvt_pk_bf16_f32 v95, v110, v111
	s_waitcnt lgkmcnt(0)
	v_mfma_f32_32x32x16_bf16 v[64:79], v[184:187], v[116:119], v[64:79]
	v_mfma_f32_32x32x16_bf16 v[48:63], v[188:191], v[80:83], v[48:63]
	v_mfma_f32_32x32x16_bf16 v[48:63], v[180:183], v[88:91], v[48:63]
	v_mfma_f32_32x32x16_bf16 v[48:63], v[10:13], v[84:87], v[48:63]
	v_mfma_f32_32x32x16_bf16 v[48:63], v[184:187], v[92:95], v[48:63]
	ds_read_b64_tr_b16 v[12:13], v0 offset:28864
	ds_read_b64_tr_b16 v[96:97], v0 offset:30016
	ds_read_b64_tr_b16 v[98:99], v0 offset:31168
	ds_read_b64_tr_b16 v[100:101], v0 offset:32320
	ds_read_b64_tr_b16 v[10:11], v0 offset:27712
	ds_read_b64_tr_b16 v[102:103], v0 offset:33472
	ds_read_b64_tr_b16 v[104:105], v0 offset:34624
	ds_read_b64_tr_b16 v[106:107], v0 offset:35776
	s_setprio 1
	s_waitcnt lgkmcnt(3)
	v_mfma_f32_32x32x16_bf16 v[32:47], v[10:13], v[120:123], v[32:47]
	v_mfma_f32_32x32x16_bf16 v[16:31], v[10:13], v[80:83], v[16:31]
	v_mfma_f32_32x32x16_bf16 v[32:47], v[96:99], v[124:127], v[32:47]
	v_mfma_f32_32x32x16_bf16 v[16:31], v[96:99], v[88:91], v[16:31]
	s_waitcnt lgkmcnt(2)
	v_mfma_f32_32x32x16_bf16 v[32:47], v[100:103], v[112:115], v[32:47]
	v_mfma_f32_32x32x16_bf16 v[16:31], v[100:103], v[84:87], v[16:31]
	s_waitcnt lgkmcnt(0)
	v_mfma_f32_32x32x16_bf16 v[32:47], v[104:107], v[116:119], v[32:47]
	v_mfma_f32_32x32x16_bf16 v[16:31], v[104:107], v[92:95], v[16:31]
	s_setprio 0

; DI unsigned pk2(float lo, float hi) { f32x2 v = {lo, hi}; bf16x2_t b = __builtin_convertvector(v, bf16x2_t); return __builtin_bit_cast(unsigned, b); }
; DI float fast_exp2(float x) { return __builtin_amdgcn_exp2f(x); }
; DI void att_sm_tail(f32x16 (&S)[2], bf16x8 (&pkm)[2][2], const float mrefm, float& lrunm) {
;     {
;         f32x16& s0 = S[0]; f32x16& s1 = S[1];
;         const f32x2 nm2 = {-mrefm, -mrefm};
;         f32x2 acc2 = {0.f, 0.f};
; #pragma unroll
;         for (int i = 0; i < 16; i += 2) {
;             f32x2 a = {s0[i], s0[i + 1]}, b = {s1[i], s1[i + 1]}; a += nm2; b += nm2;
;             a.x = fast_exp2(a.x); a.y = fast_exp2(a.y); b.x = fast_exp2(b.x); b.y = fast_exp2(b.y);
;             acc2 += a; acc2 += b; s0[i] = a.x; s0[i + 1] = a.y; s1[i] = b.x; s1[i + 1] = b.y;
;         }
;         lrunm += acc2.x + acc2.y;
; #pragma unroll
;         for (int s = 0; s < 2; ++s) {
;             u32x4 w0, w1;
;             w0.x = pk2(s0[8 * s + 0], s0[8 * s + 1]); w0.y = pk2(s0[8 * s + 2], s0[8 * s + 3]); w0.z = pk2(s0[8 * s + 4], s0[8 * s + 5]); w0.w = pk2(s0[8 * s + 6], s0[8 * s + 7]);
;             w1.x = pk2(s1[8 * s + 0], s1[8 * s + 1]); w1.y = pk2(s1[8 * s + 2], s1[8 * s + 3]); w1.z = pk2(s1[8 * s + 4], s1[8 * s + 5]); w1.w = pk2(s1[8 * s + 6], s1[8 * s + 7]);
;             pkm[0][s] = __builtin_bit_cast(bf16x8, w0); pkm[1][s] = __builtin_bit_cast(bf16x8, w1);
;         }
;     }
; }
.LBB0_591:
	v_sub_f32_e32 v14, v112, v212
	v_sub_f32_e32 v15, v113, v212
	v_sub_f32_e32 v112, v128, v212
	v_sub_f32_e32 v113, v129, v212
	v_exp_f32_e32 v14, v14
	v_exp_f32_e32 v15, v15
	v_exp_f32_e32 v112, v112
	v_exp_f32_e32 v113, v113
	v_sub_f32_e32 v114, v114, v212
	v_sub_f32_e32 v115, v115, v212
	v_sub_f32_e32 v128, v130, v212
	v_sub_f32_e32 v129, v131, v212
	v_exp_f32_e32 v114, v114
	v_exp_f32_e32 v115, v115
	v_exp_f32_e32 v128, v128
	v_exp_f32_e32 v129, v129
	v_sub_f32_e32 v116, v116, v212
	v_sub_f32_e32 v117, v117, v212
	v_add_f32_e32 v130, 0, v14
	v_add_f32_e32 v131, 0, v15
	v_sub_f32_e32 v132, v132, v212
	v_sub_f32_e32 v133, v133, v212
	v_exp_f32_e32 v116, v116
	v_exp_f32_e32 v117, v117
	v_add_f32_e32 v130, v112, v130
	v_add_f32_e32 v131, v113, v131
	v_exp_f32_e32 v132, v132
	v_exp_f32_e32 v133, v133
	v_sub_f32_e32 v118, v118, v212
	v_sub_f32_e32 v119, v119, v212
	v_add_f32_e32 v130, v114, v130
	v_add_f32_e32 v131, v115, v131
	v_sub_f32_e32 v134, v134, v212
	v_sub_f32_e32 v135, v135, v212
	v_exp_f32_e32 v118, v118
	v_exp_f32_e32 v119, v119
	v_add_f32_e32 v130, v128, v130
	v_add_f32_e32 v131, v129, v131
	v_exp_f32_e32 v134, v134
	v_exp_f32_e32 v135, v135
	v_sub_f32_e32 v120, v120, v212
	v_sub_f32_e32 v121, v121, v212
	v_add_f32_e32 v130, v116, v130
	v_add_f32_e32 v131, v117, v131
	v_sub_f32_e32 v136, v136, v212
	v_sub_f32_e32 v137, v137, v212
	v_exp_f32_e32 v246, v120
	v_exp_f32_e32 v247, v121
	v_add_f32_e32 v130, v132, v130
	v_add_f32_e32 v131, v133, v131
	v_exp_f32_e32 v136, v136
	v_exp_f32_e32 v137, v137
	v_sub_f32_e32 v120, v122, v212
	v_sub_f32_e32 v121, v123, v212
	v_add_f32_e32 v130, v118, v130
	v_add_f32_e32 v131, v119, v131
	v_sub_f32_e32 v122, v138, v212
	v_sub_f32_e32 v123, v139, v212
	v_exp_f32_e32 v138, v120
	v_exp_f32_e32 v139, v121
	v_add_f32_e32 v130, v134, v130
	v_add_f32_e32 v131, v135, v131
	v_exp_f32_e32 v248, v122
	v_exp_f32_e32 v249, v123
	v_sub_f32_e32 v122, v124, v212
	v_sub_f32_e32 v123, v125, v212
	v_add_f32_e32 v120, v246, v130
	v_add_f32_e32 v121, v247, v131
	v_sub_f32_e32 v124, v140, v212
	v_sub_f32_e32 v125, v141, v212
	v_exp_f32_e32 v130, v122
	v_exp_f32_e32 v131, v123
	v_add_f32_e32 v120, v136, v120
	v_add_f32_e32 v121, v137, v121
	v_exp_f32_e32 v140, v124
	v_exp_f32_e32 v141, v125
	v_sub_f32_e32 v122, v126, v212
	v_sub_f32_e32 v123, v127, v212
	v_add_f32_e32 v120, v138, v120
	v_add_f32_e32 v121, v139, v121
	v_sub_f32_e32 v124, v142, v212
	v_sub_f32_e32 v125, v143, v212
	v_exp_f32_e32 v142, v122
	v_exp_f32_e32 v143, v123
	v_add_f32_e32 v120, v248, v120
	v_add_f32_e32 v121, v249, v121
	v_exp_f32_e32 v250, v124
	v_exp_f32_e32 v251, v125
	v_add_f32_e32 v120, v130, v120
	v_add_f32_e32 v121, v131, v121
	v_cvt_pk_bf16_f32 v122, v116, v117
	v_add_f32_e32 v120, v140, v120
	v_add_f32_e32 v121, v141, v121
	v_cvt_pk_bf16_f32 v123, v118, v119
	v_add_f32_e32 v120, v142, v120
	v_add_f32_e32 v121, v143, v121
	v_cvt_pk_bf16_f32 v112, v112, v113
	v_add_f32_e32 v120, v250, v120
	v_add_f32_e32 v121, v251, v121
	v_cvt_pk_bf16_f32 v113, v128, v129
	v_add_f32_e32 v120, v120, v121
	v_add_f32_e32 v245, v245, v120
	v_cvt_pk_bf16_f32 v120, v14, v15
	v_cvt_pk_bf16_f32 v121, v114, v115
	v_cvt_pk_bf16_f32 v114, v132, v133
	v_cvt_pk_bf16_f32 v115, v134, v135
	v_cvt_pk_bf16_f32 v124, v246, v247
	v_cvt_pk_bf16_f32 v125, v138, v139
	v_cvt_pk_bf16_f32 v126, v130, v131
	v_cvt_pk_bf16_f32 v127, v142, v143
	v_cvt_pk_bf16_f32 v116, v136, v137
	v_cvt_pk_bf16_f32 v117, v248, v249
	v_cvt_pk_bf16_f32 v118, v140, v141
	v_cvt_pk_bf16_f32 v119, v250, v251
	s_waitcnt lgkmcnt(6)
; DI void att_sm_tail(f32x16 (&S)[2], bf16x8 (&pkm)[2][2], const float mrefm, float& lrunm) {
;     {
;         f32x16& s0 = S[0]; f32x16& s1 = S[1];
;         const f32x2 nm2 = {-mrefm, -mrefm};
;         f32x2 acc2 = {0.f, 0.f};
; #pragma unroll
;         for (int i = 0; i < 16; i += 2) {
;             f32x2 a = {s0[i], s0[i + 1]}, b = {s1[i], s1[i + 1]}; a += nm2; b += nm2;
;             a.x = fast_exp2(a.x); a.y = fast_exp2(a.y); b.x = fast_exp2(b.x); b.y = fast_exp2(b.y);
;             acc2 += a; acc2 += b; s0[i] = a.x; s0[i + 1] = a.y; s1[i] = b.x; s1[i + 1] = b.y;
;         }
;         lrunm += acc2.x + acc2.y;
; #pragma unroll
;         for (int s = 0; s < 2; ++s) {
;             u32x4 w0, w1;
;             w0.x = pk2(s0[8 * s + 0], s0[8 * s + 1]); w0.y = pk2(s0[8 * s + 2], s0[8 * s + 3]); w0.z = pk2(s0[8 * s + 4], s0[8 * s + 5]); w0.w = pk2(s0[8 * s + 6], s0[8 * s + 7]);
;             w1.x = pk2(s1[8 * s + 0], s1[8 * s + 1]); w1.y = pk2(s1[8 * s + 2], s1[8 * s + 3]); w1.z = pk2(s1[8 * s + 4], s1[8 * s + 5]); w1.w = pk2(s1[8 * s + 6], s1[8 * s + 7]);
;             pkm[0][s] = __builtin_bit_cast(bf16x8, w0); pkm[1][s] = __builtin_bit_cast(bf16x8, w1);
;         }
;     }
; }
; DI void att_pvmm1(const s16x4 (&lo)[4], const s16x4 (&hi)[4], const bf16x8 (&pkm)[2][2], f32x16& oe) {
; #pragma unroll
;     for (int q = 0; q < 4; ++q) { const bf16x8 vf = (bf16x8){lo[q][0], lo[q][1], lo[q][2], lo[q][3], hi[q][0], hi[q][1], hi[q][2], hi[q][3]};
;         oe = __builtin_amdgcn_mfma_f32_32x32x16_bf16(vf, pkm[q >> 1][q & 1], oe, 0, 0, 0); }
; }
; DI void att_vload(const LAS unsigned char* vb, int e, s16x4 (&lo)[4], s16x4 (&hi)[4]) {
;     constexpr int VP = 144;
; #pragma unroll
;     for (int q = 0; q < 4; ++q) { const LAS unsigned char* p = vb + (16 * q) * VP + 64 * e;
;         lo[q] = __builtin_bit_cast(s16x4, __builtin_amdgcn_ds_read_tr16_b64_v4i16((LAS s16x4*)p));
;         hi[q] = __builtin_bit_cast(s16x4, __builtin_amdgcn_ds_read_tr16_b64_v4i16((LAS s16x4*)(p + 8 * VP))); }
; }
; template <int NMAP>
; DI void att_pvmm(const s16x4 (&lo)[4], const s16x4 (&hi)[4], const bf16x8 (&pk)[NMAP][2][2], f32x16 (&o)[NMAP][2], int e) {
;     __builtin_amdgcn_s_setprio(1);
; #pragma unroll
;     for (int q = 0; q < 4; ++q) { const bf16x8 vf = (bf16x8){lo[q][0], lo[q][1], lo[q][2], lo[q][3], hi[q][0], hi[q][1], hi[q][2], hi[q][3]};
; #pragma unroll
	v_mfma_f32_32x32x16_bf16 v[64:79], v[188:191], v[120:123], v[64:79]
	v_add_f32_e64 v14, v80, -v210
	v_add_f32_e64 v15, v81, -v210
	v_add_f32_e64 v80, v96, -v210
	v_add_f32_e64 v81, v97, -v210
	v_exp_f32_e32 v14, v14
	v_exp_f32_e32 v15, v15
	v_exp_f32_e32 v96, v80
	v_exp_f32_e32 v97, v81
	v_sub_f32_e32 v82, v82, v210
	v_sub_f32_e32 v83, v83, v210
	v_sub_f32_e32 v98, v98, v210
	v_sub_f32_e32 v99, v99, v210
	v_exp_f32_e32 v82, v82
	v_exp_f32_e32 v83, v83
	v_exp_f32_e32 v98, v98
	v_exp_f32_e32 v99, v99
	v_sub_f32_e32 v84, v84, v210
	v_sub_f32_e32 v85, v85, v210
	v_add_f32_e32 v80, 0, v14
	v_add_f32_e32 v81, 0, v15
	v_sub_f32_e32 v100, v100, v210
	v_sub_f32_e32 v101, v101, v210
	v_exp_f32_e32 v84, v84
	v_exp_f32_e32 v85, v85
	v_add_f32_e32 v80, v96, v80
	v_add_f32_e32 v81, v97, v81
	v_exp_f32_e32 v100, v100
	v_exp_f32_e32 v101, v101
	v_sub_f32_e32 v86, v86, v210
	v_sub_f32_e32 v87, v87, v210
	v_add_f32_e32 v80, v82, v80
	v_add_f32_e32 v81, v83, v81
	v_sub_f32_e32 v102, v102, v210
	v_sub_f32_e32 v103, v103, v210
	v_exp_f32_e32 v86, v86
	v_exp_f32_e32 v87, v87
	v_add_f32_e32 v80, v98, v80
	v_add_f32_e32 v81, v99, v81
	v_exp_f32_e32 v102, v102
	v_exp_f32_e32 v103, v103
	v_sub_f32_e32 v88, v88, v210
	v_sub_f32_e32 v89, v89, v210
	v_add_f32_e32 v80, v84, v80
	v_add_f32_e32 v81, v85, v81
	v_sub_f32_e32 v104, v104, v210
	v_sub_f32_e32 v105, v105, v210
	v_exp_f32_e32 v88, v88
	v_exp_f32_e32 v89, v89
	v_add_f32_e32 v80, v100, v80
	v_add_f32_e32 v81, v101, v81
	v_exp_f32_e32 v104, v104
	v_exp_f32_e32 v105, v105
	v_add_f32_e32 v80, v86, v80
	v_add_f32_e32 v81, v87, v81
	s_nop 0
	v_add_f32_e32 v80, v102, v80
	v_add_f32_e32 v81, v103, v81
	s_nop 0
	v_add_f32_e32 v80, v88, v80
	v_add_f32_e32 v81, v89, v81
	s_nop 0
	v_add_f32_e32 v80, v104, v80
	v_add_f32_e32 v81, v105, v81
	s_waitcnt lgkmcnt(4)
	v_mfma_f32_32x32x16_bf16 v[64:79], v[184:187], v[124:127], v[64:79]
	v_add_f32_e64 v90, v90, -v210
	v_add_f32_e64 v91, v91, -v210
	v_add_f32_e64 v106, v106, -v210
	v_add_f32_e64 v107, v107, -v210
	v_exp_f32_e32 v90, v90
	v_exp_f32_e32 v91, v91
	v_exp_f32_e32 v106, v106
	v_exp_f32_e32 v107, v107
	v_sub_f32_e32 v92, v92, v210
	v_sub_f32_e32 v93, v93, v210
	v_sub_f32_e32 v108, v108, v210
	v_sub_f32_e32 v109, v109, v210
	v_exp_f32_e32 v92, v92
	v_exp_f32_e32 v93, v93
	v_exp_f32_e32 v108, v108
	v_exp_f32_e32 v109, v109
	v_sub_f32_e32 v94, v94, v210
	v_sub_f32_e32 v95, v95, v210
	v_add_f32_e32 v80, v90, v80
	v_add_f32_e32 v81, v91, v81
	v_sub_f32_e32 v110, v110, v210
	v_sub_f32_e32 v111, v111, v210
	v_exp_f32_e32 v94, v94
	v_exp_f32_e32 v95, v95
	v_add_f32_e32 v80, v106, v80
	v_add_f32_e32 v81, v107, v81
	v_exp_f32_e32 v110, v110
	v_exp_f32_e32 v111, v111
	v_add_f32_e32 v80, v92, v80
	v_add_f32_e32 v81, v93, v81
	s_nop 0
	v_add_f32_e32 v80, v108, v80
	v_add_f32_e32 v81, v109, v81
	s_nop 0
	v_add_f32_e32 v80, v94, v80
	v_add_f32_e32 v81, v95, v81
	s_nop 0
	v_add_f32_e32 v80, v110, v80
	v_add_f32_e32 v81, v111, v81
	s_nop 0
	v_add_f32_e32 v80, v80, v81
	v_add_f32_e32 v236, v236, v80
	v_cvt_pk_bf16_f32 v80, v14, v15
	v_cvt_pk_bf16_f32 v81, v82, v83
	v_cvt_pk_bf16_f32 v82, v84, v85
	v_cvt_pk_bf16_f32 v83, v86, v87
	v_cvt_pk_bf16_f32 v84, v96, v97
	v_cvt_pk_bf16_f32 v85, v98, v99
	s_waitcnt lgkmcnt(2)
	v_mfma_f32_32x32x16_bf16 v[64:79], v[180:183], v[112:115], v[64:79]
	v_cvt_pk_bf16_f32 v86, v100, v101
	v_cvt_pk_bf16_f32 v87, v102, v103
	v_cvt_pk_bf16_f32 v88, v88, v89
	v_cvt_pk_bf16_f32 v89, v90, v91
	v_cvt_pk_bf16_f32 v90, v92, v93
	v_cvt_pk_bf16_f32 v91, v94, v95
	v_cvt_pk_bf16_f32 v92, v104, v105
	v_cvt_pk_bf16_f32 v93, v106, v107
	v_cvt_pk_bf16_f32 v94, v108, v109
	v_cvt_pk_bf16_f32 v95, v110, v111
	s_waitcnt lgkmcnt(0)
	v_mfma_f32_32x32x16_bf16 v[64:79], v[10:13], v[116:119], v[64:79]
	v_mfma_f32_32x32x16_bf16 v[48:63], v[188:191], v[80:83], v[48:63]
	v_mfma_f32_32x32x16_bf16 v[48:63], v[184:187], v[88:91], v[48:63]
	v_mfma_f32_32x32x16_bf16 v[48:63], v[180:183], v[84:87], v[48:63]
	v_mfma_f32_32x32x16_bf16 v[48:63], v[10:13], v[92:95], v[48:63]
	ds_read_b64_tr_b16 v[10:11], v0 offset:36928
	ds_read_b64_tr_b16 v[12:13], v0 offset:38080
	ds_read_b64_tr_b16 v[96:97], v0 offset:39232
	ds_read_b64_tr_b16 v[98:99], v0 offset:40384
	ds_read_b64_tr_b16 v[100:101], v0 offset:41536
	ds_read_b64_tr_b16 v[102:103], v0 offset:42688
	ds_read_b64_tr_b16 v[104:105], v0 offset:43840
	ds_read_b64_tr_b16 v[106:107], v0 offset:44992
	s_setprio 1
	s_waitcnt lgkmcnt(6)
	v_mfma_f32_32x32x16_bf16 v[32:47], v[10:13], v[120:123], v[32:47]
	v_mfma_f32_32x32x16_bf16 v[16:31], v[10:13], v[80:83], v[16:31]
	s_waitcnt lgkmcnt(4)
	v_mfma_f32_32x32x16_bf16 v[32:47], v[96:99], v[124:127], v[32:47]
	v_mfma_f32_32x32x16_bf16 v[16:31], v[96:99], v[88:91], v[16:31]
	s_waitcnt lgkmcnt(2)
	v_mfma_f32_32x32x16_bf16 v[32:47], v[100:103], v[112:115], v[32:47]
	v_mfma_f32_32x32x16_bf16 v[16:31], v[100:103], v[84:87], v[16:31]
	s_waitcnt lgkmcnt(0)
	v_mfma_f32_32x32x16_bf16 v[32:47], v[104:107], v[116:119], v[32:47]
	v_mfma_f32_32x32x16_bf16 v[16:31], v[104:107], v[92:95], v[16:31]
	s_setprio 0

; #define LAS __attribute__((address_space(3)))
; DI unsigned pk2(float lo, float hi) { f32x2 v = {lo, hi}; bf16x2_t b = __builtin_convertvector(v, bf16x2_t); return __builtin_bit_cast(unsigned, b); }
; DI void att_sm_tail(f32x16 (&S)[2], bf16x8 (&pkm)[2][2], const float mrefm, float& lrunm) {
;     {
;         f32x16& s0 = S[0]; f32x16& s1 = S[1];
;         const f32x2 nm2 = {-mrefm, -mrefm};
;         f32x2 acc2 = {0.f, 0.f};
; #pragma unroll
;         for (int i = 0; i < 16; i += 2) {
;             f32x2 a = {s0[i], s0[i + 1]}, b = {s1[i], s1[i + 1]}; a += nm2; b += nm2;
;             a.x = fast_exp2(a.x); a.y = fast_exp2(a.y); b.x = fast_exp2(b.x); b.y = fast_exp2(b.y);
;             acc2 += a; acc2 += b; s0[i] = a.x; s0[i + 1] = a.y; s1[i] = b.x; s1[i + 1] = b.y;
;         }
;         lrunm += acc2.x + acc2.y;
; #pragma unroll
;         for (int s = 0; s < 2; ++s) {
;             u32x4 w0, w1;
;             w0.x = pk2(s0[8 * s + 0], s0[8 * s + 1]); w0.y = pk2(s0[8 * s + 2], s0[8 * s + 3]); w0.z = pk2(s0[8 * s + 4], s0[8 * s + 5]); w0.w = pk2(s0[8 * s + 6], s0[8 * s + 7]);
;             w1.x = pk2(s1[8 * s + 0], s1[8 * s + 1]); w1.y = pk2(s1[8 * s + 2], s1[8 * s + 3]); w1.z = pk2(s1[8 * s + 4], s1[8 * s + 5]); w1.w = pk2(s1[8 * s + 6], s1[8 * s + 7]);
;             pkm[0][s] = __builtin_bit_cast(bf16x8, w0); pkm[1][s] = __builtin_bit_cast(bf16x8, w1);
;         }
;     }
; }
; DI void att_vload(const LAS unsigned char* vb, int e, s16x4 (&lo)[4], s16x4 (&hi)[4]) {
;     constexpr int VP = 144;
; #pragma unroll
;     for (int q = 0; q < 4; ++q) { const LAS unsigned char* p = vb + (16 * q) * VP + 64 * e;
;         lo[q] = __builtin_bit_cast(s16x4, __builtin_amdgcn_ds_read_tr16_b64_v4i16((LAS s16x4*)p));
;         hi[q] = __builtin_bit_cast(s16x4, __builtin_amdgcn_ds_read_tr16_b64_v4i16((LAS s16x4*)(p + 8 * VP))); }
; }
; template <int NMAP>
; DI void att_pvmm(const s16x4 (&lo)[4], const s16x4 (&hi)[4], const bf16x8 (&pk)[NMAP][2][2], f32x16 (&o)[NMAP][2], int e) {
;     __builtin_amdgcn_s_setprio(1);
; #pragma unroll
;     for (int q = 0; q < 4; ++q) { const bf16x8 vf = (bf16x8){lo[q][0], lo[q][1], lo[q][2], lo[q][3], hi[q][0], hi[q][1], hi[q][2], hi[q][3]};
; #pragma unroll
;         for (int mp = 0; mp < NMAP; ++mp) o[mp][e] = __builtin_amdgcn_mfma_f32_32x32x16_bf16(vf, pk[mp][q >> 1][q & 1], o[mp][e], 0, 0, 0); }
;     __builtin_amdgcn_s_setprio(0);
; }
.LBB0_614:
	v_sub_f32_e32 v14, v48, v136
	v_sub_f32_e32 v15, v49, v136
	v_sub_f32_e32 v48, v64, v136
	v_sub_f32_e32 v49, v65, v136
	v_exp_f32_e32 v14, v14
	v_exp_f32_e32 v15, v15
	v_exp_f32_e32 v64, v48
	v_exp_f32_e32 v65, v49
	v_sub_f32_e32 v48, v50, v136
	v_sub_f32_e32 v49, v51, v136
	v_sub_f32_e32 v50, v66, v136
	v_sub_f32_e32 v51, v67, v136
	v_exp_f32_e32 v66, v48
	v_exp_f32_e32 v67, v49
	v_exp_f32_e32 v152, v50
	v_exp_f32_e32 v153, v51
	v_sub_f32_e32 v50, v52, v136
	v_sub_f32_e32 v51, v53, v136
	v_add_f32_e32 v48, 0, v14
	v_add_f32_e32 v49, 0, v15
	v_sub_f32_e32 v52, v68, v136
	v_sub_f32_e32 v53, v69, v136
	v_exp_f32_e32 v50, v50
	v_exp_f32_e32 v51, v51
	v_add_f32_e32 v48, v64, v48
	v_add_f32_e32 v49, v65, v49
	v_exp_f32_e32 v68, v52
	v_exp_f32_e32 v69, v53
	v_sub_f32_e32 v52, v54, v136
	v_sub_f32_e32 v53, v55, v136
	v_add_f32_e32 v48, v66, v48
	v_add_f32_e32 v49, v67, v49
	v_sub_f32_e32 v54, v70, v136
	v_sub_f32_e32 v55, v71, v136
	v_exp_f32_e32 v52, v52
	v_exp_f32_e32 v53, v53
	v_add_f32_e32 v48, v152, v48
	v_add_f32_e32 v49, v153, v49
	v_exp_f32_e32 v70, v54
	v_exp_f32_e32 v71, v55
	v_sub_f32_e32 v54, v56, v136
	v_sub_f32_e32 v55, v57, v136
	v_add_f32_e32 v48, v50, v48
	v_add_f32_e32 v49, v51, v49
	v_sub_f32_e32 v56, v72, v136
	v_sub_f32_e32 v57, v73, v136
	v_exp_f32_e32 v72, v54
	v_exp_f32_e32 v73, v55
	v_add_f32_e32 v48, v68, v48
	v_add_f32_e32 v49, v69, v49
	v_exp_f32_e32 v154, v56
	v_exp_f32_e32 v155, v57
	v_sub_f32_e32 v54, v58, v136
	v_sub_f32_e32 v55, v59, v136
	v_add_f32_e32 v48, v52, v48
	v_add_f32_e32 v49, v53, v49
	v_sub_f32_e32 v56, v74, v136
	v_sub_f32_e32 v57, v75, v136
	v_exp_f32_e32 v58, v54
	v_exp_f32_e32 v59, v55
	v_add_f32_e32 v48, v70, v48
	v_add_f32_e32 v49, v71, v49
	v_exp_f32_e32 v74, v56
	v_exp_f32_e32 v75, v57
	v_sub_f32_e32 v54, v60, v136
	v_sub_f32_e32 v55, v61, v136
	v_add_f32_e32 v48, v72, v48
	v_add_f32_e32 v49, v73, v49
	v_sub_f32_e32 v56, v76, v136
	v_sub_f32_e32 v57, v77, v136
	v_exp_f32_e32 v60, v54
	v_exp_f32_e32 v61, v55
	v_add_f32_e32 v48, v154, v48
	v_add_f32_e32 v49, v155, v49
	v_exp_f32_e32 v76, v56
	v_exp_f32_e32 v77, v57
	v_sub_f32_e32 v54, v62, v136
	v_sub_f32_e32 v55, v63, v136
	v_add_f32_e32 v48, v58, v48
	v_add_f32_e32 v49, v59, v49
	v_sub_f32_e32 v56, v78, v136
	v_sub_f32_e32 v57, v79, v136
	v_exp_f32_e32 v62, v54
	v_exp_f32_e32 v63, v55
	v_add_f32_e32 v48, v74, v48
	v_add_f32_e32 v49, v75, v49
	v_exp_f32_e32 v78, v56
	v_exp_f32_e32 v79, v57
	v_add_f32_e32 v48, v60, v48
	v_add_f32_e32 v49, v61, v49
	v_cvt_pk_bf16_f32 v50, v50, v51
	v_add_f32_e32 v48, v76, v48
	v_add_f32_e32 v49, v77, v49
	v_cvt_pk_bf16_f32 v51, v52, v53
	v_add_f32_e32 v48, v62, v48
	v_add_f32_e32 v49, v63, v49
	v_cvt_pk_bf16_f32 v52, v64, v65
	v_add_f32_e32 v48, v78, v48
	v_add_f32_e32 v49, v79, v49
	v_cvt_pk_bf16_f32 v53, v152, v153
	v_add_f32_e32 v48, v48, v49
	v_add_f32_e32 v131, v131, v48
	v_cvt_pk_bf16_f32 v48, v14, v15
	v_cvt_pk_bf16_f32 v49, v66, v67
	v_cvt_pk_bf16_f32 v54, v68, v69
	v_cvt_pk_bf16_f32 v55, v70, v71
	v_cvt_pk_bf16_f32 v56, v72, v73
	v_cvt_pk_bf16_f32 v57, v58, v59
	v_cvt_pk_bf16_f32 v58, v60, v61
	v_cvt_pk_bf16_f32 v59, v62, v63
	v_cvt_pk_bf16_f32 v60, v154, v155
	v_cvt_pk_bf16_f32 v61, v74, v75
	v_cvt_pk_bf16_f32 v62, v76, v77
	v_cvt_pk_bf16_f32 v63, v78, v79
	s_setprio 1
	s_waitcnt lgkmcnt(6)
	v_mfma_f32_32x32x16_bf16 v[32:47], v[120:123], v[48:51], v[32:47]
	s_waitcnt lgkmcnt(4)
	v_mfma_f32_32x32x16_bf16 v[32:47], v[116:119], v[56:59], v[32:47]
	s_waitcnt lgkmcnt(2)
	v_mfma_f32_32x32x16_bf16 v[32:47], v[112:115], v[52:55], v[32:47]
	s_waitcnt lgkmcnt(0)
	v_mfma_f32_32x32x16_bf16 v[32:47], v[10:13], v[60:63], v[32:47]
	s_setprio 0
	ds_read_b64_tr_b16 v[10:11], v0 offset:18496
	ds_read_b64_tr_b16 v[12:13], v0 offset:19648
	ds_read_b64_tr_b16 v[64:65], v0 offset:20800
	ds_read_b64_tr_b16 v[66:67], v0 offset:21952
	ds_read_b64_tr_b16 v[68:69], v0 offset:23104
	ds_read_b64_tr_b16 v[70:71], v0 offset:24256
	ds_read_b64_tr_b16 v[72:73], v0 offset:25408
	ds_read_b64_tr_b16 v[74:75], v0 offset:26560
	s_setprio 1
	s_waitcnt lgkmcnt(6)
	v_mfma_f32_32x32x16_bf16 v[16:31], v[10:13], v[48:51], v[16:31]
	s_waitcnt lgkmcnt(4)
	v_mfma_f32_32x32x16_bf16 v[16:31], v[64:67], v[56:59], v[16:31]
	s_waitcnt lgkmcnt(2)
	v_mfma_f32_32x32x16_bf16 v[16:31], v[68:71], v[52:55], v[16:31]
	s_waitcnt lgkmcnt(0)
	v_mfma_f32_32x32x16_bf16 v[16:31], v[72:75], v[60:63], v[16:31]
	s_setprio 0

; #define LAS __attribute__((address_space(3)))
; DI unsigned pk2(float lo, float hi) { f32x2 v = {lo, hi}; bf16x2_t b = __builtin_convertvector(v, bf16x2_t); return __builtin_bit_cast(unsigned, b); }
; DI void att_sm_tail(f32x16 (&S)[2], bf16x8 (&pkm)[2][2], const float mrefm, float& lrunm) {
;     {
;         f32x16& s0 = S[0]; f32x16& s1 = S[1];
;         const f32x2 nm2 = {-mrefm, -mrefm};
;         f32x2 acc2 = {0.f, 0.f};
; #pragma unroll
;         for (int i = 0; i < 16; i += 2) {
;             f32x2 a = {s0[i], s0[i + 1]}, b = {s1[i], s1[i + 1]}; a += nm2; b += nm2;
;             a.x = fast_exp2(a.x); a.y = fast_exp2(a.y); b.x = fast_exp2(b.x); b.y = fast_exp2(b.y);
;             acc2 += a; acc2 += b; s0[i] = a.x; s0[i + 1] = a.y; s1[i] = b.x; s1[i + 1] = b.y;
;         }
;         lrunm += acc2.x + acc2.y;
; #pragma unroll
;         for (int s = 0; s < 2; ++s) {
;             u32x4 w0, w1;
;             w0.x = pk2(s0[8 * s + 0], s0[8 * s + 1]); w0.y = pk2(s0[8 * s + 2], s0[8 * s + 3]); w0.z = pk2(s0[8 * s + 4], s0[8 * s + 5]); w0.w = pk2(s0[8 * s + 6], s0[8 * s + 7]);
;             w1.x = pk2(s1[8 * s + 0], s1[8 * s + 1]); w1.y = pk2(s1[8 * s + 2], s1[8 * s + 3]); w1.z = pk2(s1[8 * s + 4], s1[8 * s + 5]); w1.w = pk2(s1[8 * s + 6], s1[8 * s + 7]);
;             pkm[0][s] = __builtin_bit_cast(bf16x8, w0); pkm[1][s] = __builtin_bit_cast(bf16x8, w1);
;         }
;     }
; }
; DI void att_vload(const LAS unsigned char* vb, int e, s16x4 (&lo)[4], s16x4 (&hi)[4]) {
;     constexpr int VP = 144;
; #pragma unroll
;     for (int q = 0; q < 4; ++q) { const LAS unsigned char* p = vb + (16 * q) * VP + 64 * e;
;         lo[q] = __builtin_bit_cast(s16x4, __builtin_amdgcn_ds_read_tr16_b64_v4i16((LAS s16x4*)p));
;         hi[q] = __builtin_bit_cast(s16x4, __builtin_amdgcn_ds_read_tr16_b64_v4i16((LAS s16x4*)(p + 8 * VP))); }
; }
; template <int NMAP>
; DI void att_pvmm(const s16x4 (&lo)[4], const s16x4 (&hi)[4], const bf16x8 (&pk)[NMAP][2][2], f32x16 (&o)[NMAP][2], int e) {
;     __builtin_amdgcn_s_setprio(1);
; #pragma unroll
;     for (int q = 0; q < 4; ++q) { const bf16x8 vf = (bf16x8){lo[q][0], lo[q][1], lo[q][2], lo[q][3], hi[q][0], hi[q][1], hi[q][2], hi[q][3]};
; #pragma unroll
;         for (int mp = 0; mp < NMAP; ++mp) o[mp][e] = __builtin_amdgcn_mfma_f32_32x32x16_bf16(vf, pk[mp][q >> 1][q & 1], o[mp][e], 0, 0, 0); }
;     __builtin_amdgcn_s_setprio(0);
; }
.LBB0_625:
	v_sub_f32_e32 v14, v48, v136
	v_sub_f32_e32 v15, v49, v136
	v_sub_f32_e32 v48, v64, v136
	v_sub_f32_e32 v49, v65, v136
	v_exp_f32_e32 v14, v14
	v_exp_f32_e32 v15, v15
	v_exp_f32_e32 v64, v48
	v_exp_f32_e32 v65, v49
	v_sub_f32_e32 v48, v50, v136
	v_sub_f32_e32 v49, v51, v136
	v_sub_f32_e32 v50, v66, v136
	v_sub_f32_e32 v51, v67, v136
	v_exp_f32_e32 v66, v48
	v_exp_f32_e32 v67, v49
	v_exp_f32_e32 v152, v50
	v_exp_f32_e32 v153, v51
	v_sub_f32_e32 v50, v52, v136
	v_sub_f32_e32 v51, v53, v136
	v_add_f32_e32 v48, 0, v14
	v_add_f32_e32 v49, 0, v15
	v_sub_f32_e32 v52, v68, v136
	v_sub_f32_e32 v53, v69, v136
	v_exp_f32_e32 v50, v50
	v_exp_f32_e32 v51, v51
	v_add_f32_e32 v48, v64, v48
	v_add_f32_e32 v49, v65, v49
	v_exp_f32_e32 v68, v52
	v_exp_f32_e32 v69, v53
	v_sub_f32_e32 v52, v54, v136
	v_sub_f32_e32 v53, v55, v136
	v_add_f32_e32 v48, v66, v48
	v_add_f32_e32 v49, v67, v49
	v_sub_f32_e32 v54, v70, v136
	v_sub_f32_e32 v55, v71, v136
	v_exp_f32_e32 v52, v52
	v_exp_f32_e32 v53, v53
	v_add_f32_e32 v48, v152, v48
	v_add_f32_e32 v49, v153, v49
	v_exp_f32_e32 v70, v54
	v_exp_f32_e32 v71, v55
	v_sub_f32_e32 v54, v56, v136
	v_sub_f32_e32 v55, v57, v136
	v_add_f32_e32 v48, v50, v48
	v_add_f32_e32 v49, v51, v49
	v_sub_f32_e32 v56, v72, v136
	v_sub_f32_e32 v57, v73, v136
	v_exp_f32_e32 v72, v54
	v_exp_f32_e32 v73, v55
	v_add_f32_e32 v48, v68, v48
	v_add_f32_e32 v49, v69, v49
	v_exp_f32_e32 v154, v56
	v_exp_f32_e32 v155, v57
	v_sub_f32_e32 v54, v58, v136
	v_sub_f32_e32 v55, v59, v136
	v_add_f32_e32 v48, v52, v48
	v_add_f32_e32 v49, v53, v49
	v_sub_f32_e32 v56, v74, v136
	v_sub_f32_e32 v57, v75, v136
	v_exp_f32_e32 v58, v54
	v_exp_f32_e32 v59, v55
	v_add_f32_e32 v48, v70, v48
	v_add_f32_e32 v49, v71, v49
	v_exp_f32_e32 v74, v56
	v_exp_f32_e32 v75, v57
	v_sub_f32_e32 v54, v60, v136
	v_sub_f32_e32 v55, v61, v136
	v_add_f32_e32 v48, v72, v48
	v_add_f32_e32 v49, v73, v49
	v_sub_f32_e32 v56, v76, v136
	v_sub_f32_e32 v57, v77, v136
	v_exp_f32_e32 v60, v54
	v_exp_f32_e32 v61, v55
	v_add_f32_e32 v48, v154, v48
	v_add_f32_e32 v49, v155, v49
	v_exp_f32_e32 v76, v56
	v_exp_f32_e32 v77, v57
	v_sub_f32_e32 v54, v62, v136
	v_sub_f32_e32 v55, v63, v136
	v_add_f32_e32 v48, v58, v48
	v_add_f32_e32 v49, v59, v49
	v_sub_f32_e32 v56, v78, v136
	v_sub_f32_e32 v57, v79, v136
	v_exp_f32_e32 v62, v54
	v_exp_f32_e32 v63, v55
	v_add_f32_e32 v48, v74, v48
	v_add_f32_e32 v49, v75, v49
	v_exp_f32_e32 v78, v56
	v_exp_f32_e32 v79, v57
	v_add_f32_e32 v48, v60, v48
	v_add_f32_e32 v49, v61, v49
	v_cvt_pk_bf16_f32 v50, v50, v51
	v_add_f32_e32 v48, v76, v48
	v_add_f32_e32 v49, v77, v49
	v_cvt_pk_bf16_f32 v51, v52, v53
	v_add_f32_e32 v48, v62, v48
	v_add_f32_e32 v49, v63, v49
	v_cvt_pk_bf16_f32 v52, v64, v65
	v_add_f32_e32 v48, v78, v48
	v_add_f32_e32 v49, v79, v49
	v_cvt_pk_bf16_f32 v53, v152, v153
	v_add_f32_e32 v48, v48, v49
	v_add_f32_e32 v131, v131, v48
	v_cvt_pk_bf16_f32 v48, v14, v15
	v_cvt_pk_bf16_f32 v49, v66, v67
	v_cvt_pk_bf16_f32 v54, v68, v69
	v_cvt_pk_bf16_f32 v55, v70, v71
	v_cvt_pk_bf16_f32 v56, v72, v73
	v_cvt_pk_bf16_f32 v57, v58, v59
	v_cvt_pk_bf16_f32 v58, v60, v61
	v_cvt_pk_bf16_f32 v59, v62, v63
	v_cvt_pk_bf16_f32 v60, v154, v155
	v_cvt_pk_bf16_f32 v61, v74, v75
	v_cvt_pk_bf16_f32 v62, v76, v77
	v_cvt_pk_bf16_f32 v63, v78, v79
	s_setprio 1
	s_waitcnt lgkmcnt(3)
	v_mfma_f32_32x32x16_bf16 v[32:47], v[120:123], v[48:51], v[32:47]
	v_mfma_f32_32x32x16_bf16 v[32:47], v[116:119], v[56:59], v[32:47]
	s_waitcnt lgkmcnt(2)
	v_mfma_f32_32x32x16_bf16 v[32:47], v[112:115], v[52:55], v[32:47]
	s_waitcnt lgkmcnt(0)
	v_mfma_f32_32x32x16_bf16 v[32:47], v[10:13], v[60:63], v[32:47]
	s_setprio 0
	ds_read_b64_tr_b16 v[12:13], v0 offset:28864
	ds_read_b64_tr_b16 v[64:65], v0 offset:30016
	ds_read_b64_tr_b16 v[66:67], v0 offset:31168
	ds_read_b64_tr_b16 v[68:69], v0 offset:32320
	ds_read_b64_tr_b16 v[10:11], v0 offset:27712
	ds_read_b64_tr_b16 v[70:71], v0 offset:33472
	ds_read_b64_tr_b16 v[72:73], v0 offset:34624
	ds_read_b64_tr_b16 v[74:75], v0 offset:35776
	s_setprio 1
	s_waitcnt lgkmcnt(3)
	v_mfma_f32_32x32x16_bf16 v[16:31], v[10:13], v[48:51], v[16:31]
	v_mfma_f32_32x32x16_bf16 v[16:31], v[64:67], v[56:59], v[16:31]
	s_waitcnt lgkmcnt(2)
	v_mfma_f32_32x32x16_bf16 v[16:31], v[68:71], v[52:55], v[16:31]
	s_waitcnt lgkmcnt(0)
	v_mfma_f32_32x32x16_bf16 v[16:31], v[72:75], v[60:63], v[16:31]
	s_setprio 0

; #define LAS __attribute__((address_space(3)))
; DI unsigned pk2(float lo, float hi) { f32x2 v = {lo, hi}; bf16x2_t b = __builtin_convertvector(v, bf16x2_t); return __builtin_bit_cast(unsigned, b); }
; DI void att_sm_tail(f32x16 (&S)[2], bf16x8 (&pkm)[2][2], const float mrefm, float& lrunm) {
;     {
;         f32x16& s0 = S[0]; f32x16& s1 = S[1];
;         const f32x2 nm2 = {-mrefm, -mrefm};
;         f32x2 acc2 = {0.f, 0.f};
; #pragma unroll
;         for (int i = 0; i < 16; i += 2) {
;             f32x2 a = {s0[i], s0[i + 1]}, b = {s1[i], s1[i + 1]}; a += nm2; b += nm2;
;             a.x = fast_exp2(a.x); a.y = fast_exp2(a.y); b.x = fast_exp2(b.x); b.y = fast_exp2(b.y);
;             acc2 += a; acc2 += b; s0[i] = a.x; s0[i + 1] = a.y; s1[i] = b.x; s1[i + 1] = b.y;
;         }
;         lrunm += acc2.x + acc2.y;
; #pragma unroll
;         for (int s = 0; s < 2; ++s) {
;             u32x4 w0, w1;
;             w0.x = pk2(s0[8 * s + 0], s0[8 * s + 1]); w0.y = pk2(s0[8 * s + 2], s0[8 * s + 3]); w0.z = pk2(s0[8 * s + 4], s0[8 * s + 5]); w0.w = pk2(s0[8 * s + 6], s0[8 * s + 7]);
;             w1.x = pk2(s1[8 * s + 0], s1[8 * s + 1]); w1.y = pk2(s1[8 * s + 2], s1[8 * s + 3]); w1.z = pk2(s1[8 * s + 4], s1[8 * s + 5]); w1.w = pk2(s1[8 * s + 6], s1[8 * s + 7]);
;             pkm[0][s] = __builtin_bit_cast(bf16x8, w0); pkm[1][s] = __builtin_bit_cast(bf16x8, w1);
;         }
;     }
; }
; DI void att_vload(const LAS unsigned char* vb, int e, s16x4 (&lo)[4], s16x4 (&hi)[4]) {
;     constexpr int VP = 144;
; #pragma unroll
;     for (int q = 0; q < 4; ++q) { const LAS unsigned char* p = vb + (16 * q) * VP + 64 * e;
;         lo[q] = __builtin_bit_cast(s16x4, __builtin_amdgcn_ds_read_tr16_b64_v4i16((LAS s16x4*)p));
;         hi[q] = __builtin_bit_cast(s16x4, __builtin_amdgcn_ds_read_tr16_b64_v4i16((LAS s16x4*)(p + 8 * VP))); }
; }
; template <int NMAP>
; DI void att_pvmm(const s16x4 (&lo)[4], const s16x4 (&hi)[4], const bf16x8 (&pk)[NMAP][2][2], f32x16 (&o)[NMAP][2], int e) {
;     __builtin_amdgcn_s_setprio(1);
; #pragma unroll
;     for (int q = 0; q < 4; ++q) { const bf16x8 vf = (bf16x8){lo[q][0], lo[q][1], lo[q][2], lo[q][3], hi[q][0], hi[q][1], hi[q][2], hi[q][3]};
; #pragma unroll
;         for (int mp = 0; mp < NMAP; ++mp) o[mp][e] = __builtin_amdgcn_mfma_f32_32x32x16_bf16(vf, pk[mp][q >> 1][q & 1], o[mp][e], 0, 0, 0); }
;     __builtin_amdgcn_s_setprio(0);
; }
.LBB0_636:
	v_sub_f32_e32 v14, v48, v136
	v_sub_f32_e32 v15, v49, v136
	v_sub_f32_e32 v48, v64, v136
	v_sub_f32_e32 v49, v65, v136
	v_exp_f32_e32 v14, v14
	v_exp_f32_e32 v15, v15
	v_exp_f32_e32 v64, v48
	v_exp_f32_e32 v65, v49
	v_sub_f32_e32 v48, v50, v136
	v_sub_f32_e32 v49, v51, v136
	v_sub_f32_e32 v50, v66, v136
	v_sub_f32_e32 v51, v67, v136
	v_exp_f32_e32 v66, v48
	v_exp_f32_e32 v67, v49
	v_exp_f32_e32 v152, v50
	v_exp_f32_e32 v153, v51
	v_sub_f32_e32 v50, v52, v136
	v_sub_f32_e32 v51, v53, v136
	v_add_f32_e32 v48, 0, v14
	v_add_f32_e32 v49, 0, v15
	v_sub_f32_e32 v52, v68, v136
	v_sub_f32_e32 v53, v69, v136
	v_exp_f32_e32 v50, v50
	v_exp_f32_e32 v51, v51
	v_add_f32_e32 v48, v64, v48
	v_add_f32_e32 v49, v65, v49
	v_exp_f32_e32 v68, v52
	v_exp_f32_e32 v69, v53
	v_sub_f32_e32 v52, v54, v136
	v_sub_f32_e32 v53, v55, v136
	v_add_f32_e32 v48, v66, v48
	v_add_f32_e32 v49, v67, v49
	v_sub_f32_e32 v54, v70, v136
	v_sub_f32_e32 v55, v71, v136
	v_exp_f32_e32 v52, v52
	v_exp_f32_e32 v53, v53
	v_add_f32_e32 v48, v152, v48
	v_add_f32_e32 v49, v153, v49
	v_exp_f32_e32 v70, v54
	v_exp_f32_e32 v71, v55
	v_sub_f32_e32 v54, v56, v136
	v_sub_f32_e32 v55, v57, v136
	v_add_f32_e32 v48, v50, v48
	v_add_f32_e32 v49, v51, v49
	v_sub_f32_e32 v56, v72, v136
	v_sub_f32_e32 v57, v73, v136
	v_exp_f32_e32 v72, v54
	v_exp_f32_e32 v73, v55
	v_add_f32_e32 v48, v68, v48
	v_add_f32_e32 v49, v69, v49
	v_exp_f32_e32 v154, v56
	v_exp_f32_e32 v155, v57
	v_sub_f32_e32 v54, v58, v136
	v_sub_f32_e32 v55, v59, v136
	v_add_f32_e32 v48, v52, v48
	v_add_f32_e32 v49, v53, v49
	v_sub_f32_e32 v56, v74, v136
	v_sub_f32_e32 v57, v75, v136
	v_exp_f32_e32 v58, v54
	v_exp_f32_e32 v59, v55
	v_add_f32_e32 v48, v70, v48
	v_add_f32_e32 v49, v71, v49
	v_exp_f32_e32 v74, v56
	v_exp_f32_e32 v75, v57
	v_sub_f32_e32 v54, v60, v136
	v_sub_f32_e32 v55, v61, v136
	v_add_f32_e32 v48, v72, v48
	v_add_f32_e32 v49, v73, v49
	v_sub_f32_e32 v56, v76, v136
	v_sub_f32_e32 v57, v77, v136
	v_exp_f32_e32 v60, v54
	v_exp_f32_e32 v61, v55
	v_add_f32_e32 v48, v154, v48
	v_add_f32_e32 v49, v155, v49
	v_exp_f32_e32 v76, v56
	v_exp_f32_e32 v77, v57
	v_sub_f32_e32 v54, v62, v136
	v_sub_f32_e32 v55, v63, v136
	v_add_f32_e32 v48, v58, v48
	v_add_f32_e32 v49, v59, v49
	v_sub_f32_e32 v56, v78, v136
	v_sub_f32_e32 v57, v79, v136
	v_exp_f32_e32 v62, v54
	v_exp_f32_e32 v63, v55
	v_add_f32_e32 v48, v74, v48
	v_add_f32_e32 v49, v75, v49
	v_exp_f32_e32 v78, v56
	v_exp_f32_e32 v79, v57
	v_add_f32_e32 v48, v60, v48
	v_add_f32_e32 v49, v61, v49
	v_cvt_pk_bf16_f32 v50, v50, v51
	v_add_f32_e32 v48, v76, v48
	v_add_f32_e32 v49, v77, v49
	v_cvt_pk_bf16_f32 v51, v52, v53
	v_add_f32_e32 v48, v62, v48
	v_add_f32_e32 v49, v63, v49
	v_cvt_pk_bf16_f32 v52, v64, v65
	v_add_f32_e32 v48, v78, v48
	v_add_f32_e32 v49, v79, v49
	v_cvt_pk_bf16_f32 v53, v152, v153
	v_add_f32_e32 v48, v48, v49
	v_add_f32_e32 v131, v131, v48
	v_cvt_pk_bf16_f32 v48, v14, v15
	v_cvt_pk_bf16_f32 v49, v66, v67
	v_cvt_pk_bf16_f32 v54, v68, v69
	v_cvt_pk_bf16_f32 v55, v70, v71
	v_cvt_pk_bf16_f32 v56, v72, v73
	v_cvt_pk_bf16_f32 v57, v58, v59
	v_cvt_pk_bf16_f32 v58, v60, v61
	v_cvt_pk_bf16_f32 v59, v62, v63
	v_cvt_pk_bf16_f32 v60, v154, v155
	v_cvt_pk_bf16_f32 v61, v74, v75
	v_cvt_pk_bf16_f32 v62, v76, v77
	v_cvt_pk_bf16_f32 v63, v78, v79
	s_setprio 1
	s_waitcnt lgkmcnt(6)
	v_mfma_f32_32x32x16_bf16 v[32:47], v[120:123], v[48:51], v[32:47]
	s_waitcnt lgkmcnt(4)
	v_mfma_f32_32x32x16_bf16 v[32:47], v[116:119], v[56:59], v[32:47]
	s_waitcnt lgkmcnt(2)
	v_mfma_f32_32x32x16_bf16 v[32:47], v[112:115], v[52:55], v[32:47]
	s_waitcnt lgkmcnt(0)
	v_mfma_f32_32x32x16_bf16 v[32:47], v[10:13], v[60:63], v[32:47]
	s_setprio 0
	ds_read_b64_tr_b16 v[10:11], v0 offset:36928
	ds_read_b64_tr_b16 v[12:13], v0 offset:38080
	ds_read_b64_tr_b16 v[64:65], v0 offset:39232
	ds_read_b64_tr_b16 v[66:67], v0 offset:40384
	ds_read_b64_tr_b16 v[68:69], v0 offset:41536
	ds_read_b64_tr_b16 v[70:71], v0 offset:42688
	ds_read_b64_tr_b16 v[72:73], v0 offset:43840
	ds_read_b64_tr_b16 v[74:75], v0 offset:44992
	s_setprio 1
	s_waitcnt lgkmcnt(6)
	v_mfma_f32_32x32x16_bf16 v[16:31], v[10:13], v[48:51], v[16:31]
	s_waitcnt lgkmcnt(4)
	v_mfma_f32_32x32x16_bf16 v[16:31], v[64:67], v[56:59], v[16:31]
	s_waitcnt lgkmcnt(2)
	v_mfma_f32_32x32x16_bf16 v[16:31], v[68:71], v[52:55], v[16:31]
	s_waitcnt lgkmcnt(0)
	v_mfma_f32_32x32x16_bf16 v[16:31], v[72:75], v[60:63], v[16:31]
	s_setprio 0

; #define LAS __attribute__((address_space(3)))
; DI unsigned pk2(float lo, float hi) { f32x2 v = {lo, hi}; bf16x2_t b = __builtin_convertvector(v, bf16x2_t); return __builtin_bit_cast(unsigned, b); }
; DI void att_sm_tail(f32x16 (&S)[2], bf16x8 (&pkm)[2][2], const float mrefm, float& lrunm) {
;     {
;         f32x16& s0 = S[0]; f32x16& s1 = S[1];
;         const f32x2 nm2 = {-mrefm, -mrefm};
;         f32x2 acc2 = {0.f, 0.f};
; #pragma unroll
;         for (int i = 0; i < 16; i += 2) {
;             f32x2 a = {s0[i], s0[i + 1]}, b = {s1[i], s1[i + 1]}; a += nm2; b += nm2;
;             a.x = fast_exp2(a.x); a.y = fast_exp2(a.y); b.x = fast_exp2(b.x); b.y = fast_exp2(b.y);
;             acc2 += a; acc2 += b; s0[i] = a.x; s0[i + 1] = a.y; s1[i] = b.x; s1[i + 1] = b.y;
;         }
;         lrunm += acc2.x + acc2.y;
; #pragma unroll
;         for (int s = 0; s < 2; ++s) {
;             u32x4 w0, w1;
;             w0.x = pk2(s0[8 * s + 0], s0[8 * s + 1]); w0.y = pk2(s0[8 * s + 2], s0[8 * s + 3]); w0.z = pk2(s0[8 * s + 4], s0[8 * s + 5]); w0.w = pk2(s0[8 * s + 6], s0[8 * s + 7]);
;             w1.x = pk2(s1[8 * s + 0], s1[8 * s + 1]); w1.y = pk2(s1[8 * s + 2], s1[8 * s + 3]); w1.z = pk2(s1[8 * s + 4], s1[8 * s + 5]); w1.w = pk2(s1[8 * s + 6], s1[8 * s + 7]);
;             pkm[0][s] = __builtin_bit_cast(bf16x8, w0); pkm[1][s] = __builtin_bit_cast(bf16x8, w1);
;         }
;     }
; }
; DI void att_vload(const LAS unsigned char* vb, int e, s16x4 (&lo)[4], s16x4 (&hi)[4]) {
;     constexpr int VP = 144;
; #pragma unroll
;     for (int q = 0; q < 4; ++q) { const LAS unsigned char* p = vb + (16 * q) * VP + 64 * e;
;         lo[q] = __builtin_bit_cast(s16x4, __builtin_amdgcn_ds_read_tr16_b64_v4i16((LAS s16x4*)p));
;         hi[q] = __builtin_bit_cast(s16x4, __builtin_amdgcn_ds_read_tr16_b64_v4i16((LAS s16x4*)(p + 8 * VP))); }
; }
; template <int NMAP>
; DI void att_pvmm(const s16x4 (&lo)[4], const s16x4 (&hi)[4], const bf16x8 (&pk)[NMAP][2][2], f32x16 (&o)[NMAP][2], int e) {
;     __builtin_amdgcn_s_setprio(1);
; #pragma unroll
;     for (int q = 0; q < 4; ++q) { const bf16x8 vf = (bf16x8){lo[q][0], lo[q][1], lo[q][2], lo[q][3], hi[q][0], hi[q][1], hi[q][2], hi[q][3]};
; #pragma unroll
;         for (int mp = 0; mp < NMAP; ++mp) o[mp][e] = __builtin_amdgcn_mfma_f32_32x32x16_bf16(vf, pk[mp][q >> 1][q & 1], o[mp][e], 0, 0, 0); }
;     __builtin_amdgcn_s_setprio(0);
; }
.LBB0_658:
	v_sub_f32_e32 v14, v48, v164
	v_sub_f32_e32 v15, v49, v164
	v_sub_f32_e32 v48, v64, v164
	v_sub_f32_e32 v49, v65, v164
	v_exp_f32_e32 v14, v14
	v_exp_f32_e32 v15, v15
	v_exp_f32_e32 v64, v48
	v_exp_f32_e32 v65, v49
	v_sub_f32_e32 v48, v50, v164
	v_sub_f32_e32 v49, v51, v164
	v_sub_f32_e32 v50, v66, v164
	v_sub_f32_e32 v51, v67, v164
	v_exp_f32_e32 v66, v48
	v_exp_f32_e32 v67, v49
	v_exp_f32_e32 v174, v50
	v_exp_f32_e32 v175, v51
	v_sub_f32_e32 v50, v52, v164
	v_sub_f32_e32 v51, v53, v164
	v_add_f32_e32 v48, 0, v14
	v_add_f32_e32 v49, 0, v15
	v_sub_f32_e32 v52, v68, v164
	v_sub_f32_e32 v53, v69, v164
	v_exp_f32_e32 v50, v50
	v_exp_f32_e32 v51, v51
	v_add_f32_e32 v48, v64, v48
	v_add_f32_e32 v49, v65, v49
	v_exp_f32_e32 v68, v52
	v_exp_f32_e32 v69, v53
	v_sub_f32_e32 v52, v54, v164
	v_sub_f32_e32 v53, v55, v164
	v_add_f32_e32 v48, v66, v48
	v_add_f32_e32 v49, v67, v49
	v_sub_f32_e32 v54, v70, v164
	v_sub_f32_e32 v55, v71, v164
	v_exp_f32_e32 v52, v52
	v_exp_f32_e32 v53, v53
	v_add_f32_e32 v48, v174, v48
	v_add_f32_e32 v49, v175, v49
	v_exp_f32_e32 v70, v54
	v_exp_f32_e32 v71, v55
	v_sub_f32_e32 v54, v56, v164
	v_sub_f32_e32 v55, v57, v164
	v_add_f32_e32 v48, v50, v48
	v_add_f32_e32 v49, v51, v49
	v_sub_f32_e32 v56, v72, v164
	v_sub_f32_e32 v57, v73, v164
	v_exp_f32_e32 v72, v54
	v_exp_f32_e32 v73, v55
	v_add_f32_e32 v48, v68, v48
	v_add_f32_e32 v49, v69, v49
	v_exp_f32_e32 v176, v56
	v_exp_f32_e32 v177, v57
	v_sub_f32_e32 v54, v58, v164
	v_sub_f32_e32 v55, v59, v164
	v_add_f32_e32 v48, v52, v48
	v_add_f32_e32 v49, v53, v49
	v_sub_f32_e32 v56, v74, v164
	v_sub_f32_e32 v57, v75, v164
	v_exp_f32_e32 v58, v54
	v_exp_f32_e32 v59, v55
	v_add_f32_e32 v48, v70, v48
	v_add_f32_e32 v49, v71, v49
	v_exp_f32_e32 v74, v56
	v_exp_f32_e32 v75, v57
	v_sub_f32_e32 v54, v60, v164
	v_sub_f32_e32 v55, v61, v164
	v_add_f32_e32 v48, v72, v48
	v_add_f32_e32 v49, v73, v49
	v_sub_f32_e32 v56, v76, v164
	v_sub_f32_e32 v57, v77, v164
	v_exp_f32_e32 v60, v54
	v_exp_f32_e32 v61, v55
	v_add_f32_e32 v48, v176, v48
	v_add_f32_e32 v49, v177, v49
	v_exp_f32_e32 v76, v56
	v_exp_f32_e32 v77, v57
	v_sub_f32_e32 v54, v62, v164
	v_sub_f32_e32 v55, v63, v164
	v_add_f32_e32 v48, v58, v48
	v_add_f32_e32 v49, v59, v49
	v_sub_f32_e32 v56, v78, v164
	v_sub_f32_e32 v57, v79, v164
	v_exp_f32_e32 v62, v54
	v_exp_f32_e32 v63, v55
	v_add_f32_e32 v48, v74, v48
	v_add_f32_e32 v49, v75, v49
	v_exp_f32_e32 v78, v56
	v_exp_f32_e32 v79, v57
	v_add_f32_e32 v48, v60, v48
	v_add_f32_e32 v49, v61, v49
	v_cvt_pk_bf16_f32 v50, v50, v51
	v_add_f32_e32 v48, v76, v48
	v_add_f32_e32 v49, v77, v49
	v_cvt_pk_bf16_f32 v51, v52, v53
	v_add_f32_e32 v48, v62, v48
	v_add_f32_e32 v49, v63, v49
	v_cvt_pk_bf16_f32 v52, v64, v65
	v_add_f32_e32 v48, v78, v48
	v_add_f32_e32 v49, v79, v49
	v_cvt_pk_bf16_f32 v53, v174, v175
	v_add_f32_e32 v0, v48, v49
	v_add_f32_e32 v172, v172, v0
	v_cvt_pk_bf16_f32 v48, v14, v15
	v_cvt_pk_bf16_f32 v49, v66, v67
	v_cvt_pk_bf16_f32 v54, v68, v69
	v_cvt_pk_bf16_f32 v55, v70, v71
	v_cvt_pk_bf16_f32 v56, v72, v73
	v_cvt_pk_bf16_f32 v57, v58, v59
	v_cvt_pk_bf16_f32 v58, v60, v61
	v_cvt_pk_bf16_f32 v59, v62, v63
	v_cvt_pk_bf16_f32 v60, v176, v177
	v_cvt_pk_bf16_f32 v61, v74, v75
	v_cvt_pk_bf16_f32 v62, v76, v77
	v_cvt_pk_bf16_f32 v63, v78, v79
	s_setprio 1
	s_waitcnt lgkmcnt(2)
	v_mfma_f32_32x32x16_bf16 v[32:47], v[140:143], v[48:51], v[32:47]
	v_mfma_f32_32x32x16_bf16 v[32:47], v[136:139], v[56:59], v[32:47]
	v_mfma_f32_32x32x16_bf16 v[32:47], v[132:135], v[52:55], v[32:47]
	s_waitcnt lgkmcnt(0)
	v_mfma_f32_32x32x16_bf16 v[32:47], v[10:13], v[60:63], v[32:47]
	s_setprio 0
	ds_read_b64_tr_b16 v[10:11], v173 offset:28992
	ds_read_b64_tr_b16 v[12:13], v173 offset:30144
	ds_read_b64_tr_b16 v[64:65], v173 offset:31296
	ds_read_b64_tr_b16 v[66:67], v173 offset:32448
	ds_read_b64_tr_b16 v[68:69], v173 offset:26688
	ds_read_b64_tr_b16 v[70:71], v173 offset:27840
	ds_read_b64_tr_b16 v[72:73], v173 offset:33600
	ds_read_b64_tr_b16 v[74:75], v173 offset:34752
	s_setprio 1
	s_waitcnt lgkmcnt(2)
	v_mfma_f32_32x32x16_bf16 v[16:31], v[68:71], v[48:51], v[16:31]
	v_mfma_f32_32x32x16_bf16 v[16:31], v[10:13], v[56:59], v[16:31]
	v_mfma_f32_32x32x16_bf16 v[16:31], v[64:67], v[52:55], v[16:31]
	s_waitcnt lgkmcnt(0)
	v_mfma_f32_32x32x16_bf16 v[16:31], v[72:75], v[60:63], v[16:31]
	s_setprio 0

; #define LAS __attribute__((address_space(3)))
; DI unsigned pk2(float lo, float hi) { f32x2 v = {lo, hi}; bf16x2_t b = __builtin_convertvector(v, bf16x2_t); return __builtin_bit_cast(unsigned, b); }
; DI void att_sm_tail(f32x16 (&S)[2], bf16x8 (&pkm)[2][2], const float mrefm, float& lrunm) {
;     {
;         f32x16& s0 = S[0]; f32x16& s1 = S[1];
;         const f32x2 nm2 = {-mrefm, -mrefm};
;         f32x2 acc2 = {0.f, 0.f};
; #pragma unroll
;         for (int i = 0; i < 16; i += 2) {
;             f32x2 a = {s0[i], s0[i + 1]}, b = {s1[i], s1[i + 1]}; a += nm2; b += nm2;
;             a.x = fast_exp2(a.x); a.y = fast_exp2(a.y); b.x = fast_exp2(b.x); b.y = fast_exp2(b.y);
;             acc2 += a; acc2 += b; s0[i] = a.x; s0[i + 1] = a.y; s1[i] = b.x; s1[i + 1] = b.y;
;         }
;         lrunm += acc2.x + acc2.y;
; #pragma unroll
;         for (int s = 0; s < 2; ++s) {
;             u32x4 w0, w1;
;             w0.x = pk2(s0[8 * s + 0], s0[8 * s + 1]); w0.y = pk2(s0[8 * s + 2], s0[8 * s + 3]); w0.z = pk2(s0[8 * s + 4], s0[8 * s + 5]); w0.w = pk2(s0[8 * s + 6], s0[8 * s + 7]);
;             w1.x = pk2(s1[8 * s + 0], s1[8 * s + 1]); w1.y = pk2(s1[8 * s + 2], s1[8 * s + 3]); w1.z = pk2(s1[8 * s + 4], s1[8 * s + 5]); w1.w = pk2(s1[8 * s + 6], s1[8 * s + 7]);
;             pkm[0][s] = __builtin_bit_cast(bf16x8, w0); pkm[1][s] = __builtin_bit_cast(bf16x8, w1);
;         }
;     }
; }
; DI void att_vload(const LAS unsigned char* vb, int e, s16x4 (&lo)[4], s16x4 (&hi)[4]) {
;     constexpr int VP = 144;
; #pragma unroll
;     for (int q = 0; q < 4; ++q) { const LAS unsigned char* p = vb + (16 * q) * VP + 64 * e;
;         lo[q] = __builtin_bit_cast(s16x4, __builtin_amdgcn_ds_read_tr16_b64_v4i16((LAS s16x4*)p));
;         hi[q] = __builtin_bit_cast(s16x4, __builtin_amdgcn_ds_read_tr16_b64_v4i16((LAS s16x4*)(p + 8 * VP))); }
; }
; template <int NMAP>
; DI void att_pvmm(const s16x4 (&lo)[4], const s16x4 (&hi)[4], const bf16x8 (&pk)[NMAP][2][2], f32x16 (&o)[NMAP][2], int e) {
;     __builtin_amdgcn_s_setprio(1);
; #pragma unroll
;     for (int q = 0; q < 4; ++q) { const bf16x8 vf = (bf16x8){lo[q][0], lo[q][1], lo[q][2], lo[q][3], hi[q][0], hi[q][1], hi[q][2], hi[q][3]};
; #pragma unroll
;         for (int mp = 0; mp < NMAP; ++mp) o[mp][e] = __builtin_amdgcn_mfma_f32_32x32x16_bf16(vf, pk[mp][q >> 1][q & 1], o[mp][e], 0, 0, 0); }
;     __builtin_amdgcn_s_setprio(0);
; }
.LBB0_666:
	v_sub_f32_e32 v14, v48, v164
	v_sub_f32_e32 v15, v49, v164
	v_sub_f32_e32 v48, v64, v164
	v_sub_f32_e32 v49, v65, v164
	v_exp_f32_e32 v14, v14
	v_exp_f32_e32 v15, v15
	v_exp_f32_e32 v64, v48
	v_exp_f32_e32 v65, v49
	v_sub_f32_e32 v48, v50, v164
	v_sub_f32_e32 v49, v51, v164
	v_sub_f32_e32 v50, v66, v164
	v_sub_f32_e32 v51, v67, v164
	v_exp_f32_e32 v66, v48
	v_exp_f32_e32 v67, v49
	v_exp_f32_e32 v174, v50
	v_exp_f32_e32 v175, v51
	v_sub_f32_e32 v50, v52, v164
	v_sub_f32_e32 v51, v53, v164
	v_add_f32_e32 v48, 0, v14
	v_add_f32_e32 v49, 0, v15
	v_sub_f32_e32 v52, v68, v164
	v_sub_f32_e32 v53, v69, v164
	v_exp_f32_e32 v50, v50
	v_exp_f32_e32 v51, v51
	v_add_f32_e32 v48, v64, v48
	v_add_f32_e32 v49, v65, v49
	v_exp_f32_e32 v68, v52
	v_exp_f32_e32 v69, v53
	v_sub_f32_e32 v52, v54, v164
	v_sub_f32_e32 v53, v55, v164
	v_add_f32_e32 v48, v66, v48
	v_add_f32_e32 v49, v67, v49
	v_sub_f32_e32 v54, v70, v164
	v_sub_f32_e32 v55, v71, v164
	v_exp_f32_e32 v52, v52
	v_exp_f32_e32 v53, v53
	v_add_f32_e32 v48, v174, v48
	v_add_f32_e32 v49, v175, v49
	v_exp_f32_e32 v70, v54
	v_exp_f32_e32 v71, v55
	v_sub_f32_e32 v54, v56, v164
	v_sub_f32_e32 v55, v57, v164
	v_add_f32_e32 v48, v50, v48
	v_add_f32_e32 v49, v51, v49
	v_sub_f32_e32 v56, v72, v164
	v_sub_f32_e32 v57, v73, v164
	v_exp_f32_e32 v72, v54
	v_exp_f32_e32 v73, v55
	v_add_f32_e32 v48, v68, v48
	v_add_f32_e32 v49, v69, v49
	v_exp_f32_e32 v176, v56
	v_exp_f32_e32 v177, v57
	v_sub_f32_e32 v54, v58, v164
	v_sub_f32_e32 v55, v59, v164
	v_add_f32_e32 v48, v52, v48
	v_add_f32_e32 v49, v53, v49
	v_sub_f32_e32 v56, v74, v164
	v_sub_f32_e32 v57, v75, v164
	v_exp_f32_e32 v58, v54
	v_exp_f32_e32 v59, v55
	v_add_f32_e32 v48, v70, v48
	v_add_f32_e32 v49, v71, v49
	v_exp_f32_e32 v74, v56
	v_exp_f32_e32 v75, v57
	v_sub_f32_e32 v54, v60, v164
	v_sub_f32_e32 v55, v61, v164
	v_add_f32_e32 v48, v72, v48
	v_add_f32_e32 v49, v73, v49
	v_sub_f32_e32 v56, v76, v164
	v_sub_f32_e32 v57, v77, v164
	v_exp_f32_e32 v60, v54
	v_exp_f32_e32 v61, v55
	v_add_f32_e32 v48, v176, v48
	v_add_f32_e32 v49, v177, v49
	v_exp_f32_e32 v76, v56
	v_exp_f32_e32 v77, v57
	v_sub_f32_e32 v54, v62, v164
	v_sub_f32_e32 v55, v63, v164
	v_add_f32_e32 v48, v58, v48
	v_add_f32_e32 v49, v59, v49
	v_sub_f32_e32 v56, v78, v164
	v_sub_f32_e32 v57, v79, v164
	v_exp_f32_e32 v62, v54
	v_exp_f32_e32 v63, v55
	v_add_f32_e32 v48, v74, v48
	v_add_f32_e32 v49, v75, v49
	v_exp_f32_e32 v78, v56
	v_exp_f32_e32 v79, v57
	v_add_f32_e32 v48, v60, v48
	v_add_f32_e32 v49, v61, v49
	v_cvt_pk_bf16_f32 v50, v50, v51
	v_add_f32_e32 v48, v76, v48
	v_add_f32_e32 v49, v77, v49
	v_cvt_pk_bf16_f32 v51, v52, v53
	v_add_f32_e32 v48, v62, v48
	v_add_f32_e32 v49, v63, v49
	v_cvt_pk_bf16_f32 v52, v64, v65
	v_add_f32_e32 v48, v78, v48
	v_add_f32_e32 v49, v79, v49
	v_cvt_pk_bf16_f32 v53, v174, v175
	v_add_f32_e32 v0, v48, v49
	v_add_f32_e32 v172, v172, v0
	v_cvt_pk_bf16_f32 v48, v14, v15
	v_cvt_pk_bf16_f32 v49, v66, v67
	v_cvt_pk_bf16_f32 v54, v68, v69
	v_cvt_pk_bf16_f32 v55, v70, v71
	v_cvt_pk_bf16_f32 v56, v72, v73
	v_cvt_pk_bf16_f32 v57, v58, v59
	v_cvt_pk_bf16_f32 v58, v60, v61
	v_cvt_pk_bf16_f32 v59, v62, v63
	v_cvt_pk_bf16_f32 v60, v176, v177
	v_cvt_pk_bf16_f32 v61, v74, v75
	v_cvt_pk_bf16_f32 v62, v76, v77
	v_cvt_pk_bf16_f32 v63, v78, v79
	s_setprio 1
	s_waitcnt lgkmcnt(6)
	v_mfma_f32_32x32x16_bf16 v[32:47], v[140:143], v[48:51], v[32:47]
	s_waitcnt lgkmcnt(4)
	v_mfma_f32_32x32x16_bf16 v[32:47], v[136:139], v[56:59], v[32:47]
	s_waitcnt lgkmcnt(2)
	v_mfma_f32_32x32x16_bf16 v[32:47], v[132:135], v[52:55], v[32:47]
	s_waitcnt lgkmcnt(0)
	v_mfma_f32_32x32x16_bf16 v[32:47], v[10:13], v[60:63], v[32:47]
	s_setprio 0
	ds_read_b64_tr_b16 v[10:11], v173 offset:35904
	ds_read_b64_tr_b16 v[12:13], v173 offset:37056
	ds_read_b64_tr_b16 v[64:65], v173 offset:38208
	ds_read_b64_tr_b16 v[66:67], v173 offset:39360
	ds_read_b64_tr_b16 v[68:69], v173 offset:40512
	ds_read_b64_tr_b16 v[70:71], v173 offset:41664
	ds_read_b64_tr_b16 v[72:73], v173 offset:42816
	ds_read_b64_tr_b16 v[74:75], v173 offset:43968
	s_setprio 1
	s_waitcnt lgkmcnt(6)
	v_mfma_f32_32x32x16_bf16 v[16:31], v[10:13], v[48:51], v[16:31]
	s_waitcnt lgkmcnt(4)
	v_mfma_f32_32x32x16_bf16 v[16:31], v[64:67], v[56:59], v[16:31]
	s_waitcnt lgkmcnt(2)
	v_mfma_f32_32x32x16_bf16 v[16:31], v[68:71], v[52:55], v[16:31]
	s_waitcnt lgkmcnt(0)
	v_mfma_f32_32x32x16_bf16 v[16:31], v[72:75], v[60:63], v[16:31]
	s_setprio 0

; #define LAS __attribute__((address_space(3)))
; DI unsigned pk2(float lo, float hi) { f32x2 v = {lo, hi}; bf16x2_t b = __builtin_convertvector(v, bf16x2_t); return __builtin_bit_cast(unsigned, b); }
; DI void att_sm_tail(f32x16 (&S)[2], bf16x8 (&pkm)[2][2], const float mrefm, float& lrunm) {
;     {
;         f32x16& s0 = S[0]; f32x16& s1 = S[1];
;         const f32x2 nm2 = {-mrefm, -mrefm};
;         f32x2 acc2 = {0.f, 0.f};
; #pragma unroll
;         for (int i = 0; i < 16; i += 2) {
;             f32x2 a = {s0[i], s0[i + 1]}, b = {s1[i], s1[i + 1]}; a += nm2; b += nm2;
;             a.x = fast_exp2(a.x); a.y = fast_exp2(a.y); b.x = fast_exp2(b.x); b.y = fast_exp2(b.y);
;             acc2 += a; acc2 += b; s0[i] = a.x; s0[i + 1] = a.y; s1[i] = b.x; s1[i + 1] = b.y;
;         }
;         lrunm += acc2.x + acc2.y;
; #pragma unroll
;         for (int s = 0; s < 2; ++s) {
;             u32x4 w0, w1;
;             w0.x = pk2(s0[8 * s + 0], s0[8 * s + 1]); w0.y = pk2(s0[8 * s + 2], s0[8 * s + 3]); w0.z = pk2(s0[8 * s + 4], s0[8 * s + 5]); w0.w = pk2(s0[8 * s + 6], s0[8 * s + 7]);
;             w1.x = pk2(s1[8 * s + 0], s1[8 * s + 1]); w1.y = pk2(s1[8 * s + 2], s1[8 * s + 3]); w1.z = pk2(s1[8 * s + 4], s1[8 * s + 5]); w1.w = pk2(s1[8 * s + 6], s1[8 * s + 7]);
;             pkm[0][s] = __builtin_bit_cast(bf16x8, w0); pkm[1][s] = __builtin_bit_cast(bf16x8, w1);
;         }
;     }
; }
; DI void att_vload(const LAS unsigned char* vb, int e, s16x4 (&lo)[4], s16x4 (&hi)[4]) {
;     constexpr int VP = 144;
; #pragma unroll
;     for (int q = 0; q < 4; ++q) { const LAS unsigned char* p = vb + (16 * q) * VP + 64 * e;
;         lo[q] = __builtin_bit_cast(s16x4, __builtin_amdgcn_ds_read_tr16_b64_v4i16((LAS s16x4*)p));
;         hi[q] = __builtin_bit_cast(s16x4, __builtin_amdgcn_ds_read_tr16_b64_v4i16((LAS s16x4*)(p + 8 * VP))); }
; }
; template <int NMAP>
; DI void att_pvmm(const s16x4 (&lo)[4], const s16x4 (&hi)[4], const bf16x8 (&pk)[NMAP][2][2], f32x16 (&o)[NMAP][2], int e) {
;     __builtin_amdgcn_s_setprio(1);
; #pragma unroll
;     for (int q = 0; q < 4; ++q) { const bf16x8 vf = (bf16x8){lo[q][0], lo[q][1], lo[q][2], lo[q][3], hi[q][0], hi[q][1], hi[q][2], hi[q][3]};
; #pragma unroll
;         for (int mp = 0; mp < NMAP; ++mp) o[mp][e] = __builtin_amdgcn_mfma_f32_32x32x16_bf16(vf, pk[mp][q >> 1][q & 1], o[mp][e], 0, 0, 0); }
;     __builtin_amdgcn_s_setprio(0);
; }
.LBB0_674:
	v_sub_f32_e32 v14, v48, v164
	v_sub_f32_e32 v15, v49, v164
	v_sub_f32_e32 v48, v64, v164
	v_sub_f32_e32 v49, v65, v164
	v_exp_f32_e32 v14, v14
	v_exp_f32_e32 v15, v15
	v_exp_f32_e32 v64, v48
	v_exp_f32_e32 v65, v49
	v_sub_f32_e32 v48, v50, v164
	v_sub_f32_e32 v49, v51, v164
	v_sub_f32_e32 v50, v66, v164
	v_sub_f32_e32 v51, v67, v164
	v_exp_f32_e32 v66, v48
	v_exp_f32_e32 v67, v49
	v_exp_f32_e32 v174, v50
	v_exp_f32_e32 v175, v51
	v_sub_f32_e32 v50, v52, v164
	v_sub_f32_e32 v51, v53, v164
	v_add_f32_e32 v48, 0, v14
	v_add_f32_e32 v49, 0, v15
	v_sub_f32_e32 v52, v68, v164
	v_sub_f32_e32 v53, v69, v164
	v_exp_f32_e32 v50, v50
	v_exp_f32_e32 v51, v51
	v_add_f32_e32 v48, v64, v48
	v_add_f32_e32 v49, v65, v49
	v_exp_f32_e32 v68, v52
	v_exp_f32_e32 v69, v53
	v_sub_f32_e32 v52, v54, v164
	v_sub_f32_e32 v53, v55, v164
	v_add_f32_e32 v48, v66, v48
	v_add_f32_e32 v49, v67, v49
	v_sub_f32_e32 v54, v70, v164
	v_sub_f32_e32 v55, v71, v164
	v_exp_f32_e32 v52, v52
	v_exp_f32_e32 v53, v53
	v_add_f32_e32 v48, v174, v48
	v_add_f32_e32 v49, v175, v49
	v_exp_f32_e32 v70, v54
	v_exp_f32_e32 v71, v55
	v_sub_f32_e32 v54, v56, v164
	v_sub_f32_e32 v55, v57, v164
	v_add_f32_e32 v48, v50, v48
	v_add_f32_e32 v49, v51, v49
	v_sub_f32_e32 v56, v72, v164
	v_sub_f32_e32 v57, v73, v164
	v_exp_f32_e32 v72, v54
	v_exp_f32_e32 v73, v55
	v_add_f32_e32 v48, v68, v48
	v_add_f32_e32 v49, v69, v49
	v_exp_f32_e32 v176, v56
	v_exp_f32_e32 v177, v57
	v_sub_f32_e32 v54, v58, v164
	v_sub_f32_e32 v55, v59, v164
	v_add_f32_e32 v48, v52, v48
	v_add_f32_e32 v49, v53, v49
	v_sub_f32_e32 v56, v74, v164
	v_sub_f32_e32 v57, v75, v164
	v_exp_f32_e32 v58, v54
	v_exp_f32_e32 v59, v55
	v_add_f32_e32 v48, v70, v48
	v_add_f32_e32 v49, v71, v49
	v_exp_f32_e32 v74, v56
	v_exp_f32_e32 v75, v57
	v_sub_f32_e32 v54, v60, v164
	v_sub_f32_e32 v55, v61, v164
	v_add_f32_e32 v48, v72, v48
	v_add_f32_e32 v49, v73, v49
	v_sub_f32_e32 v56, v76, v164
	v_sub_f32_e32 v57, v77, v164
	v_exp_f32_e32 v60, v54
	v_exp_f32_e32 v61, v55
	v_add_f32_e32 v48, v176, v48
	v_add_f32_e32 v49, v177, v49
	v_exp_f32_e32 v76, v56
	v_exp_f32_e32 v77, v57
	v_sub_f32_e32 v54, v62, v164
	v_sub_f32_e32 v55, v63, v164
	v_add_f32_e32 v48, v58, v48
	v_add_f32_e32 v49, v59, v49
	v_sub_f32_e32 v56, v78, v164
	v_sub_f32_e32 v57, v79, v164
	v_exp_f32_e32 v62, v54
	v_exp_f32_e32 v63, v55
	v_add_f32_e32 v48, v74, v48
	v_add_f32_e32 v49, v75, v49
	v_exp_f32_e32 v78, v56
	v_exp_f32_e32 v79, v57
	v_add_f32_e32 v48, v60, v48
	v_add_f32_e32 v49, v61, v49
	v_cvt_pk_bf16_f32 v50, v50, v51
	v_add_f32_e32 v48, v76, v48
	v_add_f32_e32 v49, v77, v49
	v_cvt_pk_bf16_f32 v51, v52, v53
	v_add_f32_e32 v48, v62, v48
	v_add_f32_e32 v49, v63, v49
	v_cvt_pk_bf16_f32 v52, v64, v65
	v_add_f32_e32 v48, v78, v48
	v_add_f32_e32 v49, v79, v49
	v_cvt_pk_bf16_f32 v53, v174, v175
	v_add_f32_e32 v0, v48, v49
	v_add_f32_e32 v172, v172, v0
	v_cvt_pk_bf16_f32 v48, v14, v15
	v_cvt_pk_bf16_f32 v49, v66, v67
	v_cvt_pk_bf16_f32 v54, v68, v69
	v_cvt_pk_bf16_f32 v55, v70, v71
	v_cvt_pk_bf16_f32 v56, v72, v73
	v_cvt_pk_bf16_f32 v57, v58, v59
	v_cvt_pk_bf16_f32 v58, v60, v61
	v_cvt_pk_bf16_f32 v59, v62, v63
	v_cvt_pk_bf16_f32 v60, v176, v177
	v_cvt_pk_bf16_f32 v61, v74, v75
	v_cvt_pk_bf16_f32 v62, v76, v77
	v_cvt_pk_bf16_f32 v63, v78, v79
	s_setprio 1
	s_waitcnt lgkmcnt(6)
	v_mfma_f32_32x32x16_bf16 v[32:47], v[140:143], v[48:51], v[32:47]
	s_waitcnt lgkmcnt(4)
	v_mfma_f32_32x32x16_bf16 v[32:47], v[136:139], v[56:59], v[32:47]
	s_waitcnt lgkmcnt(2)
	v_mfma_f32_32x32x16_bf16 v[32:47], v[132:135], v[52:55], v[32:47]
	s_waitcnt lgkmcnt(0)
	v_mfma_f32_32x32x16_bf16 v[32:47], v[10:13], v[60:63], v[32:47]
	s_setprio 0
	ds_read_b64_tr_b16 v[10:11], v173 offset:45120
	ds_read_b64_tr_b16 v[12:13], v173 offset:46272
	ds_read_b64_tr_b16 v[64:65], v173 offset:47424
	ds_read_b64_tr_b16 v[66:67], v173 offset:48576
	ds_read_b64_tr_b16 v[68:69], v173 offset:49728
	ds_read_b64_tr_b16 v[70:71], v173 offset:50880
	ds_read_b64_tr_b16 v[72:73], v173 offset:52032
	ds_read_b64_tr_b16 v[74:75], v173 offset:53184
	s_setprio 1
	s_waitcnt lgkmcnt(6)
	v_mfma_f32_32x32x16_bf16 v[16:31], v[10:13], v[48:51], v[16:31]
	s_waitcnt lgkmcnt(4)
	v_mfma_f32_32x32x16_bf16 v[16:31], v[64:67], v[56:59], v[16:31]
	s_waitcnt lgkmcnt(2)
	v_mfma_f32_32x32x16_bf16 v[16:31], v[68:71], v[52:55], v[16:31]
	s_waitcnt lgkmcnt(0)
	v_mfma_f32_32x32x16_bf16 v[16:31], v[72:75], v[60:63], v[16:31]
	s_setprio 0

; #define GAS __attribute__((address_space(1)))
;     DI void operator()(const f32x4 (&acc)[2][2][4][2], const Unit& u, int wr, int wc, int fr, int fq) const {
;     ...
;         } else {
;             const int col0 = u.pn * BM + wc * 64 + 8 * fq;
;             f32x4 bb[2][2];
; #pragma unroll
;             for (int bj = 0; bj < 2; ++bj) { bb[bj][0] = *(const GAS f32x4*)(bias + col0 + bj * 32); bb[bj][1] = *(const GAS f32x4*)(bias + col0 + bj * 32 + 4); }
; #pragma unroll
;             for (int ai = 0; ai < 2; ++ai)
; #pragma unroll
;                 for (int m = 0; m < 4; ++m) { const size_t offb = (size_t)(row0 + ai * HALF + m * 16) * DM + col0;
;                     u32x4 brv[2], mgv[2];
; #pragma unroll
;                     for (int bj = 0; bj < 2; ++bj) { brv[bj] = *(const GAS u32x4*)(BR + offb + bj * 32); mgv[bj] = (gi > 0) ? *(const GAS u32x4*)(MG + offb + bj * 32) : (u32x4){0, 0, 0, 0}; }
; #pragma unroll
;                     for (int bj = 0; bj < 2; ++bj) { const size_t off = offb + bj * 32; const u32x4 br = brv[bj], mg = mgv[bj];
;                         f32x4 x0 = acc[ai][bj][m][0] + bb[bj][0], x1 = acc[ai][bj][m][1] + bb[bj][1]; float v[8];
;                         const float bv[8] = {__uint_as_float(br.x << 16), __uint_as_float(br.x & 0xffff0000u), __uint_as_float(br.y << 16), __uint_as_float(br.y & 0xffff0000u),
;                                              __uint_as_float(br.z << 16), __uint_as_float(br.z & 0xffff0000u), __uint_as_float(br.w << 16), __uint_as_float(br.w & 0xffff0000u)};
; #pragma unroll
;                         for (int j = 0; j < 4; ++j) { v[j] = fast_rcp(1.0f + fast_exp2(-x0[j] * LOG2E)) * bv[j]; v[4 + j] = fast_rcp(1.0f + fast_exp2(-x1[j] * LOG2E)) * bv[4 + j]; }
;                         v[0] += __uint_as_float(mg.x << 16); v[1] += __uint_as_float(mg.x & 0xffff0000u); v[2] += __uint_as_float(mg.y << 16); v[3] += __uint_as_float(mg.y & 0xffff0000u);
;                         v[4] += __uint_as_float(mg.z << 16); v[5] += __uint_as_float(mg.z & 0xffff0000u); v[6] += __uint_as_float(mg.w << 16); v[7] += __uint_as_float(mg.w & 0xffff0000u);
;                         u32x4 w; w.x = pk2(v[0], v[1]); w.y = pk2(v[2], v[3]); w.z = pk2(v[4], v[5]); w.w = pk2(v[6], v[7]);
;                         if (gi < 3) *(GAS u32x4*)(MG + off) = w; else *(GAS u32x4*)(BR + off) = w; } }
;         }
.LBB0_812:
	s_cmp_lt_i32 s46, 1
	s_cbranch_scc1 .Lm3_nomg
	v_ashrrev_i32_e32 v177, 31, v176
	v_mov_b32_e32 v130, s80
	v_mov_b32_e32 v131, s81
	v_ashrrev_i32_e32 v179, 31, v178
	v_lshlrev_b64 v[146:147], 10, v[176:177]
	v_lshl_add_u64 v[180:181], v[178:179], 2, v[130:131]
	v_lshl_add_u64 v[164:165], v[146:147], 0, v[178:179]
	global_load_dwordx4 v[130:133], v[180:181], off
	global_load_dwordx4 v[134:137], v[180:181], off offset:16
	global_load_dwordx4 v[138:141], v[180:181], off offset:128
	global_load_dwordx4 v[142:145], v[180:181], off offset:144
	v_lshlrev_b64 v[164:165], 1, v[164:165]
	s_cmp_lt_i32 s46, 3
	s_cselect_b32 s1, s35, s45
	s_cselect_b32 s0, s34, s44
	s_add_u32 s40, s44, 0x0
	s_addc_u32 s41, s45, 0
	v_lshl_add_u64 v[146:147], v[164:165], 0, s[40:41]
	s_add_u32 s6, s34, 0x0
	s_addc_u32 s7, s35, 0
	v_lshl_add_u64 v[180:181], v[164:165], 0, s[6:7]
	global_load_dwordx4 v[148:151], v[146:147], off
	global_load_dwordx4 v[152:155], v[180:181], off
	global_load_dwordx4 v[156:159], v[146:147], off offset:64
	global_load_dwordx4 v[160:163], v[180:181], off offset:64
	s_add_u32 s40, s44, 0x8000
	s_addc_u32 s41, s45, 0
	v_lshl_add_u64 v[146:147], v[164:165], 0, s[40:41]
	s_add_u32 s6, s34, 0x8000
	s_addc_u32 s7, s35, 0
	v_lshl_add_u64 v[180:181], v[164:165], 0, s[6:7]
	global_load_dwordx4 v[236:239], v[146:147], off
	global_load_dwordx4 v[240:243], v[180:181], off
	global_load_dwordx4 v[244:247], v[146:147], off offset:64
	global_load_dwordx4 v[248:251], v[180:181], off offset:64
	s_add_u32 s40, s44, 0x10000
	s_addc_u32 s41, s45, 0
	v_lshl_add_u64 v[146:147], v[164:165], 0, s[40:41]
	s_add_u32 s6, s34, 0x10000
	s_addc_u32 s7, s35, 0
	v_lshl_add_u64 v[180:181], v[164:165], 0, s[6:7]
	global_load_dwordx4 v[194:197], v[146:147], off
	global_load_dwordx4 v[200:203], v[180:181], off
	global_load_dwordx4 v[204:207], v[146:147], off offset:64
	global_load_dwordx4 v[230:233], v[180:181], off offset:64
	s_waitcnt vmcnt(8)
	s_add_u32 s40, s0, 0x0
	s_addc_u32 s41, s1, 0
	v_lshl_add_u64 v[176:177], v[164:165], 0, s[40:41]
	v_add_f32_e32 v122, v122, v130
	v_add_f32_e32 v123, v123, v131
	v_add_f32_e32 v124, v124, v132
	v_add_f32_e32 v125, v125, v133
	v_add_f32_e32 v126, v126, v134
	v_add_f32_e32 v127, v127, v135
	v_add_f32_e32 v128, v128, v136
	v_add_f32_e32 v129, v129, v137
	v_mul_f32_e32 v122, 0xbfb8aa3b, v122
	v_mul_f32_e32 v123, 0xbfb8aa3b, v123
	v_mul_f32_e32 v124, 0xbfb8aa3b, v124
	v_mul_f32_e32 v125, 0xbfb8aa3b, v125
	v_mul_f32_e32 v126, 0xbfb8aa3b, v126
	v_mul_f32_e32 v127, 0xbfb8aa3b, v127
	v_mul_f32_e32 v128, 0xbfb8aa3b, v128
	v_mul_f32_e32 v129, 0xbfb8aa3b, v129
	v_exp_f32_e32 v122, v122
	v_exp_f32_e32 v123, v123
	v_exp_f32_e32 v124, v124
	v_exp_f32_e32 v125, v125
	v_exp_f32_e32 v126, v126
	v_exp_f32_e32 v127, v127
	v_exp_f32_e32 v128, v128
	v_exp_f32_e32 v129, v129
	v_add_f32_e32 v122, 1.0, v122
	v_add_f32_e32 v123, 1.0, v123
	v_add_f32_e32 v124, 1.0, v124
	v_add_f32_e32 v125, 1.0, v125
	v_add_f32_e32 v126, 1.0, v126
	v_add_f32_e32 v127, 1.0, v127
	v_add_f32_e32 v128, 1.0, v128
	v_add_f32_e32 v129, 1.0, v129
	v_rcp_f32_e32 v122, v122
	v_rcp_f32_e32 v123, v123
	v_rcp_f32_e32 v124, v124
	v_rcp_f32_e32 v125, v125
	v_rcp_f32_e32 v126, v126
	v_rcp_f32_e32 v127, v127
	v_rcp_f32_e32 v128, v128
	v_rcp_f32_e32 v129, v129
	v_lshlrev_b32_e32 v146, 16, v148
	v_and_b32_e32 v147, 0xffff0000, v148
	v_lshlrev_b32_e32 v180, 16, v152
	v_and_b32_e32 v181, 0xffff0000, v152
	v_pk_fma_f32 v[122:123], v[122:123], v[146:147], v[180:181]
	v_lshlrev_b32_e32 v190, 16, v149
	v_and_b32_e32 v191, 0xffff0000, v149
	v_lshlrev_b32_e32 v208, 16, v153
	v_and_b32_e32 v209, 0xffff0000, v153
	v_pk_fma_f32 v[124:125], v[124:125], v[190:191], v[208:209]
	v_lshlrev_b32_e32 v146, 16, v150
	v_and_b32_e32 v147, 0xffff0000, v150
	v_lshlrev_b32_e32 v180, 16, v154
	v_and_b32_e32 v181, 0xffff0000, v154
	v_pk_fma_f32 v[126:127], v[126:127], v[146:147], v[180:181]
	v_lshlrev_b32_e32 v190, 16, v151
	v_and_b32_e32 v191, 0xffff0000, v151
	v_lshlrev_b32_e32 v208, 16, v155
	v_and_b32_e32 v209, 0xffff0000, v155
	v_pk_fma_f32 v[128:129], v[128:129], v[190:191], v[208:209]
	v_cvt_pk_bf16_f32 v148, v122, v123
	v_cvt_pk_bf16_f32 v149, v124, v125
	v_cvt_pk_bf16_f32 v150, v126, v127
	v_cvt_pk_bf16_f32 v151, v128, v129
	global_store_dwordx4 v[176:177], v[148:151], off
	v_add_f32_e32 v118, v118, v138
	v_add_f32_e32 v119, v119, v139
	v_add_f32_e32 v120, v120, v140
	v_add_f32_e32 v121, v121, v141
	v_add_f32_e32 v114, v114, v142
	v_add_f32_e32 v115, v115, v143
	v_add_f32_e32 v116, v116, v144
	v_add_f32_e32 v117, v117, v145
	v_mul_f32_e32 v118, 0xbfb8aa3b, v118
	v_mul_f32_e32 v119, 0xbfb8aa3b, v119
	v_mul_f32_e32 v120, 0xbfb8aa3b, v120
	v_mul_f32_e32 v121, 0xbfb8aa3b, v121
	v_mul_f32_e32 v114, 0xbfb8aa3b, v114
	v_mul_f32_e32 v115, 0xbfb8aa3b, v115
	v_mul_f32_e32 v116, 0xbfb8aa3b, v116
	v_mul_f32_e32 v117, 0xbfb8aa3b, v117
	v_exp_f32_e32 v118, v118
	v_exp_f32_e32 v119, v119
	v_exp_f32_e32 v120, v120
	v_exp_f32_e32 v121, v121
	v_exp_f32_e32 v114, v114
	v_exp_f32_e32 v115, v115
	v_exp_f32_e32 v116, v116
	v_exp_f32_e32 v117, v117
	v_add_f32_e32 v118, 1.0, v118
	v_add_f32_e32 v119, 1.0, v119
	v_add_f32_e32 v120, 1.0, v120
	v_add_f32_e32 v121, 1.0, v121
	v_add_f32_e32 v114, 1.0, v114
	v_add_f32_e32 v115, 1.0, v115
	v_add_f32_e32 v116, 1.0, v116
	v_add_f32_e32 v117, 1.0, v117
	v_rcp_f32_e32 v118, v118
	v_rcp_f32_e32 v119, v119
	v_rcp_f32_e32 v120, v120
	v_rcp_f32_e32 v121, v121
	v_rcp_f32_e32 v114, v114
	v_rcp_f32_e32 v115, v115
	v_rcp_f32_e32 v116, v116
	v_rcp_f32_e32 v117, v117
	v_lshlrev_b32_e32 v146, 16, v156
	v_and_b32_e32 v147, 0xffff0000, v156
	v_lshlrev_b32_e32 v180, 16, v160
	v_and_b32_e32 v181, 0xffff0000, v160
	v_pk_fma_f32 v[118:119], v[118:119], v[146:147], v[180:181]
	v_lshlrev_b32_e32 v190, 16, v157
	v_and_b32_e32 v191, 0xffff0000, v157
	v_lshlrev_b32_e32 v208, 16, v161
	v_and_b32_e32 v209, 0xffff0000, v161
	v_pk_fma_f32 v[120:121], v[120:121], v[190:191], v[208:209]
	v_lshlrev_b32_e32 v146, 16, v158
	v_and_b32_e32 v147, 0xffff0000, v158
	v_lshlrev_b32_e32 v180, 16, v162
	v_and_b32_e32 v181, 0xffff0000, v162
	v_pk_fma_f32 v[114:115], v[114:115], v[146:147], v[180:181]
	v_lshlrev_b32_e32 v190, 16, v159
	v_and_b32_e32 v191, 0xffff0000, v159
	v_lshlrev_b32_e32 v208, 16, v163
	v_and_b32_e32 v209, 0xffff0000, v163
	v_pk_fma_f32 v[116:117], v[116:117], v[190:191], v[208:209]
	v_cvt_pk_bf16_f32 v156, v118, v119
	v_cvt_pk_bf16_f32 v157, v120, v121
	v_cvt_pk_bf16_f32 v158, v114, v115
	v_cvt_pk_bf16_f32 v159, v116, v117
	global_store_dwordx4 v[176:177], v[156:159], off offset:64
	s_add_u32 s40, s44, 0x18000
	s_addc_u32 s41, s45, 0
	v_lshl_add_u64 v[146:147], v[164:165], 0, s[40:41]
	s_add_u32 s6, s34, 0x18000
	s_addc_u32 s7, s35, 0
	v_lshl_add_u64 v[180:181], v[164:165], 0, s[6:7]
	global_load_dwordx4 v[148:151], v[146:147], off
	global_load_dwordx4 v[152:155], v[180:181], off
	global_load_dwordx4 v[156:159], v[146:147], off offset:64
	global_load_dwordx4 v[160:163], v[180:181], off offset:64
	s_waitcnt vmcnt(10)
; #define GAS __attribute__((address_space(1)))
; DI unsigned pk2(float lo, float hi) { f32x2 v = {lo, hi}; bf16x2_t b = __builtin_convertvector(v, bf16x2_t); return __builtin_bit_cast(unsigned, b); }
; DI float fast_exp2(float x) { return __builtin_amdgcn_exp2f(x); }
; DI float fast_rcp(float x) { return __builtin_amdgcn_rcpf(x); }
;     DI void operator()(const f32x4 (&acc)[2][2][4][2], const Unit& u, int wr, int wc, int fr, int fq) const {
;     ...
;                     for (int bj = 0; bj < 2; ++bj) { brv[bj] = *(const GAS u32x4*)(BR + offb + bj * 32); mgv[bj] = (gi > 0) ? *(const GAS u32x4*)(MG + offb + bj * 32) : (u32x4){0, 0, 0, 0}; }
; #pragma unroll
;                     for (int bj = 0; bj < 2; ++bj) { const size_t off = offb + bj * 32; const u32x4 br = brv[bj], mg = mgv[bj];
;                         f32x4 x0 = acc[ai][bj][m][0] + bb[bj][0], x1 = acc[ai][bj][m][1] + bb[bj][1]; float v[8];
;                         const float bv[8] = {__uint_as_float(br.x << 16), __uint_as_float(br.x & 0xffff0000u), __uint_as_float(br.y << 16), __uint_as_float(br.y & 0xffff0000u),
;                                              __uint_as_float(br.z << 16), __uint_as_float(br.z & 0xffff0000u), __uint_as_float(br.w << 16), __uint_as_float(br.w & 0xffff0000u)};
; #pragma unroll
;                         for (int j = 0; j < 4; ++j) { v[j] = fast_rcp(1.0f + fast_exp2(-x0[j] * LOG2E)) * bv[j]; v[4 + j] = fast_rcp(1.0f + fast_exp2(-x1[j] * LOG2E)) * bv[4 + j]; }
;                         v[0] += __uint_as_float(mg.x << 16); v[1] += __uint_as_float(mg.x & 0xffff0000u); v[2] += __uint_as_float(mg.y << 16); v[3] += __uint_as_float(mg.y & 0xffff0000u);
;                         v[4] += __uint_as_float(mg.z << 16); v[5] += __uint_as_float(mg.z & 0xffff0000u); v[6] += __uint_as_float(mg.w << 16); v[7] += __uint_as_float(mg.w & 0xffff0000u);
;                         u32x4 w; w.x = pk2(v[0], v[1]); w.y = pk2(v[2], v[3]); w.z = pk2(v[4], v[5]); w.w = pk2(v[6], v[7]);
;                         if (gi < 3) *(GAS u32x4*)(MG + off) = w; else *(GAS u32x4*)(BR + off) = w; } }
	s_add_u32 s40, s0, 0x8000
	s_addc_u32 s41, s1, 0
	v_lshl_add_u64 v[176:177], v[164:165], 0, s[40:41]
	v_add_f32_e32 v110, v110, v130
	v_add_f32_e32 v111, v111, v131
	v_add_f32_e32 v112, v112, v132
	v_add_f32_e32 v113, v113, v133
	v_add_f32_e32 v106, v106, v134
	v_add_f32_e32 v107, v107, v135
	v_add_f32_e32 v108, v108, v136
	v_add_f32_e32 v109, v109, v137
	v_mul_f32_e32 v110, 0xbfb8aa3b, v110
	v_mul_f32_e32 v111, 0xbfb8aa3b, v111
	v_mul_f32_e32 v112, 0xbfb8aa3b, v112
	v_mul_f32_e32 v113, 0xbfb8aa3b, v113
	v_mul_f32_e32 v106, 0xbfb8aa3b, v106
	v_mul_f32_e32 v107, 0xbfb8aa3b, v107
	v_mul_f32_e32 v108, 0xbfb8aa3b, v108
	v_mul_f32_e32 v109, 0xbfb8aa3b, v109
	v_exp_f32_e32 v110, v110
	v_exp_f32_e32 v111, v111
	v_exp_f32_e32 v112, v112
	v_exp_f32_e32 v113, v113
	v_exp_f32_e32 v106, v106
	v_exp_f32_e32 v107, v107
	v_exp_f32_e32 v108, v108
	v_exp_f32_e32 v109, v109
	v_add_f32_e32 v110, 1.0, v110
	v_add_f32_e32 v111, 1.0, v111
	v_add_f32_e32 v112, 1.0, v112
	v_add_f32_e32 v113, 1.0, v113
	v_add_f32_e32 v106, 1.0, v106
	v_add_f32_e32 v107, 1.0, v107
	v_add_f32_e32 v108, 1.0, v108
	v_add_f32_e32 v109, 1.0, v109
	v_rcp_f32_e32 v110, v110
	v_rcp_f32_e32 v111, v111
	v_rcp_f32_e32 v112, v112
	v_rcp_f32_e32 v113, v113
	v_rcp_f32_e32 v106, v106
	v_rcp_f32_e32 v107, v107
	v_rcp_f32_e32 v108, v108
	v_rcp_f32_e32 v109, v109
	v_lshlrev_b32_e32 v146, 16, v236
	v_and_b32_e32 v147, 0xffff0000, v236
	v_lshlrev_b32_e32 v180, 16, v240
	v_and_b32_e32 v181, 0xffff0000, v240
	v_pk_fma_f32 v[110:111], v[110:111], v[146:147], v[180:181]
	v_lshlrev_b32_e32 v190, 16, v237
	v_and_b32_e32 v191, 0xffff0000, v237
	v_lshlrev_b32_e32 v208, 16, v241
	v_and_b32_e32 v209, 0xffff0000, v241
	v_pk_fma_f32 v[112:113], v[112:113], v[190:191], v[208:209]
	v_lshlrev_b32_e32 v146, 16, v238
	v_and_b32_e32 v147, 0xffff0000, v238
	v_lshlrev_b32_e32 v180, 16, v242
	v_and_b32_e32 v181, 0xffff0000, v242
	v_pk_fma_f32 v[106:107], v[106:107], v[146:147], v[180:181]
	v_lshlrev_b32_e32 v190, 16, v239
	v_and_b32_e32 v191, 0xffff0000, v239
	v_lshlrev_b32_e32 v208, 16, v243
	v_and_b32_e32 v209, 0xffff0000, v243
	v_pk_fma_f32 v[108:109], v[108:109], v[190:191], v[208:209]
	v_cvt_pk_bf16_f32 v236, v110, v111
	v_cvt_pk_bf16_f32 v237, v112, v113
	v_cvt_pk_bf16_f32 v238, v106, v107
	v_cvt_pk_bf16_f32 v239, v108, v109
	global_store_dwordx4 v[176:177], v[236:239], off
	v_add_f32_e32 v102, v102, v138
	v_add_f32_e32 v103, v103, v139
	v_add_f32_e32 v104, v104, v140
	v_add_f32_e32 v105, v105, v141
	v_add_f32_e32 v98, v98, v142
	v_add_f32_e32 v99, v99, v143
	v_add_f32_e32 v100, v100, v144
	v_add_f32_e32 v101, v101, v145
	v_mul_f32_e32 v102, 0xbfb8aa3b, v102
	v_mul_f32_e32 v103, 0xbfb8aa3b, v103
	v_mul_f32_e32 v104, 0xbfb8aa3b, v104
	v_mul_f32_e32 v105, 0xbfb8aa3b, v105
	v_mul_f32_e32 v98, 0xbfb8aa3b, v98
	v_mul_f32_e32 v99, 0xbfb8aa3b, v99
	v_mul_f32_e32 v100, 0xbfb8aa3b, v100
	v_mul_f32_e32 v101, 0xbfb8aa3b, v101
	v_exp_f32_e32 v102, v102
	v_exp_f32_e32 v103, v103
	v_exp_f32_e32 v104, v104
	v_exp_f32_e32 v105, v105
	v_exp_f32_e32 v98, v98
	v_exp_f32_e32 v99, v99
	v_exp_f32_e32 v100, v100
	v_exp_f32_e32 v101, v101
	v_add_f32_e32 v102, 1.0, v102
	v_add_f32_e32 v103, 1.0, v103
	v_add_f32_e32 v104, 1.0, v104
	v_add_f32_e32 v105, 1.0, v105
	v_add_f32_e32 v98, 1.0, v98
	v_add_f32_e32 v99, 1.0, v99
	v_add_f32_e32 v100, 1.0, v100
	v_add_f32_e32 v101, 1.0, v101
	v_rcp_f32_e32 v102, v102
	v_rcp_f32_e32 v103, v103
	v_rcp_f32_e32 v104, v104
	v_rcp_f32_e32 v105, v105
	v_rcp_f32_e32 v98, v98
	v_rcp_f32_e32 v99, v99
	v_rcp_f32_e32 v100, v100
	v_rcp_f32_e32 v101, v101
	v_lshlrev_b32_e32 v146, 16, v244
	v_and_b32_e32 v147, 0xffff0000, v244
	v_lshlrev_b32_e32 v180, 16, v248
	v_and_b32_e32 v181, 0xffff0000, v248
	v_pk_fma_f32 v[102:103], v[102:103], v[146:147], v[180:181]
	v_lshlrev_b32_e32 v190, 16, v245
	v_and_b32_e32 v191, 0xffff0000, v245
	v_lshlrev_b32_e32 v208, 16, v249
	v_and_b32_e32 v209, 0xffff0000, v249
	v_pk_fma_f32 v[104:105], v[104:105], v[190:191], v[208:209]
	v_lshlrev_b32_e32 v146, 16, v246
	v_and_b32_e32 v147, 0xffff0000, v246
	v_lshlrev_b32_e32 v180, 16, v250
	v_and_b32_e32 v181, 0xffff0000, v250
	v_pk_fma_f32 v[98:99], v[98:99], v[146:147], v[180:181]
	v_lshlrev_b32_e32 v190, 16, v247
	v_and_b32_e32 v191, 0xffff0000, v247
	v_lshlrev_b32_e32 v208, 16, v251
	v_and_b32_e32 v209, 0xffff0000, v251
	v_pk_fma_f32 v[100:101], v[100:101], v[190:191], v[208:209]
	v_cvt_pk_bf16_f32 v244, v102, v103
	v_cvt_pk_bf16_f32 v245, v104, v105
	v_cvt_pk_bf16_f32 v246, v98, v99
	v_cvt_pk_bf16_f32 v247, v100, v101
	global_store_dwordx4 v[176:177], v[244:247], off offset:64
	s_add_u32 s40, s44, 0x40000
	s_addc_u32 s41, s45, 0
	v_lshl_add_u64 v[146:147], v[164:165], 0, s[40:41]
	s_add_u32 s6, s34, 0x40000
	s_addc_u32 s7, s35, 0
	v_lshl_add_u64 v[180:181], v[164:165], 0, s[6:7]
	global_load_dwordx4 v[236:239], v[146:147], off
	global_load_dwordx4 v[240:243], v[180:181], off
	global_load_dwordx4 v[244:247], v[146:147], off offset:64
	global_load_dwordx4 v[248:251], v[180:181], off offset:64
	s_waitcnt vmcnt(12)
; #define GAS __attribute__((address_space(1)))
; DI unsigned pk2(float lo, float hi) { f32x2 v = {lo, hi}; bf16x2_t b = __builtin_convertvector(v, bf16x2_t); return __builtin_bit_cast(unsigned, b); }
; DI float fast_exp2(float x) { return __builtin_amdgcn_exp2f(x); }
; DI float fast_rcp(float x) { return __builtin_amdgcn_rcpf(x); }
;     DI void operator()(const f32x4 (&acc)[2][2][4][2], const Unit& u, int wr, int wc, int fr, int fq) const {
;     ...
;                     for (int bj = 0; bj < 2; ++bj) { brv[bj] = *(const GAS u32x4*)(BR + offb + bj * 32); mgv[bj] = (gi > 0) ? *(const GAS u32x4*)(MG + offb + bj * 32) : (u32x4){0, 0, 0, 0}; }
; #pragma unroll
;                     for (int bj = 0; bj < 2; ++bj) { const size_t off = offb + bj * 32; const u32x4 br = brv[bj], mg = mgv[bj];
;                         f32x4 x0 = acc[ai][bj][m][0] + bb[bj][0], x1 = acc[ai][bj][m][1] + bb[bj][1]; float v[8];
;                         const float bv[8] = {__uint_as_float(br.x << 16), __uint_as_float(br.x & 0xffff0000u), __uint_as_float(br.y << 16), __uint_as_float(br.y & 0xffff0000u),
;                                              __uint_as_float(br.z << 16), __uint_as_float(br.z & 0xffff0000u), __uint_as_float(br.w << 16), __uint_as_float(br.w & 0xffff0000u)};
; #pragma unroll
;                         for (int j = 0; j < 4; ++j) { v[j] = fast_rcp(1.0f + fast_exp2(-x0[j] * LOG2E)) * bv[j]; v[4 + j] = fast_rcp(1.0f + fast_exp2(-x1[j] * LOG2E)) * bv[4 + j]; }
;                         v[0] += __uint_as_float(mg.x << 16); v[1] += __uint_as_float(mg.x & 0xffff0000u); v[2] += __uint_as_float(mg.y << 16); v[3] += __uint_as_float(mg.y & 0xffff0000u);
;                         v[4] += __uint_as_float(mg.z << 16); v[5] += __uint_as_float(mg.z & 0xffff0000u); v[6] += __uint_as_float(mg.w << 16); v[7] += __uint_as_float(mg.w & 0xffff0000u);
;                         u32x4 w; w.x = pk2(v[0], v[1]); w.y = pk2(v[2], v[3]); w.z = pk2(v[4], v[5]); w.w = pk2(v[6], v[7]);
;                         if (gi < 3) *(GAS u32x4*)(MG + off) = w; else *(GAS u32x4*)(BR + off) = w; } }
	s_add_u32 s40, s0, 0x10000
	s_addc_u32 s41, s1, 0
	v_lshl_add_u64 v[176:177], v[164:165], 0, s[40:41]
	v_add_f32_e32 v94, v94, v130
	v_add_f32_e32 v95, v95, v131
	v_add_f32_e32 v96, v96, v132
	v_add_f32_e32 v97, v97, v133
	v_add_f32_e32 v90, v90, v134
	v_add_f32_e32 v91, v91, v135
	v_add_f32_e32 v92, v92, v136
	v_add_f32_e32 v93, v93, v137
	v_mul_f32_e32 v94, 0xbfb8aa3b, v94
	v_mul_f32_e32 v95, 0xbfb8aa3b, v95
	v_mul_f32_e32 v96, 0xbfb8aa3b, v96
	v_mul_f32_e32 v97, 0xbfb8aa3b, v97
	v_mul_f32_e32 v90, 0xbfb8aa3b, v90
	v_mul_f32_e32 v91, 0xbfb8aa3b, v91
	v_mul_f32_e32 v92, 0xbfb8aa3b, v92
	v_mul_f32_e32 v93, 0xbfb8aa3b, v93
	v_exp_f32_e32 v94, v94
	v_exp_f32_e32 v95, v95
	v_exp_f32_e32 v96, v96
	v_exp_f32_e32 v97, v97
	v_exp_f32_e32 v90, v90
	v_exp_f32_e32 v91, v91
	v_exp_f32_e32 v92, v92
	v_exp_f32_e32 v93, v93
	v_add_f32_e32 v94, 1.0, v94
	v_add_f32_e32 v95, 1.0, v95
	v_add_f32_e32 v96, 1.0, v96
	v_add_f32_e32 v97, 1.0, v97
	v_add_f32_e32 v90, 1.0, v90
	v_add_f32_e32 v91, 1.0, v91
	v_add_f32_e32 v92, 1.0, v92
	v_add_f32_e32 v93, 1.0, v93
	v_rcp_f32_e32 v94, v94
	v_rcp_f32_e32 v95, v95
	v_rcp_f32_e32 v96, v96
	v_rcp_f32_e32 v97, v97
	v_rcp_f32_e32 v90, v90
	v_rcp_f32_e32 v91, v91
	v_rcp_f32_e32 v92, v92
	v_rcp_f32_e32 v93, v93
	v_lshlrev_b32_e32 v146, 16, v194
	v_and_b32_e32 v147, 0xffff0000, v194
	v_lshlrev_b32_e32 v180, 16, v200
	v_and_b32_e32 v181, 0xffff0000, v200
	v_pk_fma_f32 v[94:95], v[94:95], v[146:147], v[180:181]
	v_lshlrev_b32_e32 v190, 16, v195
	v_and_b32_e32 v191, 0xffff0000, v195
	v_lshlrev_b32_e32 v208, 16, v201
	v_and_b32_e32 v209, 0xffff0000, v201
	v_pk_fma_f32 v[96:97], v[96:97], v[190:191], v[208:209]
	v_lshlrev_b32_e32 v146, 16, v196
	v_and_b32_e32 v147, 0xffff0000, v196
	v_lshlrev_b32_e32 v180, 16, v202
	v_and_b32_e32 v181, 0xffff0000, v202
	v_pk_fma_f32 v[90:91], v[90:91], v[146:147], v[180:181]
	v_lshlrev_b32_e32 v190, 16, v197
	v_and_b32_e32 v191, 0xffff0000, v197
	v_lshlrev_b32_e32 v208, 16, v203
	v_and_b32_e32 v209, 0xffff0000, v203
	v_pk_fma_f32 v[92:93], v[92:93], v[190:191], v[208:209]
	v_cvt_pk_bf16_f32 v194, v94, v95
	v_cvt_pk_bf16_f32 v195, v96, v97
	v_cvt_pk_bf16_f32 v196, v90, v91
	v_cvt_pk_bf16_f32 v197, v92, v93
	global_store_dwordx4 v[176:177], v[194:197], off
	v_add_f32_e32 v86, v86, v138
	v_add_f32_e32 v87, v87, v139
	v_add_f32_e32 v88, v88, v140
	v_add_f32_e32 v89, v89, v141
	v_add_f32_e32 v82, v82, v142
	v_add_f32_e32 v83, v83, v143
	v_add_f32_e32 v84, v84, v144
	v_add_f32_e32 v85, v85, v145
	v_mul_f32_e32 v86, 0xbfb8aa3b, v86
	v_mul_f32_e32 v87, 0xbfb8aa3b, v87
	v_mul_f32_e32 v88, 0xbfb8aa3b, v88
	v_mul_f32_e32 v89, 0xbfb8aa3b, v89
	v_mul_f32_e32 v82, 0xbfb8aa3b, v82
	v_mul_f32_e32 v83, 0xbfb8aa3b, v83
	v_mul_f32_e32 v84, 0xbfb8aa3b, v84
	v_mul_f32_e32 v85, 0xbfb8aa3b, v85
	v_exp_f32_e32 v86, v86
	v_exp_f32_e32 v87, v87
	v_exp_f32_e32 v88, v88
	v_exp_f32_e32 v89, v89
	v_exp_f32_e32 v82, v82
	v_exp_f32_e32 v83, v83
	v_exp_f32_e32 v84, v84
	v_exp_f32_e32 v85, v85
	v_add_f32_e32 v86, 1.0, v86
	v_add_f32_e32 v87, 1.0, v87
	v_add_f32_e32 v88, 1.0, v88
	v_add_f32_e32 v89, 1.0, v89
	v_add_f32_e32 v82, 1.0, v82
	v_add_f32_e32 v83, 1.0, v83
	v_add_f32_e32 v84, 1.0, v84
	v_add_f32_e32 v85, 1.0, v85
	v_rcp_f32_e32 v86, v86
	v_rcp_f32_e32 v87, v87
	v_rcp_f32_e32 v88, v88
	v_rcp_f32_e32 v89, v89
	v_rcp_f32_e32 v82, v82
	v_rcp_f32_e32 v83, v83
	v_rcp_f32_e32 v84, v84
	v_rcp_f32_e32 v85, v85
	v_lshlrev_b32_e32 v146, 16, v204
	v_and_b32_e32 v147, 0xffff0000, v204
	v_lshlrev_b32_e32 v180, 16, v230
	v_and_b32_e32 v181, 0xffff0000, v230
	v_pk_fma_f32 v[86:87], v[86:87], v[146:147], v[180:181]
	v_lshlrev_b32_e32 v190, 16, v205
	v_and_b32_e32 v191, 0xffff0000, v205
	v_lshlrev_b32_e32 v208, 16, v231
	v_and_b32_e32 v209, 0xffff0000, v231
	v_pk_fma_f32 v[88:89], v[88:89], v[190:191], v[208:209]
	v_lshlrev_b32_e32 v146, 16, v206
	v_and_b32_e32 v147, 0xffff0000, v206
	v_lshlrev_b32_e32 v180, 16, v232
	v_and_b32_e32 v181, 0xffff0000, v232
	v_pk_fma_f32 v[82:83], v[82:83], v[146:147], v[180:181]
	v_lshlrev_b32_e32 v190, 16, v207
	v_and_b32_e32 v191, 0xffff0000, v207
	v_lshlrev_b32_e32 v208, 16, v233
	v_and_b32_e32 v209, 0xffff0000, v233
	v_pk_fma_f32 v[84:85], v[84:85], v[190:191], v[208:209]
	v_cvt_pk_bf16_f32 v204, v86, v87
	v_cvt_pk_bf16_f32 v205, v88, v89
	v_cvt_pk_bf16_f32 v206, v82, v83
	v_cvt_pk_bf16_f32 v207, v84, v85
	global_store_dwordx4 v[176:177], v[204:207], off offset:64
	s_add_u32 s40, s44, 0x48000
	s_addc_u32 s41, s45, 0
	v_lshl_add_u64 v[146:147], v[164:165], 0, s[40:41]
	s_add_u32 s6, s34, 0x48000
	s_addc_u32 s7, s35, 0
	v_lshl_add_u64 v[180:181], v[164:165], 0, s[6:7]
	global_load_dwordx4 v[194:197], v[146:147], off
	global_load_dwordx4 v[200:203], v[180:181], off
	global_load_dwordx4 v[204:207], v[146:147], off offset:64
	global_load_dwordx4 v[230:233], v[180:181], off offset:64
	s_waitcnt vmcnt(12)
; #define GAS __attribute__((address_space(1)))
; DI unsigned pk2(float lo, float hi) { f32x2 v = {lo, hi}; bf16x2_t b = __builtin_convertvector(v, bf16x2_t); return __builtin_bit_cast(unsigned, b); }
; DI float fast_exp2(float x) { return __builtin_amdgcn_exp2f(x); }
; DI float fast_rcp(float x) { return __builtin_amdgcn_rcpf(x); }
;     DI void operator()(const f32x4 (&acc)[2][2][4][2], const Unit& u, int wr, int wc, int fr, int fq) const {
;     ...
;                     for (int bj = 0; bj < 2; ++bj) { brv[bj] = *(const GAS u32x4*)(BR + offb + bj * 32); mgv[bj] = (gi > 0) ? *(const GAS u32x4*)(MG + offb + bj * 32) : (u32x4){0, 0, 0, 0}; }
; #pragma unroll
;                     for (int bj = 0; bj < 2; ++bj) { const size_t off = offb + bj * 32; const u32x4 br = brv[bj], mg = mgv[bj];
;                         f32x4 x0 = acc[ai][bj][m][0] + bb[bj][0], x1 = acc[ai][bj][m][1] + bb[bj][1]; float v[8];
;                         const float bv[8] = {__uint_as_float(br.x << 16), __uint_as_float(br.x & 0xffff0000u), __uint_as_float(br.y << 16), __uint_as_float(br.y & 0xffff0000u),
;                                              __uint_as_float(br.z << 16), __uint_as_float(br.z & 0xffff0000u), __uint_as_float(br.w << 16), __uint_as_float(br.w & 0xffff0000u)};
; #pragma unroll
;                         for (int j = 0; j < 4; ++j) { v[j] = fast_rcp(1.0f + fast_exp2(-x0[j] * LOG2E)) * bv[j]; v[4 + j] = fast_rcp(1.0f + fast_exp2(-x1[j] * LOG2E)) * bv[4 + j]; }
;                         v[0] += __uint_as_float(mg.x << 16); v[1] += __uint_as_float(mg.x & 0xffff0000u); v[2] += __uint_as_float(mg.y << 16); v[3] += __uint_as_float(mg.y & 0xffff0000u);
;                         v[4] += __uint_as_float(mg.z << 16); v[5] += __uint_as_float(mg.z & 0xffff0000u); v[6] += __uint_as_float(mg.w << 16); v[7] += __uint_as_float(mg.w & 0xffff0000u);
;                         u32x4 w; w.x = pk2(v[0], v[1]); w.y = pk2(v[2], v[3]); w.z = pk2(v[4], v[5]); w.w = pk2(v[6], v[7]);
;                         if (gi < 3) *(GAS u32x4*)(MG + off) = w; else *(GAS u32x4*)(BR + off) = w; } }
	s_add_u32 s40, s0, 0x18000
	s_addc_u32 s41, s1, 0
	v_lshl_add_u64 v[176:177], v[164:165], 0, s[40:41]
	v_add_f32_e32 v78, v78, v130
	v_add_f32_e32 v79, v79, v131
	v_add_f32_e32 v80, v80, v132
	v_add_f32_e32 v81, v81, v133
	v_add_f32_e32 v74, v74, v134
	v_add_f32_e32 v75, v75, v135
	v_add_f32_e32 v76, v76, v136
	v_add_f32_e32 v77, v77, v137
	v_mul_f32_e32 v78, 0xbfb8aa3b, v78
	v_mul_f32_e32 v79, 0xbfb8aa3b, v79
	v_mul_f32_e32 v80, 0xbfb8aa3b, v80
	v_mul_f32_e32 v81, 0xbfb8aa3b, v81
	v_mul_f32_e32 v74, 0xbfb8aa3b, v74
	v_mul_f32_e32 v75, 0xbfb8aa3b, v75
	v_mul_f32_e32 v76, 0xbfb8aa3b, v76
	v_mul_f32_e32 v77, 0xbfb8aa3b, v77
	v_exp_f32_e32 v78, v78
	v_exp_f32_e32 v79, v79
	v_exp_f32_e32 v80, v80
	v_exp_f32_e32 v81, v81
	v_exp_f32_e32 v74, v74
	v_exp_f32_e32 v75, v75
	v_exp_f32_e32 v76, v76
	v_exp_f32_e32 v77, v77
	v_add_f32_e32 v78, 1.0, v78
	v_add_f32_e32 v79, 1.0, v79
	v_add_f32_e32 v80, 1.0, v80
	v_add_f32_e32 v81, 1.0, v81
	v_add_f32_e32 v74, 1.0, v74
	v_add_f32_e32 v75, 1.0, v75
	v_add_f32_e32 v76, 1.0, v76
	v_add_f32_e32 v77, 1.0, v77
	v_rcp_f32_e32 v78, v78
	v_rcp_f32_e32 v79, v79
	v_rcp_f32_e32 v80, v80
	v_rcp_f32_e32 v81, v81
	v_rcp_f32_e32 v74, v74
	v_rcp_f32_e32 v75, v75
	v_rcp_f32_e32 v76, v76
	v_rcp_f32_e32 v77, v77
	v_lshlrev_b32_e32 v146, 16, v148
	v_and_b32_e32 v147, 0xffff0000, v148
	v_lshlrev_b32_e32 v180, 16, v152
	v_and_b32_e32 v181, 0xffff0000, v152
	v_pk_fma_f32 v[78:79], v[78:79], v[146:147], v[180:181]
	v_lshlrev_b32_e32 v190, 16, v149
	v_and_b32_e32 v191, 0xffff0000, v149
	v_lshlrev_b32_e32 v208, 16, v153
	v_and_b32_e32 v209, 0xffff0000, v153
	v_pk_fma_f32 v[80:81], v[80:81], v[190:191], v[208:209]
	v_lshlrev_b32_e32 v146, 16, v150
	v_and_b32_e32 v147, 0xffff0000, v150
	v_lshlrev_b32_e32 v180, 16, v154
	v_and_b32_e32 v181, 0xffff0000, v154
	v_pk_fma_f32 v[74:75], v[74:75], v[146:147], v[180:181]
	v_lshlrev_b32_e32 v190, 16, v151
	v_and_b32_e32 v191, 0xffff0000, v151
	v_lshlrev_b32_e32 v208, 16, v155
	v_and_b32_e32 v209, 0xffff0000, v155
	v_pk_fma_f32 v[76:77], v[76:77], v[190:191], v[208:209]
	v_cvt_pk_bf16_f32 v148, v78, v79
	v_cvt_pk_bf16_f32 v149, v80, v81
	v_cvt_pk_bf16_f32 v150, v74, v75
	v_cvt_pk_bf16_f32 v151, v76, v77
	global_store_dwordx4 v[176:177], v[148:151], off
	v_add_f32_e32 v70, v70, v138
	v_add_f32_e32 v71, v71, v139
	v_add_f32_e32 v72, v72, v140
	v_add_f32_e32 v73, v73, v141
	v_add_f32_e32 v66, v66, v142
	v_add_f32_e32 v67, v67, v143
	v_add_f32_e32 v68, v68, v144
	v_add_f32_e32 v69, v69, v145
	v_mul_f32_e32 v70, 0xbfb8aa3b, v70
	v_mul_f32_e32 v71, 0xbfb8aa3b, v71
	v_mul_f32_e32 v72, 0xbfb8aa3b, v72
	v_mul_f32_e32 v73, 0xbfb8aa3b, v73
	v_mul_f32_e32 v66, 0xbfb8aa3b, v66
	v_mul_f32_e32 v67, 0xbfb8aa3b, v67
	v_mul_f32_e32 v68, 0xbfb8aa3b, v68
	v_mul_f32_e32 v69, 0xbfb8aa3b, v69
	v_exp_f32_e32 v70, v70
	v_exp_f32_e32 v71, v71
	v_exp_f32_e32 v72, v72
	v_exp_f32_e32 v73, v73
	v_exp_f32_e32 v66, v66
	v_exp_f32_e32 v67, v67
	v_exp_f32_e32 v68, v68
	v_exp_f32_e32 v69, v69
	v_add_f32_e32 v70, 1.0, v70
	v_add_f32_e32 v71, 1.0, v71
	v_add_f32_e32 v72, 1.0, v72
	v_add_f32_e32 v73, 1.0, v73
	v_add_f32_e32 v66, 1.0, v66
	v_add_f32_e32 v67, 1.0, v67
	v_add_f32_e32 v68, 1.0, v68
	v_add_f32_e32 v69, 1.0, v69
	v_rcp_f32_e32 v70, v70
	v_rcp_f32_e32 v71, v71
	v_rcp_f32_e32 v72, v72
	v_rcp_f32_e32 v73, v73
	v_rcp_f32_e32 v66, v66
	v_rcp_f32_e32 v67, v67
	v_rcp_f32_e32 v68, v68
	v_rcp_f32_e32 v69, v69
	v_lshlrev_b32_e32 v146, 16, v156
	v_and_b32_e32 v147, 0xffff0000, v156
	v_lshlrev_b32_e32 v180, 16, v160
	v_and_b32_e32 v181, 0xffff0000, v160
	v_pk_fma_f32 v[70:71], v[70:71], v[146:147], v[180:181]
	v_lshlrev_b32_e32 v190, 16, v157
	v_and_b32_e32 v191, 0xffff0000, v157
	v_lshlrev_b32_e32 v208, 16, v161
	v_and_b32_e32 v209, 0xffff0000, v161
	v_pk_fma_f32 v[72:73], v[72:73], v[190:191], v[208:209]
	v_lshlrev_b32_e32 v146, 16, v158
	v_and_b32_e32 v147, 0xffff0000, v158
	v_lshlrev_b32_e32 v180, 16, v162
	v_and_b32_e32 v181, 0xffff0000, v162
	v_pk_fma_f32 v[66:67], v[66:67], v[146:147], v[180:181]
	v_lshlrev_b32_e32 v190, 16, v159
	v_and_b32_e32 v191, 0xffff0000, v159
	v_lshlrev_b32_e32 v208, 16, v163
	v_and_b32_e32 v209, 0xffff0000, v163
	v_pk_fma_f32 v[68:69], v[68:69], v[190:191], v[208:209]
	v_cvt_pk_bf16_f32 v156, v70, v71
	v_cvt_pk_bf16_f32 v157, v72, v73
	v_cvt_pk_bf16_f32 v158, v66, v67
	v_cvt_pk_bf16_f32 v159, v68, v69
	global_store_dwordx4 v[176:177], v[156:159], off offset:64
	s_add_u32 s40, s44, 0x50000
	s_addc_u32 s41, s45, 0
	v_lshl_add_u64 v[146:147], v[164:165], 0, s[40:41]
	s_add_u32 s6, s34, 0x50000
	s_addc_u32 s7, s35, 0
	v_lshl_add_u64 v[180:181], v[164:165], 0, s[6:7]
	global_load_dwordx4 v[148:151], v[146:147], off
	global_load_dwordx4 v[152:155], v[180:181], off
	global_load_dwordx4 v[156:159], v[146:147], off offset:64
	global_load_dwordx4 v[160:163], v[180:181], off offset:64
	s_waitcnt vmcnt(12)
; #define GAS __attribute__((address_space(1)))
; DI unsigned pk2(float lo, float hi) { f32x2 v = {lo, hi}; bf16x2_t b = __builtin_convertvector(v, bf16x2_t); return __builtin_bit_cast(unsigned, b); }
; DI float fast_exp2(float x) { return __builtin_amdgcn_exp2f(x); }
; DI float fast_rcp(float x) { return __builtin_amdgcn_rcpf(x); }
;     DI void operator()(const f32x4 (&acc)[2][2][4][2], const Unit& u, int wr, int wc, int fr, int fq) const {
;     ...
;                     for (int bj = 0; bj < 2; ++bj) { brv[bj] = *(const GAS u32x4*)(BR + offb + bj * 32); mgv[bj] = (gi > 0) ? *(const GAS u32x4*)(MG + offb + bj * 32) : (u32x4){0, 0, 0, 0}; }
; #pragma unroll
;                     for (int bj = 0; bj < 2; ++bj) { const size_t off = offb + bj * 32; const u32x4 br = brv[bj], mg = mgv[bj];
;                         f32x4 x0 = acc[ai][bj][m][0] + bb[bj][0], x1 = acc[ai][bj][m][1] + bb[bj][1]; float v[8];
;                         const float bv[8] = {__uint_as_float(br.x << 16), __uint_as_float(br.x & 0xffff0000u), __uint_as_float(br.y << 16), __uint_as_float(br.y & 0xffff0000u),
;                                              __uint_as_float(br.z << 16), __uint_as_float(br.z & 0xffff0000u), __uint_as_float(br.w << 16), __uint_as_float(br.w & 0xffff0000u)};
; #pragma unroll
;                         for (int j = 0; j < 4; ++j) { v[j] = fast_rcp(1.0f + fast_exp2(-x0[j] * LOG2E)) * bv[j]; v[4 + j] = fast_rcp(1.0f + fast_exp2(-x1[j] * LOG2E)) * bv[4 + j]; }
;                         v[0] += __uint_as_float(mg.x << 16); v[1] += __uint_as_float(mg.x & 0xffff0000u); v[2] += __uint_as_float(mg.y << 16); v[3] += __uint_as_float(mg.y & 0xffff0000u);
;                         v[4] += __uint_as_float(mg.z << 16); v[5] += __uint_as_float(mg.z & 0xffff0000u); v[6] += __uint_as_float(mg.w << 16); v[7] += __uint_as_float(mg.w & 0xffff0000u);
;                         u32x4 w; w.x = pk2(v[0], v[1]); w.y = pk2(v[2], v[3]); w.z = pk2(v[4], v[5]); w.w = pk2(v[6], v[7]);
;                         if (gi < 3) *(GAS u32x4*)(MG + off) = w; else *(GAS u32x4*)(BR + off) = w; } }
	s_add_u32 s40, s0, 0x40000
	s_addc_u32 s41, s1, 0
	v_lshl_add_u64 v[176:177], v[164:165], 0, s[40:41]
	v_add_f32_e32 v62, v62, v130
	v_add_f32_e32 v63, v63, v131
	v_add_f32_e32 v64, v64, v132
	v_add_f32_e32 v65, v65, v133
	v_add_f32_e32 v58, v58, v134
	v_add_f32_e32 v59, v59, v135
	v_add_f32_e32 v60, v60, v136
	v_add_f32_e32 v61, v61, v137
	v_mul_f32_e32 v62, 0xbfb8aa3b, v62
	v_mul_f32_e32 v63, 0xbfb8aa3b, v63
	v_mul_f32_e32 v64, 0xbfb8aa3b, v64
	v_mul_f32_e32 v65, 0xbfb8aa3b, v65
	v_mul_f32_e32 v58, 0xbfb8aa3b, v58
	v_mul_f32_e32 v59, 0xbfb8aa3b, v59
	v_mul_f32_e32 v60, 0xbfb8aa3b, v60
	v_mul_f32_e32 v61, 0xbfb8aa3b, v61
	v_exp_f32_e32 v62, v62
	v_exp_f32_e32 v63, v63
	v_exp_f32_e32 v64, v64
	v_exp_f32_e32 v65, v65
	v_exp_f32_e32 v58, v58
	v_exp_f32_e32 v59, v59
	v_exp_f32_e32 v60, v60
	v_exp_f32_e32 v61, v61
	v_add_f32_e32 v62, 1.0, v62
	v_add_f32_e32 v63, 1.0, v63
	v_add_f32_e32 v64, 1.0, v64
	v_add_f32_e32 v65, 1.0, v65
	v_add_f32_e32 v58, 1.0, v58
	v_add_f32_e32 v59, 1.0, v59
	v_add_f32_e32 v60, 1.0, v60
	v_add_f32_e32 v61, 1.0, v61
	v_rcp_f32_e32 v62, v62
	v_rcp_f32_e32 v63, v63
	v_rcp_f32_e32 v64, v64
	v_rcp_f32_e32 v65, v65
	v_rcp_f32_e32 v58, v58
	v_rcp_f32_e32 v59, v59
	v_rcp_f32_e32 v60, v60
	v_rcp_f32_e32 v61, v61
	v_lshlrev_b32_e32 v146, 16, v236
	v_and_b32_e32 v147, 0xffff0000, v236
	v_lshlrev_b32_e32 v180, 16, v240
	v_and_b32_e32 v181, 0xffff0000, v240
	v_pk_fma_f32 v[62:63], v[62:63], v[146:147], v[180:181]
	v_lshlrev_b32_e32 v190, 16, v237
	v_and_b32_e32 v191, 0xffff0000, v237
	v_lshlrev_b32_e32 v208, 16, v241
	v_and_b32_e32 v209, 0xffff0000, v241
	v_pk_fma_f32 v[64:65], v[64:65], v[190:191], v[208:209]
	v_lshlrev_b32_e32 v146, 16, v238
	v_and_b32_e32 v147, 0xffff0000, v238
	v_lshlrev_b32_e32 v180, 16, v242
	v_and_b32_e32 v181, 0xffff0000, v242
	v_pk_fma_f32 v[58:59], v[58:59], v[146:147], v[180:181]
	v_lshlrev_b32_e32 v190, 16, v239
	v_and_b32_e32 v191, 0xffff0000, v239
	v_lshlrev_b32_e32 v208, 16, v243
	v_and_b32_e32 v209, 0xffff0000, v243
	v_pk_fma_f32 v[60:61], v[60:61], v[190:191], v[208:209]
	v_cvt_pk_bf16_f32 v236, v62, v63
	v_cvt_pk_bf16_f32 v237, v64, v65
	v_cvt_pk_bf16_f32 v238, v58, v59
	v_cvt_pk_bf16_f32 v239, v60, v61
	global_store_dwordx4 v[176:177], v[236:239], off
	v_add_f32_e32 v54, v54, v138
	v_add_f32_e32 v55, v55, v139
	v_add_f32_e32 v56, v56, v140
	v_add_f32_e32 v57, v57, v141
	v_add_f32_e32 v50, v50, v142
	v_add_f32_e32 v51, v51, v143
	v_add_f32_e32 v52, v52, v144
	v_add_f32_e32 v53, v53, v145
	v_mul_f32_e32 v54, 0xbfb8aa3b, v54
	v_mul_f32_e32 v55, 0xbfb8aa3b, v55
	v_mul_f32_e32 v56, 0xbfb8aa3b, v56
	v_mul_f32_e32 v57, 0xbfb8aa3b, v57
	v_mul_f32_e32 v50, 0xbfb8aa3b, v50
	v_mul_f32_e32 v51, 0xbfb8aa3b, v51
	v_mul_f32_e32 v52, 0xbfb8aa3b, v52
	v_mul_f32_e32 v53, 0xbfb8aa3b, v53
	v_exp_f32_e32 v54, v54
	v_exp_f32_e32 v55, v55
	v_exp_f32_e32 v56, v56
	v_exp_f32_e32 v57, v57
	v_exp_f32_e32 v50, v50
	v_exp_f32_e32 v51, v51
	v_exp_f32_e32 v52, v52
	v_exp_f32_e32 v53, v53
	v_add_f32_e32 v54, 1.0, v54
	v_add_f32_e32 v55, 1.0, v55
	v_add_f32_e32 v56, 1.0, v56
	v_add_f32_e32 v57, 1.0, v57
	v_add_f32_e32 v50, 1.0, v50
	v_add_f32_e32 v51, 1.0, v51
	v_add_f32_e32 v52, 1.0, v52
	v_add_f32_e32 v53, 1.0, v53
	v_rcp_f32_e32 v54, v54
	v_rcp_f32_e32 v55, v55
	v_rcp_f32_e32 v56, v56
	v_rcp_f32_e32 v57, v57
	v_rcp_f32_e32 v50, v50
	v_rcp_f32_e32 v51, v51
	v_rcp_f32_e32 v52, v52
	v_rcp_f32_e32 v53, v53
	v_lshlrev_b32_e32 v146, 16, v244
	v_and_b32_e32 v147, 0xffff0000, v244
	v_lshlrev_b32_e32 v180, 16, v248
	v_and_b32_e32 v181, 0xffff0000, v248
	v_pk_fma_f32 v[54:55], v[54:55], v[146:147], v[180:181]
	v_lshlrev_b32_e32 v190, 16, v245
	v_and_b32_e32 v191, 0xffff0000, v245
	v_lshlrev_b32_e32 v208, 16, v249
	v_and_b32_e32 v209, 0xffff0000, v249
	v_pk_fma_f32 v[56:57], v[56:57], v[190:191], v[208:209]
	v_lshlrev_b32_e32 v146, 16, v246
	v_and_b32_e32 v147, 0xffff0000, v246
	v_lshlrev_b32_e32 v180, 16, v250
	v_and_b32_e32 v181, 0xffff0000, v250
	v_pk_fma_f32 v[50:51], v[50:51], v[146:147], v[180:181]
	v_lshlrev_b32_e32 v190, 16, v247
	v_and_b32_e32 v191, 0xffff0000, v247
	v_lshlrev_b32_e32 v208, 16, v251
	v_and_b32_e32 v209, 0xffff0000, v251
	v_pk_fma_f32 v[52:53], v[52:53], v[190:191], v[208:209]
	v_cvt_pk_bf16_f32 v244, v54, v55
	v_cvt_pk_bf16_f32 v245, v56, v57
	v_cvt_pk_bf16_f32 v246, v50, v51
	v_cvt_pk_bf16_f32 v247, v52, v53
	global_store_dwordx4 v[176:177], v[244:247], off offset:64
	s_add_u32 s40, s44, 0x58000
	s_addc_u32 s41, s45, 0
	v_lshl_add_u64 v[146:147], v[164:165], 0, s[40:41]
	s_add_u32 s6, s34, 0x58000
	s_addc_u32 s7, s35, 0
	v_lshl_add_u64 v[180:181], v[164:165], 0, s[6:7]
	global_load_dwordx4 v[236:239], v[146:147], off
	global_load_dwordx4 v[240:243], v[180:181], off
	global_load_dwordx4 v[244:247], v[146:147], off offset:64
	global_load_dwordx4 v[248:251], v[180:181], off offset:64
	s_waitcnt vmcnt(12)
; #define GAS __attribute__((address_space(1)))
; DI unsigned pk2(float lo, float hi) { f32x2 v = {lo, hi}; bf16x2_t b = __builtin_convertvector(v, bf16x2_t); return __builtin_bit_cast(unsigned, b); }
; DI float fast_exp2(float x) { return __builtin_amdgcn_exp2f(x); }
; DI float fast_rcp(float x) { return __builtin_amdgcn_rcpf(x); }
;     DI void operator()(const f32x4 (&acc)[2][2][4][2], const Unit& u, int wr, int wc, int fr, int fq) const {
;     ...
;                     for (int bj = 0; bj < 2; ++bj) { brv[bj] = *(const GAS u32x4*)(BR + offb + bj * 32); mgv[bj] = (gi > 0) ? *(const GAS u32x4*)(MG + offb + bj * 32) : (u32x4){0, 0, 0, 0}; }
; #pragma unroll
;                     for (int bj = 0; bj < 2; ++bj) { const size_t off = offb + bj * 32; const u32x4 br = brv[bj], mg = mgv[bj];
;                         f32x4 x0 = acc[ai][bj][m][0] + bb[bj][0], x1 = acc[ai][bj][m][1] + bb[bj][1]; float v[8];
;                         const float bv[8] = {__uint_as_float(br.x << 16), __uint_as_float(br.x & 0xffff0000u), __uint_as_float(br.y << 16), __uint_as_float(br.y & 0xffff0000u),
;                                              __uint_as_float(br.z << 16), __uint_as_float(br.z & 0xffff0000u), __uint_as_float(br.w << 16), __uint_as_float(br.w & 0xffff0000u)};
; #pragma unroll
;                         for (int j = 0; j < 4; ++j) { v[j] = fast_rcp(1.0f + fast_exp2(-x0[j] * LOG2E)) * bv[j]; v[4 + j] = fast_rcp(1.0f + fast_exp2(-x1[j] * LOG2E)) * bv[4 + j]; }
;                         v[0] += __uint_as_float(mg.x << 16); v[1] += __uint_as_float(mg.x & 0xffff0000u); v[2] += __uint_as_float(mg.y << 16); v[3] += __uint_as_float(mg.y & 0xffff0000u);
;                         v[4] += __uint_as_float(mg.z << 16); v[5] += __uint_as_float(mg.z & 0xffff0000u); v[6] += __uint_as_float(mg.w << 16); v[7] += __uint_as_float(mg.w & 0xffff0000u);
;                         u32x4 w; w.x = pk2(v[0], v[1]); w.y = pk2(v[2], v[3]); w.z = pk2(v[4], v[5]); w.w = pk2(v[6], v[7]);
;                         if (gi < 3) *(GAS u32x4*)(MG + off) = w; else *(GAS u32x4*)(BR + off) = w; } }
	s_add_u32 s40, s0, 0x48000
	s_addc_u32 s41, s1, 0
	v_lshl_add_u64 v[176:177], v[164:165], 0, s[40:41]
	v_add_f32_e32 v46, v46, v130
	v_add_f32_e32 v47, v47, v131
	v_add_f32_e32 v48, v48, v132
	v_add_f32_e32 v49, v49, v133
	v_add_f32_e32 v42, v42, v134
	v_add_f32_e32 v43, v43, v135
	v_add_f32_e32 v44, v44, v136
	v_add_f32_e32 v45, v45, v137
	v_mul_f32_e32 v46, 0xbfb8aa3b, v46
	v_mul_f32_e32 v47, 0xbfb8aa3b, v47
	v_mul_f32_e32 v48, 0xbfb8aa3b, v48
	v_mul_f32_e32 v49, 0xbfb8aa3b, v49
	v_mul_f32_e32 v42, 0xbfb8aa3b, v42
	v_mul_f32_e32 v43, 0xbfb8aa3b, v43
	v_mul_f32_e32 v44, 0xbfb8aa3b, v44
	v_mul_f32_e32 v45, 0xbfb8aa3b, v45
	v_exp_f32_e32 v46, v46
	v_exp_f32_e32 v47, v47
	v_exp_f32_e32 v48, v48
	v_exp_f32_e32 v49, v49
	v_exp_f32_e32 v42, v42
	v_exp_f32_e32 v43, v43
	v_exp_f32_e32 v44, v44
	v_exp_f32_e32 v45, v45
	v_add_f32_e32 v46, 1.0, v46
	v_add_f32_e32 v47, 1.0, v47
	v_add_f32_e32 v48, 1.0, v48
	v_add_f32_e32 v49, 1.0, v49
	v_add_f32_e32 v42, 1.0, v42
	v_add_f32_e32 v43, 1.0, v43
	v_add_f32_e32 v44, 1.0, v44
	v_add_f32_e32 v45, 1.0, v45
	v_rcp_f32_e32 v46, v46
	v_rcp_f32_e32 v47, v47
	v_rcp_f32_e32 v48, v48
	v_rcp_f32_e32 v49, v49
	v_rcp_f32_e32 v42, v42
	v_rcp_f32_e32 v43, v43
	v_rcp_f32_e32 v44, v44
	v_rcp_f32_e32 v45, v45
	v_lshlrev_b32_e32 v146, 16, v194
	v_and_b32_e32 v147, 0xffff0000, v194
	v_lshlrev_b32_e32 v180, 16, v200
	v_and_b32_e32 v181, 0xffff0000, v200
	v_pk_fma_f32 v[46:47], v[46:47], v[146:147], v[180:181]
	v_lshlrev_b32_e32 v190, 16, v195
	v_and_b32_e32 v191, 0xffff0000, v195
	v_lshlrev_b32_e32 v208, 16, v201
	v_and_b32_e32 v209, 0xffff0000, v201
	v_pk_fma_f32 v[48:49], v[48:49], v[190:191], v[208:209]
	v_lshlrev_b32_e32 v146, 16, v196
	v_and_b32_e32 v147, 0xffff0000, v196
	v_lshlrev_b32_e32 v180, 16, v202
	v_and_b32_e32 v181, 0xffff0000, v202
	v_pk_fma_f32 v[42:43], v[42:43], v[146:147], v[180:181]
	v_lshlrev_b32_e32 v190, 16, v197
	v_and_b32_e32 v191, 0xffff0000, v197
	v_lshlrev_b32_e32 v208, 16, v203
	v_and_b32_e32 v209, 0xffff0000, v203
	v_pk_fma_f32 v[44:45], v[44:45], v[190:191], v[208:209]
	v_cvt_pk_bf16_f32 v194, v46, v47
	v_cvt_pk_bf16_f32 v195, v48, v49
	v_cvt_pk_bf16_f32 v196, v42, v43
	v_cvt_pk_bf16_f32 v197, v44, v45
	global_store_dwordx4 v[176:177], v[194:197], off
	v_add_f32_e32 v38, v38, v138
	v_add_f32_e32 v39, v39, v139
	v_add_f32_e32 v40, v40, v140
	v_add_f32_e32 v41, v41, v141
	v_add_f32_e32 v34, v34, v142
	v_add_f32_e32 v35, v35, v143
	v_add_f32_e32 v36, v36, v144
	v_add_f32_e32 v37, v37, v145
	v_mul_f32_e32 v38, 0xbfb8aa3b, v38
	v_mul_f32_e32 v39, 0xbfb8aa3b, v39
	v_mul_f32_e32 v40, 0xbfb8aa3b, v40
	v_mul_f32_e32 v41, 0xbfb8aa3b, v41
	v_mul_f32_e32 v34, 0xbfb8aa3b, v34
	v_mul_f32_e32 v35, 0xbfb8aa3b, v35
	v_mul_f32_e32 v36, 0xbfb8aa3b, v36
	v_mul_f32_e32 v37, 0xbfb8aa3b, v37
	v_exp_f32_e32 v38, v38
	v_exp_f32_e32 v39, v39
	v_exp_f32_e32 v40, v40
	v_exp_f32_e32 v41, v41
	v_exp_f32_e32 v34, v34
	v_exp_f32_e32 v35, v35
	v_exp_f32_e32 v36, v36
	v_exp_f32_e32 v37, v37
	v_add_f32_e32 v38, 1.0, v38
	v_add_f32_e32 v39, 1.0, v39
	v_add_f32_e32 v40, 1.0, v40
	v_add_f32_e32 v41, 1.0, v41
	v_add_f32_e32 v34, 1.0, v34
	v_add_f32_e32 v35, 1.0, v35
	v_add_f32_e32 v36, 1.0, v36
	v_add_f32_e32 v37, 1.0, v37
	v_rcp_f32_e32 v38, v38
	v_rcp_f32_e32 v39, v39
	v_rcp_f32_e32 v40, v40
	v_rcp_f32_e32 v41, v41
	v_rcp_f32_e32 v34, v34
	v_rcp_f32_e32 v35, v35
	v_rcp_f32_e32 v36, v36
	v_rcp_f32_e32 v37, v37
	v_lshlrev_b32_e32 v146, 16, v204
	v_and_b32_e32 v147, 0xffff0000, v204
	v_lshlrev_b32_e32 v180, 16, v230
	v_and_b32_e32 v181, 0xffff0000, v230
	v_pk_fma_f32 v[38:39], v[38:39], v[146:147], v[180:181]
	v_lshlrev_b32_e32 v190, 16, v205
	v_and_b32_e32 v191, 0xffff0000, v205
	v_lshlrev_b32_e32 v208, 16, v231
	v_and_b32_e32 v209, 0xffff0000, v231
	v_pk_fma_f32 v[40:41], v[40:41], v[190:191], v[208:209]
	v_lshlrev_b32_e32 v146, 16, v206
	v_and_b32_e32 v147, 0xffff0000, v206
	v_lshlrev_b32_e32 v180, 16, v232
	v_and_b32_e32 v181, 0xffff0000, v232
	v_pk_fma_f32 v[34:35], v[34:35], v[146:147], v[180:181]
	v_lshlrev_b32_e32 v190, 16, v207
	v_and_b32_e32 v191, 0xffff0000, v207
	v_lshlrev_b32_e32 v208, 16, v233
	v_and_b32_e32 v209, 0xffff0000, v233
	v_pk_fma_f32 v[36:37], v[36:37], v[190:191], v[208:209]
	v_cvt_pk_bf16_f32 v204, v38, v39
	v_cvt_pk_bf16_f32 v205, v40, v41
	v_cvt_pk_bf16_f32 v206, v34, v35
	v_cvt_pk_bf16_f32 v207, v36, v37
	global_store_dwordx4 v[176:177], v[204:207], off offset:64
	s_waitcnt vmcnt(8)
; #define GAS __attribute__((address_space(1)))
; DI unsigned pk2(float lo, float hi) { f32x2 v = {lo, hi}; bf16x2_t b = __builtin_convertvector(v, bf16x2_t); return __builtin_bit_cast(unsigned, b); }
; DI float fast_exp2(float x) { return __builtin_amdgcn_exp2f(x); }
; DI float fast_rcp(float x) { return __builtin_amdgcn_rcpf(x); }
;     DI void operator()(const f32x4 (&acc)[2][2][4][2], const Unit& u, int wr, int wc, int fr, int fq) const {
;     ...
;                     for (int bj = 0; bj < 2; ++bj) { brv[bj] = *(const GAS u32x4*)(BR + offb + bj * 32); mgv[bj] = (gi > 0) ? *(const GAS u32x4*)(MG + offb + bj * 32) : (u32x4){0, 0, 0, 0}; }
; #pragma unroll
;                     for (int bj = 0; bj < 2; ++bj) { const size_t off = offb + bj * 32; const u32x4 br = brv[bj], mg = mgv[bj];
;                         f32x4 x0 = acc[ai][bj][m][0] + bb[bj][0], x1 = acc[ai][bj][m][1] + bb[bj][1]; float v[8];
;                         const float bv[8] = {__uint_as_float(br.x << 16), __uint_as_float(br.x & 0xffff0000u), __uint_as_float(br.y << 16), __uint_as_float(br.y & 0xffff0000u),
;                                              __uint_as_float(br.z << 16), __uint_as_float(br.z & 0xffff0000u), __uint_as_float(br.w << 16), __uint_as_float(br.w & 0xffff0000u)};
; #pragma unroll
;                         for (int j = 0; j < 4; ++j) { v[j] = fast_rcp(1.0f + fast_exp2(-x0[j] * LOG2E)) * bv[j]; v[4 + j] = fast_rcp(1.0f + fast_exp2(-x1[j] * LOG2E)) * bv[4 + j]; }
;                         v[0] += __uint_as_float(mg.x << 16); v[1] += __uint_as_float(mg.x & 0xffff0000u); v[2] += __uint_as_float(mg.y << 16); v[3] += __uint_as_float(mg.y & 0xffff0000u);
;                         v[4] += __uint_as_float(mg.z << 16); v[5] += __uint_as_float(mg.z & 0xffff0000u); v[6] += __uint_as_float(mg.w << 16); v[7] += __uint_as_float(mg.w & 0xffff0000u);
;                         u32x4 w; w.x = pk2(v[0], v[1]); w.y = pk2(v[2], v[3]); w.z = pk2(v[4], v[5]); w.w = pk2(v[6], v[7]);
;                         if (gi < 3) *(GAS u32x4*)(MG + off) = w; else *(GAS u32x4*)(BR + off) = w; } }
	s_add_u32 s40, s0, 0x50000
	s_addc_u32 s41, s1, 0
	v_lshl_add_u64 v[176:177], v[164:165], 0, s[40:41]
	v_add_f32_e32 v30, v30, v130
	v_add_f32_e32 v31, v31, v131
	v_add_f32_e32 v32, v32, v132
	v_add_f32_e32 v33, v33, v133
	v_add_f32_e32 v26, v26, v134
	v_add_f32_e32 v27, v27, v135
	v_add_f32_e32 v28, v28, v136
	v_add_f32_e32 v29, v29, v137
	v_mul_f32_e32 v30, 0xbfb8aa3b, v30
	v_mul_f32_e32 v31, 0xbfb8aa3b, v31
	v_mul_f32_e32 v32, 0xbfb8aa3b, v32
	v_mul_f32_e32 v33, 0xbfb8aa3b, v33
	v_mul_f32_e32 v26, 0xbfb8aa3b, v26
	v_mul_f32_e32 v27, 0xbfb8aa3b, v27
	v_mul_f32_e32 v28, 0xbfb8aa3b, v28
	v_mul_f32_e32 v29, 0xbfb8aa3b, v29
	v_exp_f32_e32 v30, v30
	v_exp_f32_e32 v31, v31
	v_exp_f32_e32 v32, v32
	v_exp_f32_e32 v33, v33
	v_exp_f32_e32 v26, v26
	v_exp_f32_e32 v27, v27
	v_exp_f32_e32 v28, v28
	v_exp_f32_e32 v29, v29
	v_add_f32_e32 v30, 1.0, v30
	v_add_f32_e32 v31, 1.0, v31
	v_add_f32_e32 v32, 1.0, v32
	v_add_f32_e32 v33, 1.0, v33
	v_add_f32_e32 v26, 1.0, v26
	v_add_f32_e32 v27, 1.0, v27
	v_add_f32_e32 v28, 1.0, v28
	v_add_f32_e32 v29, 1.0, v29
	v_rcp_f32_e32 v30, v30
	v_rcp_f32_e32 v31, v31
	v_rcp_f32_e32 v32, v32
	v_rcp_f32_e32 v33, v33
	v_rcp_f32_e32 v26, v26
	v_rcp_f32_e32 v27, v27
	v_rcp_f32_e32 v28, v28
	v_rcp_f32_e32 v29, v29
	v_lshlrev_b32_e32 v146, 16, v148
	v_and_b32_e32 v147, 0xffff0000, v148
	v_lshlrev_b32_e32 v180, 16, v152
	v_and_b32_e32 v181, 0xffff0000, v152
	v_pk_fma_f32 v[30:31], v[30:31], v[146:147], v[180:181]
	v_lshlrev_b32_e32 v190, 16, v149
	v_and_b32_e32 v191, 0xffff0000, v149
	v_lshlrev_b32_e32 v208, 16, v153
	v_and_b32_e32 v209, 0xffff0000, v153
	v_pk_fma_f32 v[32:33], v[32:33], v[190:191], v[208:209]
	v_lshlrev_b32_e32 v146, 16, v150
	v_and_b32_e32 v147, 0xffff0000, v150
	v_lshlrev_b32_e32 v180, 16, v154
	v_and_b32_e32 v181, 0xffff0000, v154
	v_pk_fma_f32 v[26:27], v[26:27], v[146:147], v[180:181]
	v_lshlrev_b32_e32 v190, 16, v151
	v_and_b32_e32 v191, 0xffff0000, v151
	v_lshlrev_b32_e32 v208, 16, v155
	v_and_b32_e32 v209, 0xffff0000, v155
	v_pk_fma_f32 v[28:29], v[28:29], v[190:191], v[208:209]
	v_cvt_pk_bf16_f32 v148, v30, v31
	v_cvt_pk_bf16_f32 v149, v32, v33
	v_cvt_pk_bf16_f32 v150, v26, v27
	v_cvt_pk_bf16_f32 v151, v28, v29
	global_store_dwordx4 v[176:177], v[148:151], off
	v_add_f32_e32 v22, v22, v138
	v_add_f32_e32 v23, v23, v139
	v_add_f32_e32 v24, v24, v140
	v_add_f32_e32 v25, v25, v141
	v_add_f32_e32 v18, v18, v142
	v_add_f32_e32 v19, v19, v143
	v_add_f32_e32 v20, v20, v144
	v_add_f32_e32 v21, v21, v145
	v_mul_f32_e32 v22, 0xbfb8aa3b, v22
	v_mul_f32_e32 v23, 0xbfb8aa3b, v23
	v_mul_f32_e32 v24, 0xbfb8aa3b, v24
	v_mul_f32_e32 v25, 0xbfb8aa3b, v25
	v_mul_f32_e32 v18, 0xbfb8aa3b, v18
	v_mul_f32_e32 v19, 0xbfb8aa3b, v19
	v_mul_f32_e32 v20, 0xbfb8aa3b, v20
	v_mul_f32_e32 v21, 0xbfb8aa3b, v21
	v_exp_f32_e32 v22, v22
	v_exp_f32_e32 v23, v23
	v_exp_f32_e32 v24, v24
	v_exp_f32_e32 v25, v25
	v_exp_f32_e32 v18, v18
	v_exp_f32_e32 v19, v19
	v_exp_f32_e32 v20, v20
	v_exp_f32_e32 v21, v21
	v_add_f32_e32 v22, 1.0, v22
	v_add_f32_e32 v23, 1.0, v23
	v_add_f32_e32 v24, 1.0, v24
	v_add_f32_e32 v25, 1.0, v25
	v_add_f32_e32 v18, 1.0, v18
	v_add_f32_e32 v19, 1.0, v19
	v_add_f32_e32 v20, 1.0, v20
	v_add_f32_e32 v21, 1.0, v21
	v_rcp_f32_e32 v22, v22
	v_rcp_f32_e32 v23, v23
	v_rcp_f32_e32 v24, v24
	v_rcp_f32_e32 v25, v25
	v_rcp_f32_e32 v18, v18
	v_rcp_f32_e32 v19, v19
	v_rcp_f32_e32 v20, v20
	v_rcp_f32_e32 v21, v21
	v_lshlrev_b32_e32 v146, 16, v156
	v_and_b32_e32 v147, 0xffff0000, v156
	v_lshlrev_b32_e32 v180, 16, v160
	v_and_b32_e32 v181, 0xffff0000, v160
	v_pk_fma_f32 v[22:23], v[22:23], v[146:147], v[180:181]
	v_lshlrev_b32_e32 v190, 16, v157
	v_and_b32_e32 v191, 0xffff0000, v157
	v_lshlrev_b32_e32 v208, 16, v161
	v_and_b32_e32 v209, 0xffff0000, v161
	v_pk_fma_f32 v[24:25], v[24:25], v[190:191], v[208:209]
	v_lshlrev_b32_e32 v146, 16, v158
	v_and_b32_e32 v147, 0xffff0000, v158
	v_lshlrev_b32_e32 v180, 16, v162
	v_and_b32_e32 v181, 0xffff0000, v162
	v_pk_fma_f32 v[18:19], v[18:19], v[146:147], v[180:181]
	v_lshlrev_b32_e32 v190, 16, v159
	v_and_b32_e32 v191, 0xffff0000, v159
	v_lshlrev_b32_e32 v208, 16, v163
	v_and_b32_e32 v209, 0xffff0000, v163
	v_pk_fma_f32 v[20:21], v[20:21], v[190:191], v[208:209]
	v_cvt_pk_bf16_f32 v156, v22, v23
	v_cvt_pk_bf16_f32 v157, v24, v25
	v_cvt_pk_bf16_f32 v158, v18, v19
	v_cvt_pk_bf16_f32 v159, v20, v21
	global_store_dwordx4 v[176:177], v[156:159], off offset:64
	s_waitcnt vmcnt(4)
; #define GAS __attribute__((address_space(1)))
; DI unsigned pk2(float lo, float hi) { f32x2 v = {lo, hi}; bf16x2_t b = __builtin_convertvector(v, bf16x2_t); return __builtin_bit_cast(unsigned, b); }
; DI float fast_exp2(float x) { return __builtin_amdgcn_exp2f(x); }
; DI float fast_rcp(float x) { return __builtin_amdgcn_rcpf(x); }
;     DI void operator()(const f32x4 (&acc)[2][2][4][2], const Unit& u, int wr, int wc, int fr, int fq) const {
;     ...
;                     for (int bj = 0; bj < 2; ++bj) { brv[bj] = *(const GAS u32x4*)(BR + offb + bj * 32); mgv[bj] = (gi > 0) ? *(const GAS u32x4*)(MG + offb + bj * 32) : (u32x4){0, 0, 0, 0}; }
; #pragma unroll
;                     for (int bj = 0; bj < 2; ++bj) { const size_t off = offb + bj * 32; const u32x4 br = brv[bj], mg = mgv[bj];
;                         f32x4 x0 = acc[ai][bj][m][0] + bb[bj][0], x1 = acc[ai][bj][m][1] + bb[bj][1]; float v[8];
;                         const float bv[8] = {__uint_as_float(br.x << 16), __uint_as_float(br.x & 0xffff0000u), __uint_as_float(br.y << 16), __uint_as_float(br.y & 0xffff0000u),
;                                              __uint_as_float(br.z << 16), __uint_as_float(br.z & 0xffff0000u), __uint_as_float(br.w << 16), __uint_as_float(br.w & 0xffff0000u)};
; #pragma unroll
;                         for (int j = 0; j < 4; ++j) { v[j] = fast_rcp(1.0f + fast_exp2(-x0[j] * LOG2E)) * bv[j]; v[4 + j] = fast_rcp(1.0f + fast_exp2(-x1[j] * LOG2E)) * bv[4 + j]; }
;                         v[0] += __uint_as_float(mg.x << 16); v[1] += __uint_as_float(mg.x & 0xffff0000u); v[2] += __uint_as_float(mg.y << 16); v[3] += __uint_as_float(mg.y & 0xffff0000u);
;                         v[4] += __uint_as_float(mg.z << 16); v[5] += __uint_as_float(mg.z & 0xffff0000u); v[6] += __uint_as_float(mg.w << 16); v[7] += __uint_as_float(mg.w & 0xffff0000u);
;                         u32x4 w; w.x = pk2(v[0], v[1]); w.y = pk2(v[2], v[3]); w.z = pk2(v[4], v[5]); w.w = pk2(v[6], v[7]);
;                         if (gi < 3) *(GAS u32x4*)(MG + off) = w; else *(GAS u32x4*)(BR + off) = w; } }
	s_add_u32 s40, s0, 0x58000
	s_addc_u32 s41, s1, 0
	v_lshl_add_u64 v[176:177], v[164:165], 0, s[40:41]
	v_add_f32_e32 v14, v14, v130
	v_add_f32_e32 v15, v15, v131
	v_add_f32_e32 v16, v16, v132
	v_add_f32_e32 v17, v17, v133
	v_add_f32_e32 v10, v10, v134
	v_add_f32_e32 v11, v11, v135
	v_add_f32_e32 v12, v12, v136
	v_add_f32_e32 v13, v13, v137
	v_mul_f32_e32 v14, 0xbfb8aa3b, v14
	v_mul_f32_e32 v15, 0xbfb8aa3b, v15
	v_mul_f32_e32 v16, 0xbfb8aa3b, v16
	v_mul_f32_e32 v17, 0xbfb8aa3b, v17
	v_mul_f32_e32 v10, 0xbfb8aa3b, v10
	v_mul_f32_e32 v11, 0xbfb8aa3b, v11
	v_mul_f32_e32 v12, 0xbfb8aa3b, v12
	v_mul_f32_e32 v13, 0xbfb8aa3b, v13
	v_exp_f32_e32 v14, v14
	v_exp_f32_e32 v15, v15
	v_exp_f32_e32 v16, v16
	v_exp_f32_e32 v17, v17
	v_exp_f32_e32 v10, v10
	v_exp_f32_e32 v11, v11
	v_exp_f32_e32 v12, v12
	v_exp_f32_e32 v13, v13
	v_add_f32_e32 v14, 1.0, v14
	v_add_f32_e32 v15, 1.0, v15
	v_add_f32_e32 v16, 1.0, v16
	v_add_f32_e32 v17, 1.0, v17
	v_add_f32_e32 v10, 1.0, v10
	v_add_f32_e32 v11, 1.0, v11
	v_add_f32_e32 v12, 1.0, v12
	v_add_f32_e32 v13, 1.0, v13
	v_rcp_f32_e32 v14, v14
	v_rcp_f32_e32 v15, v15
	v_rcp_f32_e32 v16, v16
	v_rcp_f32_e32 v17, v17
	v_rcp_f32_e32 v10, v10
	v_rcp_f32_e32 v11, v11
	v_rcp_f32_e32 v12, v12
	v_rcp_f32_e32 v13, v13
	v_lshlrev_b32_e32 v146, 16, v236
	v_and_b32_e32 v147, 0xffff0000, v236
	v_lshlrev_b32_e32 v180, 16, v240
	v_and_b32_e32 v181, 0xffff0000, v240
	v_pk_fma_f32 v[14:15], v[14:15], v[146:147], v[180:181]
	v_lshlrev_b32_e32 v190, 16, v237
	v_and_b32_e32 v191, 0xffff0000, v237
	v_lshlrev_b32_e32 v208, 16, v241
	v_and_b32_e32 v209, 0xffff0000, v241
	v_pk_fma_f32 v[16:17], v[16:17], v[190:191], v[208:209]
	v_lshlrev_b32_e32 v146, 16, v238
	v_and_b32_e32 v147, 0xffff0000, v238
	v_lshlrev_b32_e32 v180, 16, v242
	v_and_b32_e32 v181, 0xffff0000, v242
	v_pk_fma_f32 v[10:11], v[10:11], v[146:147], v[180:181]
	v_lshlrev_b32_e32 v190, 16, v239
	v_and_b32_e32 v191, 0xffff0000, v239
	v_lshlrev_b32_e32 v208, 16, v243
	v_and_b32_e32 v209, 0xffff0000, v243
	v_pk_fma_f32 v[12:13], v[12:13], v[190:191], v[208:209]
	v_cvt_pk_bf16_f32 v236, v14, v15
	v_cvt_pk_bf16_f32 v237, v16, v17
	v_cvt_pk_bf16_f32 v238, v10, v11
	v_cvt_pk_bf16_f32 v239, v12, v13
	global_store_dwordx4 v[176:177], v[236:239], off
	v_add_f32_e32 v6, v6, v138
	v_add_f32_e32 v7, v7, v139
	v_add_f32_e32 v8, v8, v140
	v_add_f32_e32 v9, v9, v141
	v_add_f32_e32 v2, v2, v142
	v_add_f32_e32 v3, v3, v143
	v_add_f32_e32 v4, v4, v144
	v_add_f32_e32 v5, v5, v145
	v_mul_f32_e32 v6, 0xbfb8aa3b, v6
	v_mul_f32_e32 v7, 0xbfb8aa3b, v7
	v_mul_f32_e32 v8, 0xbfb8aa3b, v8
	v_mul_f32_e32 v9, 0xbfb8aa3b, v9
	v_mul_f32_e32 v2, 0xbfb8aa3b, v2
	v_mul_f32_e32 v3, 0xbfb8aa3b, v3
	v_mul_f32_e32 v4, 0xbfb8aa3b, v4
	v_mul_f32_e32 v5, 0xbfb8aa3b, v5
	v_exp_f32_e32 v6, v6
	v_exp_f32_e32 v7, v7
	v_exp_f32_e32 v8, v8
	v_exp_f32_e32 v9, v9
	v_exp_f32_e32 v2, v2
	v_exp_f32_e32 v3, v3
	v_exp_f32_e32 v4, v4
	v_exp_f32_e32 v5, v5
	v_add_f32_e32 v6, 1.0, v6
	v_add_f32_e32 v7, 1.0, v7
	v_add_f32_e32 v8, 1.0, v8
	v_add_f32_e32 v9, 1.0, v9
	v_add_f32_e32 v2, 1.0, v2
	v_add_f32_e32 v3, 1.0, v3
	v_add_f32_e32 v4, 1.0, v4
	v_add_f32_e32 v5, 1.0, v5
	v_rcp_f32_e32 v6, v6
	v_rcp_f32_e32 v7, v7
	v_rcp_f32_e32 v8, v8
	v_rcp_f32_e32 v9, v9
	v_rcp_f32_e32 v2, v2
	v_rcp_f32_e32 v3, v3
	v_rcp_f32_e32 v4, v4
	v_rcp_f32_e32 v5, v5
	v_lshlrev_b32_e32 v146, 16, v244
	v_and_b32_e32 v147, 0xffff0000, v244
	v_lshlrev_b32_e32 v180, 16, v248
	v_and_b32_e32 v181, 0xffff0000, v248
	v_pk_fma_f32 v[6:7], v[6:7], v[146:147], v[180:181]
	v_lshlrev_b32_e32 v190, 16, v245
	v_and_b32_e32 v191, 0xffff0000, v245
	v_lshlrev_b32_e32 v208, 16, v249
	v_and_b32_e32 v209, 0xffff0000, v249
	v_pk_fma_f32 v[8:9], v[8:9], v[190:191], v[208:209]
	v_lshlrev_b32_e32 v146, 16, v246
	v_and_b32_e32 v147, 0xffff0000, v246
	v_lshlrev_b32_e32 v180, 16, v250
	v_and_b32_e32 v181, 0xffff0000, v250
	v_pk_fma_f32 v[2:3], v[2:3], v[146:147], v[180:181]
	v_lshlrev_b32_e32 v190, 16, v247
	v_and_b32_e32 v191, 0xffff0000, v247
	v_lshlrev_b32_e32 v208, 16, v251
	v_and_b32_e32 v209, 0xffff0000, v251
	v_pk_fma_f32 v[4:5], v[4:5], v[190:191], v[208:209]
	v_cvt_pk_bf16_f32 v244, v6, v7
	v_cvt_pk_bf16_f32 v245, v8, v9
	v_cvt_pk_bf16_f32 v246, v2, v3
	v_cvt_pk_bf16_f32 v247, v4, v5
	global_store_dwordx4 v[176:177], v[244:247], off offset:64
	s_branch .LBB0_847
; #define GAS __attribute__((address_space(1)))
; DI float fast_exp2(float x) { return __builtin_amdgcn_exp2f(x); }
;     DI void operator()(const f32x4 (&acc)[2][2][4][2], const Unit& u, int wr, int wc, int fr, int fq) const {
;     ...
;             const int col0 = u.pn * BM + wc * 64 + 8 * fq;
;             f32x4 bb[2][2];
; #pragma unroll
;             for (int bj = 0; bj < 2; ++bj) { bb[bj][0] = *(const GAS f32x4*)(bias + col0 + bj * 32); bb[bj][1] = *(const GAS f32x4*)(bias + col0 + bj * 32 + 4); }
; #pragma unroll
;             for (int ai = 0; ai < 2; ++ai)
; #pragma unroll
;                 for (int m = 0; m < 4; ++m) { const size_t offb = (size_t)(row0 + ai * HALF + m * 16) * DM + col0;
;                     u32x4 brv[2], mgv[2];
; #pragma unroll
;                     for (int bj = 0; bj < 2; ++bj) { brv[bj] = *(const GAS u32x4*)(BR + offb + bj * 32); mgv[bj] = (gi > 0) ? *(const GAS u32x4*)(MG + offb + bj * 32) : (u32x4){0, 0, 0, 0}; }
; #pragma unroll
;                     for (int bj = 0; bj < 2; ++bj) { const size_t off = offb + bj * 32; const u32x4 br = brv[bj], mg = mgv[bj];
;                         f32x4 x0 = acc[ai][bj][m][0] + bb[bj][0], x1 = acc[ai][bj][m][1] + bb[bj][1]; float v[8];
;                         const float bv[8] = {__uint_as_float(br.x << 16), __uint_as_float(br.x & 0xffff0000u), __uint_as_float(br.y << 16), __uint_as_float(br.y & 0xffff0000u),
;                                              __uint_as_float(br.z << 16), __uint_as_float(br.z & 0xffff0000u), __uint_as_float(br.w << 16), __uint_as_float(br.w & 0xffff0000u)};
; #pragma unroll
;                         for (int j = 0; j < 4; ++j) { v[j] = fast_rcp(1.0f + fast_exp2(-x0[j] * LOG2E)) * bv[j]; v[4 + j] = fast_rcp(1.0f + fast_exp2(-x1[j] * LOG2E)) * bv[4 + j]; }
;                         v[0] += __uint_as_float(mg.x << 16); v[1] += __uint_as_float(mg.x & 0xffff0000u); v[2] += __uint_as_float(mg.y << 16); v[3] += __uint_as_float(mg.y & 0xffff0000u);
;                         v[4] += __uint_as_float(mg.z << 16); v[5] += __uint_as_float(mg.z & 0xffff0000u); v[6] += __uint_as_float(mg.w << 16); v[7] += __uint_as_float(mg.w & 0xffff0000u);
;                         u32x4 w; w.x = pk2(v[0], v[1]); w.y = pk2(v[2], v[3]); w.z = pk2(v[4], v[5]); w.w = pk2(v[6], v[7]);
;                         if (gi < 3) *(GAS u32x4*)(MG + off) = w; else *(GAS u32x4*)(BR + off) = w; } }
.Lm3_nomg:
	v_ashrrev_i32_e32 v177, 31, v176
	v_mov_b32_e32 v130, s80
	v_mov_b32_e32 v131, s81
	v_ashrrev_i32_e32 v179, 31, v178
	v_lshlrev_b64 v[146:147], 10, v[176:177]
	v_lshl_add_u64 v[180:181], v[178:179], 2, v[130:131]
	v_lshl_add_u64 v[164:165], v[146:147], 0, v[178:179]
	global_load_dwordx4 v[130:133], v[180:181], off
	global_load_dwordx4 v[134:137], v[180:181], off offset:16
	global_load_dwordx4 v[138:141], v[180:181], off offset:128
	global_load_dwordx4 v[142:145], v[180:181], off offset:144
	v_lshlrev_b64 v[164:165], 1, v[164:165]
	s_cmp_lt_i32 s46, 3
	s_cselect_b32 s1, s35, s45
	s_cselect_b32 s0, s34, s44
	s_add_u32 s40, s44, 0x0
	s_addc_u32 s41, s45, 0
	v_lshl_add_u64 v[146:147], v[164:165], 0, s[40:41]
	global_load_dwordx4 v[148:151], v[146:147], off
	global_load_dwordx4 v[156:159], v[146:147], off offset:64
	s_add_u32 s40, s44, 0x8000
	s_addc_u32 s41, s45, 0
	v_lshl_add_u64 v[146:147], v[164:165], 0, s[40:41]
	global_load_dwordx4 v[236:239], v[146:147], off
	global_load_dwordx4 v[244:247], v[146:147], off offset:64
	s_add_u32 s40, s44, 0x10000
	s_addc_u32 s41, s45, 0
	v_lshl_add_u64 v[146:147], v[164:165], 0, s[40:41]
	global_load_dwordx4 v[194:197], v[146:147], off
	global_load_dwordx4 v[204:207], v[146:147], off offset:64
	s_waitcnt vmcnt(4)
	s_add_u32 s40, s0, 0x0
	s_addc_u32 s41, s1, 0
	v_lshl_add_u64 v[176:177], v[164:165], 0, s[40:41]
	v_add_f32_e32 v122, v122, v130
	v_add_f32_e32 v123, v123, v131
	v_add_f32_e32 v124, v124, v132
	v_add_f32_e32 v125, v125, v133
	v_add_f32_e32 v126, v126, v134
	v_add_f32_e32 v127, v127, v135
	v_add_f32_e32 v128, v128, v136
	v_add_f32_e32 v129, v129, v137
	v_mul_f32_e32 v122, 0xbfb8aa3b, v122
	v_mul_f32_e32 v123, 0xbfb8aa3b, v123
	v_mul_f32_e32 v124, 0xbfb8aa3b, v124
	v_mul_f32_e32 v125, 0xbfb8aa3b, v125
	v_mul_f32_e32 v126, 0xbfb8aa3b, v126
	v_mul_f32_e32 v127, 0xbfb8aa3b, v127
	v_mul_f32_e32 v128, 0xbfb8aa3b, v128
	v_mul_f32_e32 v129, 0xbfb8aa3b, v129
	v_exp_f32_e32 v122, v122
	v_exp_f32_e32 v123, v123
	v_exp_f32_e32 v124, v124
	v_exp_f32_e32 v125, v125
	v_exp_f32_e32 v126, v126
	v_exp_f32_e32 v127, v127
	v_exp_f32_e32 v128, v128
	v_exp_f32_e32 v129, v129
	v_add_f32_e32 v122, 1.0, v122
	v_add_f32_e32 v123, 1.0, v123
	v_add_f32_e32 v124, 1.0, v124
	v_add_f32_e32 v125, 1.0, v125
	v_add_f32_e32 v126, 1.0, v126
	v_add_f32_e32 v127, 1.0, v127
	v_add_f32_e32 v128, 1.0, v128
	v_add_f32_e32 v129, 1.0, v129
	v_rcp_f32_e32 v122, v122
	v_rcp_f32_e32 v123, v123
	v_rcp_f32_e32 v124, v124
	v_rcp_f32_e32 v125, v125
	v_rcp_f32_e32 v126, v126
	v_rcp_f32_e32 v127, v127
	v_rcp_f32_e32 v128, v128
	v_rcp_f32_e32 v129, v129
	v_lshlrev_b32_e32 v146, 16, v148
	v_and_b32_e32 v147, 0xffff0000, v148
	v_pk_mul_f32 v[122:123], v[122:123], v[146:147]
	v_lshlrev_b32_e32 v190, 16, v149
	v_and_b32_e32 v191, 0xffff0000, v149
	v_pk_mul_f32 v[124:125], v[124:125], v[190:191]
	v_lshlrev_b32_e32 v146, 16, v150
	v_and_b32_e32 v147, 0xffff0000, v150
	v_pk_mul_f32 v[126:127], v[126:127], v[146:147]
	v_lshlrev_b32_e32 v190, 16, v151
	v_and_b32_e32 v191, 0xffff0000, v151
	v_pk_mul_f32 v[128:129], v[128:129], v[190:191]
	v_cvt_pk_bf16_f32 v148, v122, v123
	v_cvt_pk_bf16_f32 v149, v124, v125
	v_cvt_pk_bf16_f32 v150, v126, v127
	v_cvt_pk_bf16_f32 v151, v128, v129
	global_store_dwordx4 v[176:177], v[148:151], off
	v_add_f32_e32 v118, v118, v138
	v_add_f32_e32 v119, v119, v139
	v_add_f32_e32 v120, v120, v140
	v_add_f32_e32 v121, v121, v141
	v_add_f32_e32 v114, v114, v142
	v_add_f32_e32 v115, v115, v143
	v_add_f32_e32 v116, v116, v144
	v_add_f32_e32 v117, v117, v145
	v_mul_f32_e32 v118, 0xbfb8aa3b, v118
	v_mul_f32_e32 v119, 0xbfb8aa3b, v119
	v_mul_f32_e32 v120, 0xbfb8aa3b, v120
	v_mul_f32_e32 v121, 0xbfb8aa3b, v121
	v_mul_f32_e32 v114, 0xbfb8aa3b, v114
	v_mul_f32_e32 v115, 0xbfb8aa3b, v115
	v_mul_f32_e32 v116, 0xbfb8aa3b, v116
	v_mul_f32_e32 v117, 0xbfb8aa3b, v117
	v_exp_f32_e32 v118, v118
	v_exp_f32_e32 v119, v119
	v_exp_f32_e32 v120, v120
	v_exp_f32_e32 v121, v121
	v_exp_f32_e32 v114, v114
	v_exp_f32_e32 v115, v115
	v_exp_f32_e32 v116, v116
	v_exp_f32_e32 v117, v117
	v_add_f32_e32 v118, 1.0, v118
	v_add_f32_e32 v119, 1.0, v119
	v_add_f32_e32 v120, 1.0, v120
	v_add_f32_e32 v121, 1.0, v121
	v_add_f32_e32 v114, 1.0, v114
	v_add_f32_e32 v115, 1.0, v115
	v_add_f32_e32 v116, 1.0, v116
	v_add_f32_e32 v117, 1.0, v117
	v_rcp_f32_e32 v118, v118
	v_rcp_f32_e32 v119, v119
	v_rcp_f32_e32 v120, v120
	v_rcp_f32_e32 v121, v121
	v_rcp_f32_e32 v114, v114
	v_rcp_f32_e32 v115, v115
	v_rcp_f32_e32 v116, v116
	v_rcp_f32_e32 v117, v117
	v_lshlrev_b32_e32 v146, 16, v156
	v_and_b32_e32 v147, 0xffff0000, v156
	v_pk_mul_f32 v[118:119], v[118:119], v[146:147]
	v_lshlrev_b32_e32 v190, 16, v157
	v_and_b32_e32 v191, 0xffff0000, v157
	v_pk_mul_f32 v[120:121], v[120:121], v[190:191]
	v_lshlrev_b32_e32 v146, 16, v158
	v_and_b32_e32 v147, 0xffff0000, v158
	v_pk_mul_f32 v[114:115], v[114:115], v[146:147]
	v_lshlrev_b32_e32 v190, 16, v159
	v_and_b32_e32 v191, 0xffff0000, v159
	v_pk_mul_f32 v[116:117], v[116:117], v[190:191]
	v_cvt_pk_bf16_f32 v156, v118, v119
	v_cvt_pk_bf16_f32 v157, v120, v121
	v_cvt_pk_bf16_f32 v158, v114, v115
	v_cvt_pk_bf16_f32 v159, v116, v117
	global_store_dwordx4 v[176:177], v[156:159], off offset:64
	s_add_u32 s40, s44, 0x18000
	s_addc_u32 s41, s45, 0
	v_lshl_add_u64 v[146:147], v[164:165], 0, s[40:41]
	global_load_dwordx4 v[148:151], v[146:147], off
	global_load_dwordx4 v[156:159], v[146:147], off offset:64
	s_waitcnt vmcnt(6)
; #define GAS __attribute__((address_space(1)))
; DI unsigned pk2(float lo, float hi) { f32x2 v = {lo, hi}; bf16x2_t b = __builtin_convertvector(v, bf16x2_t); return __builtin_bit_cast(unsigned, b); }
; DI float fast_exp2(float x) { return __builtin_amdgcn_exp2f(x); }
; DI float fast_rcp(float x) { return __builtin_amdgcn_rcpf(x); }
;     DI void operator()(const f32x4 (&acc)[2][2][4][2], const Unit& u, int wr, int wc, int fr, int fq) const {
;     ...
;                     for (int bj = 0; bj < 2; ++bj) { brv[bj] = *(const GAS u32x4*)(BR + offb + bj * 32); mgv[bj] = (gi > 0) ? *(const GAS u32x4*)(MG + offb + bj * 32) : (u32x4){0, 0, 0, 0}; }
; #pragma unroll
;                     for (int bj = 0; bj < 2; ++bj) { const size_t off = offb + bj * 32; const u32x4 br = brv[bj], mg = mgv[bj];
;                         f32x4 x0 = acc[ai][bj][m][0] + bb[bj][0], x1 = acc[ai][bj][m][1] + bb[bj][1]; float v[8];
;                         const float bv[8] = {__uint_as_float(br.x << 16), __uint_as_float(br.x & 0xffff0000u), __uint_as_float(br.y << 16), __uint_as_float(br.y & 0xffff0000u),
;                                              __uint_as_float(br.z << 16), __uint_as_float(br.z & 0xffff0000u), __uint_as_float(br.w << 16), __uint_as_float(br.w & 0xffff0000u)};
; #pragma unroll
;                         for (int j = 0; j < 4; ++j) { v[j] = fast_rcp(1.0f + fast_exp2(-x0[j] * LOG2E)) * bv[j]; v[4 + j] = fast_rcp(1.0f + fast_exp2(-x1[j] * LOG2E)) * bv[4 + j]; }
;                         v[0] += __uint_as_float(mg.x << 16); v[1] += __uint_as_float(mg.x & 0xffff0000u); v[2] += __uint_as_float(mg.y << 16); v[3] += __uint_as_float(mg.y & 0xffff0000u);
;                         v[4] += __uint_as_float(mg.z << 16); v[5] += __uint_as_float(mg.z & 0xffff0000u); v[6] += __uint_as_float(mg.w << 16); v[7] += __uint_as_float(mg.w & 0xffff0000u);
;                         u32x4 w; w.x = pk2(v[0], v[1]); w.y = pk2(v[2], v[3]); w.z = pk2(v[4], v[5]); w.w = pk2(v[6], v[7]);
;                         if (gi < 3) *(GAS u32x4*)(MG + off) = w; else *(GAS u32x4*)(BR + off) = w; } }
	s_add_u32 s40, s0, 0x8000
	s_addc_u32 s41, s1, 0
	v_lshl_add_u64 v[176:177], v[164:165], 0, s[40:41]
	v_add_f32_e32 v110, v110, v130
	v_add_f32_e32 v111, v111, v131
	v_add_f32_e32 v112, v112, v132
	v_add_f32_e32 v113, v113, v133
	v_add_f32_e32 v106, v106, v134
	v_add_f32_e32 v107, v107, v135
	v_add_f32_e32 v108, v108, v136
	v_add_f32_e32 v109, v109, v137
	v_mul_f32_e32 v110, 0xbfb8aa3b, v110
	v_mul_f32_e32 v111, 0xbfb8aa3b, v111
	v_mul_f32_e32 v112, 0xbfb8aa3b, v112
	v_mul_f32_e32 v113, 0xbfb8aa3b, v113
	v_mul_f32_e32 v106, 0xbfb8aa3b, v106
	v_mul_f32_e32 v107, 0xbfb8aa3b, v107
	v_mul_f32_e32 v108, 0xbfb8aa3b, v108
	v_mul_f32_e32 v109, 0xbfb8aa3b, v109
	v_exp_f32_e32 v110, v110
	v_exp_f32_e32 v111, v111
	v_exp_f32_e32 v112, v112
	v_exp_f32_e32 v113, v113
	v_exp_f32_e32 v106, v106
	v_exp_f32_e32 v107, v107
	v_exp_f32_e32 v108, v108
	v_exp_f32_e32 v109, v109
	v_add_f32_e32 v110, 1.0, v110
	v_add_f32_e32 v111, 1.0, v111
	v_add_f32_e32 v112, 1.0, v112
	v_add_f32_e32 v113, 1.0, v113
	v_add_f32_e32 v106, 1.0, v106
	v_add_f32_e32 v107, 1.0, v107
	v_add_f32_e32 v108, 1.0, v108
	v_add_f32_e32 v109, 1.0, v109
	v_rcp_f32_e32 v110, v110
	v_rcp_f32_e32 v111, v111
	v_rcp_f32_e32 v112, v112
	v_rcp_f32_e32 v113, v113
	v_rcp_f32_e32 v106, v106
	v_rcp_f32_e32 v107, v107
	v_rcp_f32_e32 v108, v108
	v_rcp_f32_e32 v109, v109
	v_lshlrev_b32_e32 v146, 16, v236
	v_and_b32_e32 v147, 0xffff0000, v236
	v_pk_mul_f32 v[110:111], v[110:111], v[146:147]
	v_lshlrev_b32_e32 v190, 16, v237
	v_and_b32_e32 v191, 0xffff0000, v237
	v_pk_mul_f32 v[112:113], v[112:113], v[190:191]
	v_lshlrev_b32_e32 v146, 16, v238
	v_and_b32_e32 v147, 0xffff0000, v238
	v_pk_mul_f32 v[106:107], v[106:107], v[146:147]
	v_lshlrev_b32_e32 v190, 16, v239
	v_and_b32_e32 v191, 0xffff0000, v239
	v_pk_mul_f32 v[108:109], v[108:109], v[190:191]
	v_cvt_pk_bf16_f32 v236, v110, v111
	v_cvt_pk_bf16_f32 v237, v112, v113
	v_cvt_pk_bf16_f32 v238, v106, v107
	v_cvt_pk_bf16_f32 v239, v108, v109
	global_store_dwordx4 v[176:177], v[236:239], off
	v_add_f32_e32 v102, v102, v138
	v_add_f32_e32 v103, v103, v139
	v_add_f32_e32 v104, v104, v140
	v_add_f32_e32 v105, v105, v141
	v_add_f32_e32 v98, v98, v142
	v_add_f32_e32 v99, v99, v143
	v_add_f32_e32 v100, v100, v144
	v_add_f32_e32 v101, v101, v145
	v_mul_f32_e32 v102, 0xbfb8aa3b, v102
	v_mul_f32_e32 v103, 0xbfb8aa3b, v103
	v_mul_f32_e32 v104, 0xbfb8aa3b, v104
	v_mul_f32_e32 v105, 0xbfb8aa3b, v105
	v_mul_f32_e32 v98, 0xbfb8aa3b, v98
	v_mul_f32_e32 v99, 0xbfb8aa3b, v99
	v_mul_f32_e32 v100, 0xbfb8aa3b, v100
	v_mul_f32_e32 v101, 0xbfb8aa3b, v101
	v_exp_f32_e32 v102, v102
	v_exp_f32_e32 v103, v103
	v_exp_f32_e32 v104, v104
	v_exp_f32_e32 v105, v105
	v_exp_f32_e32 v98, v98
	v_exp_f32_e32 v99, v99
	v_exp_f32_e32 v100, v100
	v_exp_f32_e32 v101, v101
	v_add_f32_e32 v102, 1.0, v102
	v_add_f32_e32 v103, 1.0, v103
	v_add_f32_e32 v104, 1.0, v104
	v_add_f32_e32 v105, 1.0, v105
	v_add_f32_e32 v98, 1.0, v98
	v_add_f32_e32 v99, 1.0, v99
	v_add_f32_e32 v100, 1.0, v100
	v_add_f32_e32 v101, 1.0, v101
	v_rcp_f32_e32 v102, v102
	v_rcp_f32_e32 v103, v103
	v_rcp_f32_e32 v104, v104
	v_rcp_f32_e32 v105, v105
	v_rcp_f32_e32 v98, v98
	v_rcp_f32_e32 v99, v99
	v_rcp_f32_e32 v100, v100
	v_rcp_f32_e32 v101, v101
	v_lshlrev_b32_e32 v146, 16, v244
	v_and_b32_e32 v147, 0xffff0000, v244
	v_pk_mul_f32 v[102:103], v[102:103], v[146:147]
	v_lshlrev_b32_e32 v190, 16, v245
	v_and_b32_e32 v191, 0xffff0000, v245
	v_pk_mul_f32 v[104:105], v[104:105], v[190:191]
	v_lshlrev_b32_e32 v146, 16, v246
	v_and_b32_e32 v147, 0xffff0000, v246
	v_pk_mul_f32 v[98:99], v[98:99], v[146:147]
	v_lshlrev_b32_e32 v190, 16, v247
	v_and_b32_e32 v191, 0xffff0000, v247
	v_pk_mul_f32 v[100:101], v[100:101], v[190:191]
	v_cvt_pk_bf16_f32 v244, v102, v103
	v_cvt_pk_bf16_f32 v245, v104, v105
	v_cvt_pk_bf16_f32 v246, v98, v99
	v_cvt_pk_bf16_f32 v247, v100, v101
	global_store_dwordx4 v[176:177], v[244:247], off offset:64
	s_add_u32 s40, s44, 0x40000
	s_addc_u32 s41, s45, 0
	v_lshl_add_u64 v[146:147], v[164:165], 0, s[40:41]
	global_load_dwordx4 v[236:239], v[146:147], off
	global_load_dwordx4 v[244:247], v[146:147], off offset:64
	s_waitcnt vmcnt(8)
	s_add_u32 s40, s0, 0x10000
	s_addc_u32 s41, s1, 0
	v_lshl_add_u64 v[176:177], v[164:165], 0, s[40:41]
	v_add_f32_e32 v94, v94, v130
	v_add_f32_e32 v95, v95, v131
	v_add_f32_e32 v96, v96, v132
	v_add_f32_e32 v97, v97, v133
	v_add_f32_e32 v90, v90, v134
	v_add_f32_e32 v91, v91, v135
	v_add_f32_e32 v92, v92, v136
	v_add_f32_e32 v93, v93, v137
	v_mul_f32_e32 v94, 0xbfb8aa3b, v94
	v_mul_f32_e32 v95, 0xbfb8aa3b, v95
	v_mul_f32_e32 v96, 0xbfb8aa3b, v96
	v_mul_f32_e32 v97, 0xbfb8aa3b, v97
	v_mul_f32_e32 v90, 0xbfb8aa3b, v90
	v_mul_f32_e32 v91, 0xbfb8aa3b, v91
	v_mul_f32_e32 v92, 0xbfb8aa3b, v92
	v_mul_f32_e32 v93, 0xbfb8aa3b, v93
	v_exp_f32_e32 v94, v94
	v_exp_f32_e32 v95, v95
	v_exp_f32_e32 v96, v96
	v_exp_f32_e32 v97, v97
	v_exp_f32_e32 v90, v90
	v_exp_f32_e32 v91, v91
	v_exp_f32_e32 v92, v92
	v_exp_f32_e32 v93, v93
	v_add_f32_e32 v94, 1.0, v94
	v_add_f32_e32 v95, 1.0, v95
	v_add_f32_e32 v96, 1.0, v96
	v_add_f32_e32 v97, 1.0, v97
	v_add_f32_e32 v90, 1.0, v90
	v_add_f32_e32 v91, 1.0, v91
	v_add_f32_e32 v92, 1.0, v92
	v_add_f32_e32 v93, 1.0, v93
	v_rcp_f32_e32 v94, v94
	v_rcp_f32_e32 v95, v95
	v_rcp_f32_e32 v96, v96
	v_rcp_f32_e32 v97, v97
	v_rcp_f32_e32 v90, v90
	v_rcp_f32_e32 v91, v91
	v_rcp_f32_e32 v92, v92
	v_rcp_f32_e32 v93, v93
	v_lshlrev_b32_e32 v146, 16, v194
	v_and_b32_e32 v147, 0xffff0000, v194
	v_pk_mul_f32 v[94:95], v[94:95], v[146:147]
	v_lshlrev_b32_e32 v190, 16, v195
	v_and_b32_e32 v191, 0xffff0000, v195
	v_pk_mul_f32 v[96:97], v[96:97], v[190:191]
	v_lshlrev_b32_e32 v146, 16, v196
; #define GAS __attribute__((address_space(1)))
; DI unsigned pk2(float lo, float hi) { f32x2 v = {lo, hi}; bf16x2_t b = __builtin_convertvector(v, bf16x2_t); return __builtin_bit_cast(unsigned, b); }
; DI float fast_exp2(float x) { return __builtin_amdgcn_exp2f(x); }
; DI float fast_rcp(float x) { return __builtin_amdgcn_rcpf(x); }
;     DI void operator()(const f32x4 (&acc)[2][2][4][2], const Unit& u, int wr, int wc, int fr, int fq) const {
;     ...
;                     for (int bj = 0; bj < 2; ++bj) { brv[bj] = *(const GAS u32x4*)(BR + offb + bj * 32); mgv[bj] = (gi > 0) ? *(const GAS u32x4*)(MG + offb + bj * 32) : (u32x4){0, 0, 0, 0}; }
; #pragma unroll
;                     for (int bj = 0; bj < 2; ++bj) { const size_t off = offb + bj * 32; const u32x4 br = brv[bj], mg = mgv[bj];
;                         f32x4 x0 = acc[ai][bj][m][0] + bb[bj][0], x1 = acc[ai][bj][m][1] + bb[bj][1]; float v[8];
;                         const float bv[8] = {__uint_as_float(br.x << 16), __uint_as_float(br.x & 0xffff0000u), __uint_as_float(br.y << 16), __uint_as_float(br.y & 0xffff0000u),
;                                              __uint_as_float(br.z << 16), __uint_as_float(br.z & 0xffff0000u), __uint_as_float(br.w << 16), __uint_as_float(br.w & 0xffff0000u)};
; #pragma unroll
;                         for (int j = 0; j < 4; ++j) { v[j] = fast_rcp(1.0f + fast_exp2(-x0[j] * LOG2E)) * bv[j]; v[4 + j] = fast_rcp(1.0f + fast_exp2(-x1[j] * LOG2E)) * bv[4 + j]; }
;                         v[0] += __uint_as_float(mg.x << 16); v[1] += __uint_as_float(mg.x & 0xffff0000u); v[2] += __uint_as_float(mg.y << 16); v[3] += __uint_as_float(mg.y & 0xffff0000u);
;                         v[4] += __uint_as_float(mg.z << 16); v[5] += __uint_as_float(mg.z & 0xffff0000u); v[6] += __uint_as_float(mg.w << 16); v[7] += __uint_as_float(mg.w & 0xffff0000u);
;                         u32x4 w; w.x = pk2(v[0], v[1]); w.y = pk2(v[2], v[3]); w.z = pk2(v[4], v[5]); w.w = pk2(v[6], v[7]);
;                         if (gi < 3) *(GAS u32x4*)(MG + off) = w; else *(GAS u32x4*)(BR + off) = w; } }
	v_and_b32_e32 v147, 0xffff0000, v196
	v_pk_mul_f32 v[90:91], v[90:91], v[146:147]
	v_lshlrev_b32_e32 v190, 16, v197
	v_and_b32_e32 v191, 0xffff0000, v197
	v_pk_mul_f32 v[92:93], v[92:93], v[190:191]
	v_cvt_pk_bf16_f32 v194, v94, v95
	v_cvt_pk_bf16_f32 v195, v96, v97
	v_cvt_pk_bf16_f32 v196, v90, v91
	v_cvt_pk_bf16_f32 v197, v92, v93
	global_store_dwordx4 v[176:177], v[194:197], off
	v_add_f32_e32 v86, v86, v138
	v_add_f32_e32 v87, v87, v139
	v_add_f32_e32 v88, v88, v140
	v_add_f32_e32 v89, v89, v141
	v_add_f32_e32 v82, v82, v142
	v_add_f32_e32 v83, v83, v143
	v_add_f32_e32 v84, v84, v144
	v_add_f32_e32 v85, v85, v145
	v_mul_f32_e32 v86, 0xbfb8aa3b, v86
	v_mul_f32_e32 v87, 0xbfb8aa3b, v87
	v_mul_f32_e32 v88, 0xbfb8aa3b, v88
	v_mul_f32_e32 v89, 0xbfb8aa3b, v89
	v_mul_f32_e32 v82, 0xbfb8aa3b, v82
	v_mul_f32_e32 v83, 0xbfb8aa3b, v83
	v_mul_f32_e32 v84, 0xbfb8aa3b, v84
	v_mul_f32_e32 v85, 0xbfb8aa3b, v85
	v_exp_f32_e32 v86, v86
	v_exp_f32_e32 v87, v87
	v_exp_f32_e32 v88, v88
	v_exp_f32_e32 v89, v89
	v_exp_f32_e32 v82, v82
	v_exp_f32_e32 v83, v83
	v_exp_f32_e32 v84, v84
	v_exp_f32_e32 v85, v85
	v_add_f32_e32 v86, 1.0, v86
	v_add_f32_e32 v87, 1.0, v87
	v_add_f32_e32 v88, 1.0, v88
	v_add_f32_e32 v89, 1.0, v89
	v_add_f32_e32 v82, 1.0, v82
	v_add_f32_e32 v83, 1.0, v83
	v_add_f32_e32 v84, 1.0, v84
	v_add_f32_e32 v85, 1.0, v85
	v_rcp_f32_e32 v86, v86
	v_rcp_f32_e32 v87, v87
	v_rcp_f32_e32 v88, v88
	v_rcp_f32_e32 v89, v89
	v_rcp_f32_e32 v82, v82
	v_rcp_f32_e32 v83, v83
	v_rcp_f32_e32 v84, v84
	v_rcp_f32_e32 v85, v85
	v_lshlrev_b32_e32 v146, 16, v204
	v_and_b32_e32 v147, 0xffff0000, v204
	v_pk_mul_f32 v[86:87], v[86:87], v[146:147]
	v_lshlrev_b32_e32 v190, 16, v205
	v_and_b32_e32 v191, 0xffff0000, v205
	v_pk_mul_f32 v[88:89], v[88:89], v[190:191]
	v_lshlrev_b32_e32 v146, 16, v206
	v_and_b32_e32 v147, 0xffff0000, v206
	v_pk_mul_f32 v[82:83], v[82:83], v[146:147]
	v_lshlrev_b32_e32 v190, 16, v207
	v_and_b32_e32 v191, 0xffff0000, v207
	v_pk_mul_f32 v[84:85], v[84:85], v[190:191]
	v_cvt_pk_bf16_f32 v204, v86, v87
	v_cvt_pk_bf16_f32 v205, v88, v89
	v_cvt_pk_bf16_f32 v206, v82, v83
	v_cvt_pk_bf16_f32 v207, v84, v85
	global_store_dwordx4 v[176:177], v[204:207], off offset:64
	s_add_u32 s40, s44, 0x48000
	s_addc_u32 s41, s45, 0
	v_lshl_add_u64 v[146:147], v[164:165], 0, s[40:41]
	global_load_dwordx4 v[194:197], v[146:147], off
	global_load_dwordx4 v[204:207], v[146:147], off offset:64
	s_waitcnt vmcnt(8)
	s_add_u32 s40, s0, 0x18000
	s_addc_u32 s41, s1, 0
	v_lshl_add_u64 v[176:177], v[164:165], 0, s[40:41]
	v_add_f32_e32 v78, v78, v130
	v_add_f32_e32 v79, v79, v131
	v_add_f32_e32 v80, v80, v132
	v_add_f32_e32 v81, v81, v133
	v_add_f32_e32 v74, v74, v134
	v_add_f32_e32 v75, v75, v135
	v_add_f32_e32 v76, v76, v136
	v_add_f32_e32 v77, v77, v137
	v_mul_f32_e32 v78, 0xbfb8aa3b, v78
	v_mul_f32_e32 v79, 0xbfb8aa3b, v79
	v_mul_f32_e32 v80, 0xbfb8aa3b, v80
	v_mul_f32_e32 v81, 0xbfb8aa3b, v81
	v_mul_f32_e32 v74, 0xbfb8aa3b, v74
	v_mul_f32_e32 v75, 0xbfb8aa3b, v75
	v_mul_f32_e32 v76, 0xbfb8aa3b, v76
	v_mul_f32_e32 v77, 0xbfb8aa3b, v77
	v_exp_f32_e32 v78, v78
	v_exp_f32_e32 v79, v79
	v_exp_f32_e32 v80, v80
	v_exp_f32_e32 v81, v81
	v_exp_f32_e32 v74, v74
	v_exp_f32_e32 v75, v75
	v_exp_f32_e32 v76, v76
	v_exp_f32_e32 v77, v77
	v_add_f32_e32 v78, 1.0, v78
	v_add_f32_e32 v79, 1.0, v79
	v_add_f32_e32 v80, 1.0, v80
	v_add_f32_e32 v81, 1.0, v81
	v_add_f32_e32 v74, 1.0, v74
	v_add_f32_e32 v75, 1.0, v75
	v_add_f32_e32 v76, 1.0, v76
	v_add_f32_e32 v77, 1.0, v77
	v_rcp_f32_e32 v78, v78
	v_rcp_f32_e32 v79, v79
	v_rcp_f32_e32 v80, v80
	v_rcp_f32_e32 v81, v81
	v_rcp_f32_e32 v74, v74
	v_rcp_f32_e32 v75, v75
	v_rcp_f32_e32 v76, v76
	v_rcp_f32_e32 v77, v77
	v_lshlrev_b32_e32 v146, 16, v148
	v_and_b32_e32 v147, 0xffff0000, v148
	v_pk_mul_f32 v[78:79], v[78:79], v[146:147]
	v_lshlrev_b32_e32 v190, 16, v149
	v_and_b32_e32 v191, 0xffff0000, v149
	v_pk_mul_f32 v[80:81], v[80:81], v[190:191]
	v_lshlrev_b32_e32 v146, 16, v150
	v_and_b32_e32 v147, 0xffff0000, v150
	v_pk_mul_f32 v[74:75], v[74:75], v[146:147]
	v_lshlrev_b32_e32 v190, 16, v151
	v_and_b32_e32 v191, 0xffff0000, v151
	v_pk_mul_f32 v[76:77], v[76:77], v[190:191]
	v_cvt_pk_bf16_f32 v148, v78, v79
	v_cvt_pk_bf16_f32 v149, v80, v81
	v_cvt_pk_bf16_f32 v150, v74, v75
	v_cvt_pk_bf16_f32 v151, v76, v77
	global_store_dwordx4 v[176:177], v[148:151], off
	v_add_f32_e32 v70, v70, v138
	v_add_f32_e32 v71, v71, v139
	v_add_f32_e32 v72, v72, v140
	v_add_f32_e32 v73, v73, v141
	v_add_f32_e32 v66, v66, v142
	v_add_f32_e32 v67, v67, v143
	v_add_f32_e32 v68, v68, v144
	v_add_f32_e32 v69, v69, v145
	v_mul_f32_e32 v70, 0xbfb8aa3b, v70
	v_mul_f32_e32 v71, 0xbfb8aa3b, v71
	v_mul_f32_e32 v72, 0xbfb8aa3b, v72
	v_mul_f32_e32 v73, 0xbfb8aa3b, v73
	v_mul_f32_e32 v66, 0xbfb8aa3b, v66
	v_mul_f32_e32 v67, 0xbfb8aa3b, v67
	v_mul_f32_e32 v68, 0xbfb8aa3b, v68
	v_mul_f32_e32 v69, 0xbfb8aa3b, v69
	v_exp_f32_e32 v70, v70
	v_exp_f32_e32 v71, v71
	v_exp_f32_e32 v72, v72
	v_exp_f32_e32 v73, v73
	v_exp_f32_e32 v66, v66
	v_exp_f32_e32 v67, v67
	v_exp_f32_e32 v68, v68
	v_exp_f32_e32 v69, v69
	v_add_f32_e32 v70, 1.0, v70
	v_add_f32_e32 v71, 1.0, v71
	v_add_f32_e32 v72, 1.0, v72
	v_add_f32_e32 v73, 1.0, v73
	v_add_f32_e32 v66, 1.0, v66
	v_add_f32_e32 v67, 1.0, v67
	v_add_f32_e32 v68, 1.0, v68
	v_add_f32_e32 v69, 1.0, v69
	v_rcp_f32_e32 v70, v70
	v_rcp_f32_e32 v71, v71
	v_rcp_f32_e32 v72, v72
	v_rcp_f32_e32 v73, v73
	v_rcp_f32_e32 v66, v66
	v_rcp_f32_e32 v67, v67
	v_rcp_f32_e32 v68, v68
	v_rcp_f32_e32 v69, v69
	v_lshlrev_b32_e32 v146, 16, v156
	v_and_b32_e32 v147, 0xffff0000, v156
	v_pk_mul_f32 v[70:71], v[70:71], v[146:147]
	v_lshlrev_b32_e32 v190, 16, v157
	v_and_b32_e32 v191, 0xffff0000, v157
	v_pk_mul_f32 v[72:73], v[72:73], v[190:191]
	v_lshlrev_b32_e32 v146, 16, v158
	v_and_b32_e32 v147, 0xffff0000, v158
	v_pk_mul_f32 v[66:67], v[66:67], v[146:147]
	v_lshlrev_b32_e32 v190, 16, v159
	v_and_b32_e32 v191, 0xffff0000, v159
	v_pk_mul_f32 v[68:69], v[68:69], v[190:191]
	v_cvt_pk_bf16_f32 v156, v70, v71
	v_cvt_pk_bf16_f32 v157, v72, v73
	v_cvt_pk_bf16_f32 v158, v66, v67
	v_cvt_pk_bf16_f32 v159, v68, v69
	global_store_dwordx4 v[176:177], v[156:159], off offset:64
	s_add_u32 s40, s44, 0x50000
	s_addc_u32 s41, s45, 0
	v_lshl_add_u64 v[146:147], v[164:165], 0, s[40:41]
	global_load_dwordx4 v[148:151], v[146:147], off
	global_load_dwordx4 v[156:159], v[146:147], off offset:64
	s_waitcnt vmcnt(8)
; #define GAS __attribute__((address_space(1)))
; DI unsigned pk2(float lo, float hi) { f32x2 v = {lo, hi}; bf16x2_t b = __builtin_convertvector(v, bf16x2_t); return __builtin_bit_cast(unsigned, b); }
; DI float fast_exp2(float x) { return __builtin_amdgcn_exp2f(x); }
; DI float fast_rcp(float x) { return __builtin_amdgcn_rcpf(x); }
;     DI void operator()(const f32x4 (&acc)[2][2][4][2], const Unit& u, int wr, int wc, int fr, int fq) const {
;     ...
;                     for (int bj = 0; bj < 2; ++bj) { brv[bj] = *(const GAS u32x4*)(BR + offb + bj * 32); mgv[bj] = (gi > 0) ? *(const GAS u32x4*)(MG + offb + bj * 32) : (u32x4){0, 0, 0, 0}; }
; #pragma unroll
;                     for (int bj = 0; bj < 2; ++bj) { const size_t off = offb + bj * 32; const u32x4 br = brv[bj], mg = mgv[bj];
;                         f32x4 x0 = acc[ai][bj][m][0] + bb[bj][0], x1 = acc[ai][bj][m][1] + bb[bj][1]; float v[8];
;                         const float bv[8] = {__uint_as_float(br.x << 16), __uint_as_float(br.x & 0xffff0000u), __uint_as_float(br.y << 16), __uint_as_float(br.y & 0xffff0000u),
;                                              __uint_as_float(br.z << 16), __uint_as_float(br.z & 0xffff0000u), __uint_as_float(br.w << 16), __uint_as_float(br.w & 0xffff0000u)};
; #pragma unroll
;                         for (int j = 0; j < 4; ++j) { v[j] = fast_rcp(1.0f + fast_exp2(-x0[j] * LOG2E)) * bv[j]; v[4 + j] = fast_rcp(1.0f + fast_exp2(-x1[j] * LOG2E)) * bv[4 + j]; }
;                         v[0] += __uint_as_float(mg.x << 16); v[1] += __uint_as_float(mg.x & 0xffff0000u); v[2] += __uint_as_float(mg.y << 16); v[3] += __uint_as_float(mg.y & 0xffff0000u);
;                         v[4] += __uint_as_float(mg.z << 16); v[5] += __uint_as_float(mg.z & 0xffff0000u); v[6] += __uint_as_float(mg.w << 16); v[7] += __uint_as_float(mg.w & 0xffff0000u);
;                         u32x4 w; w.x = pk2(v[0], v[1]); w.y = pk2(v[2], v[3]); w.z = pk2(v[4], v[5]); w.w = pk2(v[6], v[7]);
;                         if (gi < 3) *(GAS u32x4*)(MG + off) = w; else *(GAS u32x4*)(BR + off) = w; } }
	s_add_u32 s40, s0, 0x40000
	s_addc_u32 s41, s1, 0
	v_lshl_add_u64 v[176:177], v[164:165], 0, s[40:41]
	v_add_f32_e32 v62, v62, v130
	v_add_f32_e32 v63, v63, v131
	v_add_f32_e32 v64, v64, v132
	v_add_f32_e32 v65, v65, v133
	v_add_f32_e32 v58, v58, v134
	v_add_f32_e32 v59, v59, v135
	v_add_f32_e32 v60, v60, v136
	v_add_f32_e32 v61, v61, v137
	v_mul_f32_e32 v62, 0xbfb8aa3b, v62
	v_mul_f32_e32 v63, 0xbfb8aa3b, v63
	v_mul_f32_e32 v64, 0xbfb8aa3b, v64
	v_mul_f32_e32 v65, 0xbfb8aa3b, v65
	v_mul_f32_e32 v58, 0xbfb8aa3b, v58
	v_mul_f32_e32 v59, 0xbfb8aa3b, v59
	v_mul_f32_e32 v60, 0xbfb8aa3b, v60
	v_mul_f32_e32 v61, 0xbfb8aa3b, v61
	v_exp_f32_e32 v62, v62
	v_exp_f32_e32 v63, v63
	v_exp_f32_e32 v64, v64
	v_exp_f32_e32 v65, v65
	v_exp_f32_e32 v58, v58
	v_exp_f32_e32 v59, v59
	v_exp_f32_e32 v60, v60
	v_exp_f32_e32 v61, v61
	v_add_f32_e32 v62, 1.0, v62
	v_add_f32_e32 v63, 1.0, v63
	v_add_f32_e32 v64, 1.0, v64
	v_add_f32_e32 v65, 1.0, v65
	v_add_f32_e32 v58, 1.0, v58
	v_add_f32_e32 v59, 1.0, v59
	v_add_f32_e32 v60, 1.0, v60
	v_add_f32_e32 v61, 1.0, v61
	v_rcp_f32_e32 v62, v62
	v_rcp_f32_e32 v63, v63
	v_rcp_f32_e32 v64, v64
	v_rcp_f32_e32 v65, v65
	v_rcp_f32_e32 v58, v58
	v_rcp_f32_e32 v59, v59
	v_rcp_f32_e32 v60, v60
	v_rcp_f32_e32 v61, v61
	v_lshlrev_b32_e32 v146, 16, v236
	v_and_b32_e32 v147, 0xffff0000, v236
	v_pk_mul_f32 v[62:63], v[62:63], v[146:147]
	v_lshlrev_b32_e32 v190, 16, v237
	v_and_b32_e32 v191, 0xffff0000, v237
	v_pk_mul_f32 v[64:65], v[64:65], v[190:191]
	v_lshlrev_b32_e32 v146, 16, v238
	v_and_b32_e32 v147, 0xffff0000, v238
	v_pk_mul_f32 v[58:59], v[58:59], v[146:147]
	v_lshlrev_b32_e32 v190, 16, v239
	v_and_b32_e32 v191, 0xffff0000, v239
	v_pk_mul_f32 v[60:61], v[60:61], v[190:191]
	v_cvt_pk_bf16_f32 v236, v62, v63
	v_cvt_pk_bf16_f32 v237, v64, v65
	v_cvt_pk_bf16_f32 v238, v58, v59
	v_cvt_pk_bf16_f32 v239, v60, v61
	global_store_dwordx4 v[176:177], v[236:239], off
	v_add_f32_e32 v54, v54, v138
	v_add_f32_e32 v55, v55, v139
	v_add_f32_e32 v56, v56, v140
	v_add_f32_e32 v57, v57, v141
	v_add_f32_e32 v50, v50, v142
	v_add_f32_e32 v51, v51, v143
	v_add_f32_e32 v52, v52, v144
	v_add_f32_e32 v53, v53, v145
	v_mul_f32_e32 v54, 0xbfb8aa3b, v54
	v_mul_f32_e32 v55, 0xbfb8aa3b, v55
	v_mul_f32_e32 v56, 0xbfb8aa3b, v56
	v_mul_f32_e32 v57, 0xbfb8aa3b, v57
	v_mul_f32_e32 v50, 0xbfb8aa3b, v50
	v_mul_f32_e32 v51, 0xbfb8aa3b, v51
	v_mul_f32_e32 v52, 0xbfb8aa3b, v52
	v_mul_f32_e32 v53, 0xbfb8aa3b, v53
	v_exp_f32_e32 v54, v54
	v_exp_f32_e32 v55, v55
	v_exp_f32_e32 v56, v56
	v_exp_f32_e32 v57, v57
	v_exp_f32_e32 v50, v50
	v_exp_f32_e32 v51, v51
	v_exp_f32_e32 v52, v52
	v_exp_f32_e32 v53, v53
	v_add_f32_e32 v54, 1.0, v54
	v_add_f32_e32 v55, 1.0, v55
	v_add_f32_e32 v56, 1.0, v56
	v_add_f32_e32 v57, 1.0, v57
	v_add_f32_e32 v50, 1.0, v50
	v_add_f32_e32 v51, 1.0, v51
	v_add_f32_e32 v52, 1.0, v52
	v_add_f32_e32 v53, 1.0, v53
	v_rcp_f32_e32 v54, v54
	v_rcp_f32_e32 v55, v55
	v_rcp_f32_e32 v56, v56
	v_rcp_f32_e32 v57, v57
	v_rcp_f32_e32 v50, v50
	v_rcp_f32_e32 v51, v51
	v_rcp_f32_e32 v52, v52
	v_rcp_f32_e32 v53, v53
	v_lshlrev_b32_e32 v146, 16, v244
	v_and_b32_e32 v147, 0xffff0000, v244
	v_pk_mul_f32 v[54:55], v[54:55], v[146:147]
	v_lshlrev_b32_e32 v190, 16, v245
	v_and_b32_e32 v191, 0xffff0000, v245
	v_pk_mul_f32 v[56:57], v[56:57], v[190:191]
	v_lshlrev_b32_e32 v146, 16, v246
	v_and_b32_e32 v147, 0xffff0000, v246
	v_pk_mul_f32 v[50:51], v[50:51], v[146:147]
	v_lshlrev_b32_e32 v190, 16, v247
	v_and_b32_e32 v191, 0xffff0000, v247
	v_pk_mul_f32 v[52:53], v[52:53], v[190:191]
	v_cvt_pk_bf16_f32 v244, v54, v55
	v_cvt_pk_bf16_f32 v245, v56, v57
	v_cvt_pk_bf16_f32 v246, v50, v51
	v_cvt_pk_bf16_f32 v247, v52, v53
	global_store_dwordx4 v[176:177], v[244:247], off offset:64
	s_add_u32 s40, s44, 0x58000
	s_addc_u32 s41, s45, 0
	v_lshl_add_u64 v[146:147], v[164:165], 0, s[40:41]
	global_load_dwordx4 v[236:239], v[146:147], off
	global_load_dwordx4 v[244:247], v[146:147], off offset:64
	s_waitcnt vmcnt(8)
	s_add_u32 s40, s0, 0x48000
	s_addc_u32 s41, s1, 0
	v_lshl_add_u64 v[176:177], v[164:165], 0, s[40:41]
	v_add_f32_e32 v46, v46, v130
	v_add_f32_e32 v47, v47, v131
	v_add_f32_e32 v48, v48, v132
	v_add_f32_e32 v49, v49, v133
	v_add_f32_e32 v42, v42, v134
	v_add_f32_e32 v43, v43, v135
	v_add_f32_e32 v44, v44, v136
	v_add_f32_e32 v45, v45, v137
	v_mul_f32_e32 v46, 0xbfb8aa3b, v46
	v_mul_f32_e32 v47, 0xbfb8aa3b, v47
	v_mul_f32_e32 v48, 0xbfb8aa3b, v48
	v_mul_f32_e32 v49, 0xbfb8aa3b, v49
	v_mul_f32_e32 v42, 0xbfb8aa3b, v42
	v_mul_f32_e32 v43, 0xbfb8aa3b, v43
	v_mul_f32_e32 v44, 0xbfb8aa3b, v44
	v_mul_f32_e32 v45, 0xbfb8aa3b, v45
	v_exp_f32_e32 v46, v46
	v_exp_f32_e32 v47, v47
	v_exp_f32_e32 v48, v48
	v_exp_f32_e32 v49, v49
	v_exp_f32_e32 v42, v42
	v_exp_f32_e32 v43, v43
	v_exp_f32_e32 v44, v44
	v_exp_f32_e32 v45, v45
	v_add_f32_e32 v46, 1.0, v46
	v_add_f32_e32 v47, 1.0, v47
	v_add_f32_e32 v48, 1.0, v48
	v_add_f32_e32 v49, 1.0, v49
	v_add_f32_e32 v42, 1.0, v42
	v_add_f32_e32 v43, 1.0, v43
	v_add_f32_e32 v44, 1.0, v44
	v_add_f32_e32 v45, 1.0, v45
	v_rcp_f32_e32 v46, v46
	v_rcp_f32_e32 v47, v47
	v_rcp_f32_e32 v48, v48
	v_rcp_f32_e32 v49, v49
	v_rcp_f32_e32 v42, v42
	v_rcp_f32_e32 v43, v43
	v_rcp_f32_e32 v44, v44
	v_rcp_f32_e32 v45, v45
	v_lshlrev_b32_e32 v146, 16, v194
	v_and_b32_e32 v147, 0xffff0000, v194
	v_pk_mul_f32 v[46:47], v[46:47], v[146:147]
	v_lshlrev_b32_e32 v190, 16, v195
	v_and_b32_e32 v191, 0xffff0000, v195
	v_pk_mul_f32 v[48:49], v[48:49], v[190:191]
	v_lshlrev_b32_e32 v146, 16, v196
	v_and_b32_e32 v147, 0xffff0000, v196
	v_pk_mul_f32 v[42:43], v[42:43], v[146:147]
	v_lshlrev_b32_e32 v190, 16, v197
	v_and_b32_e32 v191, 0xffff0000, v197
	v_pk_mul_f32 v[44:45], v[44:45], v[190:191]
; #define GAS __attribute__((address_space(1)))
; DI unsigned pk2(float lo, float hi) { f32x2 v = {lo, hi}; bf16x2_t b = __builtin_convertvector(v, bf16x2_t); return __builtin_bit_cast(unsigned, b); }
; DI float fast_exp2(float x) { return __builtin_amdgcn_exp2f(x); }
; DI float fast_rcp(float x) { return __builtin_amdgcn_rcpf(x); }
;     DI void operator()(const f32x4 (&acc)[2][2][4][2], const Unit& u, int wr, int wc, int fr, int fq) const {
;     ...
;                     for (int bj = 0; bj < 2; ++bj) { brv[bj] = *(const GAS u32x4*)(BR + offb + bj * 32); mgv[bj] = (gi > 0) ? *(const GAS u32x4*)(MG + offb + bj * 32) : (u32x4){0, 0, 0, 0}; }
; #pragma unroll
;                     for (int bj = 0; bj < 2; ++bj) { const size_t off = offb + bj * 32; const u32x4 br = brv[bj], mg = mgv[bj];
;                         f32x4 x0 = acc[ai][bj][m][0] + bb[bj][0], x1 = acc[ai][bj][m][1] + bb[bj][1]; float v[8];
;                         const float bv[8] = {__uint_as_float(br.x << 16), __uint_as_float(br.x & 0xffff0000u), __uint_as_float(br.y << 16), __uint_as_float(br.y & 0xffff0000u),
;                                              __uint_as_float(br.z << 16), __uint_as_float(br.z & 0xffff0000u), __uint_as_float(br.w << 16), __uint_as_float(br.w & 0xffff0000u)};
; #pragma unroll
;                         for (int j = 0; j < 4; ++j) { v[j] = fast_rcp(1.0f + fast_exp2(-x0[j] * LOG2E)) * bv[j]; v[4 + j] = fast_rcp(1.0f + fast_exp2(-x1[j] * LOG2E)) * bv[4 + j]; }
;                         v[0] += __uint_as_float(mg.x << 16); v[1] += __uint_as_float(mg.x & 0xffff0000u); v[2] += __uint_as_float(mg.y << 16); v[3] += __uint_as_float(mg.y & 0xffff0000u);
;                         v[4] += __uint_as_float(mg.z << 16); v[5] += __uint_as_float(mg.z & 0xffff0000u); v[6] += __uint_as_float(mg.w << 16); v[7] += __uint_as_float(mg.w & 0xffff0000u);
;                         u32x4 w; w.x = pk2(v[0], v[1]); w.y = pk2(v[2], v[3]); w.z = pk2(v[4], v[5]); w.w = pk2(v[6], v[7]);
;                         if (gi < 3) *(GAS u32x4*)(MG + off) = w; else *(GAS u32x4*)(BR + off) = w; } }
	v_cvt_pk_bf16_f32 v194, v46, v47
	v_cvt_pk_bf16_f32 v195, v48, v49
	v_cvt_pk_bf16_f32 v196, v42, v43
	v_cvt_pk_bf16_f32 v197, v44, v45
	global_store_dwordx4 v[176:177], v[194:197], off
	v_add_f32_e32 v38, v38, v138
	v_add_f32_e32 v39, v39, v139
	v_add_f32_e32 v40, v40, v140
	v_add_f32_e32 v41, v41, v141
	v_add_f32_e32 v34, v34, v142
	v_add_f32_e32 v35, v35, v143
	v_add_f32_e32 v36, v36, v144
	v_add_f32_e32 v37, v37, v145
	v_mul_f32_e32 v38, 0xbfb8aa3b, v38
	v_mul_f32_e32 v39, 0xbfb8aa3b, v39
	v_mul_f32_e32 v40, 0xbfb8aa3b, v40
	v_mul_f32_e32 v41, 0xbfb8aa3b, v41
	v_mul_f32_e32 v34, 0xbfb8aa3b, v34
	v_mul_f32_e32 v35, 0xbfb8aa3b, v35
	v_mul_f32_e32 v36, 0xbfb8aa3b, v36
	v_mul_f32_e32 v37, 0xbfb8aa3b, v37
	v_exp_f32_e32 v38, v38
	v_exp_f32_e32 v39, v39
	v_exp_f32_e32 v40, v40
	v_exp_f32_e32 v41, v41
	v_exp_f32_e32 v34, v34
	v_exp_f32_e32 v35, v35
	v_exp_f32_e32 v36, v36
	v_exp_f32_e32 v37, v37
	v_add_f32_e32 v38, 1.0, v38
	v_add_f32_e32 v39, 1.0, v39
	v_add_f32_e32 v40, 1.0, v40
	v_add_f32_e32 v41, 1.0, v41
	v_add_f32_e32 v34, 1.0, v34
	v_add_f32_e32 v35, 1.0, v35
	v_add_f32_e32 v36, 1.0, v36
	v_add_f32_e32 v37, 1.0, v37
	v_rcp_f32_e32 v38, v38
	v_rcp_f32_e32 v39, v39
	v_rcp_f32_e32 v40, v40
	v_rcp_f32_e32 v41, v41
	v_rcp_f32_e32 v34, v34
	v_rcp_f32_e32 v35, v35
	v_rcp_f32_e32 v36, v36
	v_rcp_f32_e32 v37, v37
	v_lshlrev_b32_e32 v146, 16, v204
	v_and_b32_e32 v147, 0xffff0000, v204
	v_pk_mul_f32 v[38:39], v[38:39], v[146:147]
	v_lshlrev_b32_e32 v190, 16, v205
	v_and_b32_e32 v191, 0xffff0000, v205
	v_pk_mul_f32 v[40:41], v[40:41], v[190:191]
	v_lshlrev_b32_e32 v146, 16, v206
	v_and_b32_e32 v147, 0xffff0000, v206
	v_pk_mul_f32 v[34:35], v[34:35], v[146:147]
	v_lshlrev_b32_e32 v190, 16, v207
	v_and_b32_e32 v191, 0xffff0000, v207
	v_pk_mul_f32 v[36:37], v[36:37], v[190:191]
	v_cvt_pk_bf16_f32 v204, v38, v39
	v_cvt_pk_bf16_f32 v205, v40, v41
	v_cvt_pk_bf16_f32 v206, v34, v35
	v_cvt_pk_bf16_f32 v207, v36, v37
	global_store_dwordx4 v[176:177], v[204:207], off offset:64
	s_waitcnt vmcnt(6)
	s_add_u32 s40, s0, 0x50000
	s_addc_u32 s41, s1, 0
	v_lshl_add_u64 v[176:177], v[164:165], 0, s[40:41]
	v_add_f32_e32 v30, v30, v130
	v_add_f32_e32 v31, v31, v131
	v_add_f32_e32 v32, v32, v132
	v_add_f32_e32 v33, v33, v133
	v_add_f32_e32 v26, v26, v134
	v_add_f32_e32 v27, v27, v135
	v_add_f32_e32 v28, v28, v136
	v_add_f32_e32 v29, v29, v137
	v_mul_f32_e32 v30, 0xbfb8aa3b, v30
	v_mul_f32_e32 v31, 0xbfb8aa3b, v31
	v_mul_f32_e32 v32, 0xbfb8aa3b, v32
	v_mul_f32_e32 v33, 0xbfb8aa3b, v33
	v_mul_f32_e32 v26, 0xbfb8aa3b, v26
	v_mul_f32_e32 v27, 0xbfb8aa3b, v27
	v_mul_f32_e32 v28, 0xbfb8aa3b, v28
	v_mul_f32_e32 v29, 0xbfb8aa3b, v29
	v_exp_f32_e32 v30, v30
	v_exp_f32_e32 v31, v31
	v_exp_f32_e32 v32, v32
	v_exp_f32_e32 v33, v33
	v_exp_f32_e32 v26, v26
	v_exp_f32_e32 v27, v27
	v_exp_f32_e32 v28, v28
	v_exp_f32_e32 v29, v29
	v_add_f32_e32 v30, 1.0, v30
	v_add_f32_e32 v31, 1.0, v31
	v_add_f32_e32 v32, 1.0, v32
	v_add_f32_e32 v33, 1.0, v33
	v_add_f32_e32 v26, 1.0, v26
	v_add_f32_e32 v27, 1.0, v27
	v_add_f32_e32 v28, 1.0, v28
	v_add_f32_e32 v29, 1.0, v29
	v_rcp_f32_e32 v30, v30
	v_rcp_f32_e32 v31, v31
	v_rcp_f32_e32 v32, v32
	v_rcp_f32_e32 v33, v33
	v_rcp_f32_e32 v26, v26
	v_rcp_f32_e32 v27, v27
	v_rcp_f32_e32 v28, v28
	v_rcp_f32_e32 v29, v29
	v_lshlrev_b32_e32 v146, 16, v148
	v_and_b32_e32 v147, 0xffff0000, v148
	v_pk_mul_f32 v[30:31], v[30:31], v[146:147]
	v_lshlrev_b32_e32 v190, 16, v149
	v_and_b32_e32 v191, 0xffff0000, v149
	v_pk_mul_f32 v[32:33], v[32:33], v[190:191]
	v_lshlrev_b32_e32 v146, 16, v150
	v_and_b32_e32 v147, 0xffff0000, v150
	v_pk_mul_f32 v[26:27], v[26:27], v[146:147]
	v_lshlrev_b32_e32 v190, 16, v151
	v_and_b32_e32 v191, 0xffff0000, v151
	v_pk_mul_f32 v[28:29], v[28:29], v[190:191]
	v_cvt_pk_bf16_f32 v148, v30, v31
	v_cvt_pk_bf16_f32 v149, v32, v33
	v_cvt_pk_bf16_f32 v150, v26, v27
	v_cvt_pk_bf16_f32 v151, v28, v29
	global_store_dwordx4 v[176:177], v[148:151], off
	v_add_f32_e32 v22, v22, v138
	v_add_f32_e32 v23, v23, v139
	v_add_f32_e32 v24, v24, v140
	v_add_f32_e32 v25, v25, v141
	v_add_f32_e32 v18, v18, v142
	v_add_f32_e32 v19, v19, v143
	v_add_f32_e32 v20, v20, v144
	v_add_f32_e32 v21, v21, v145
	v_mul_f32_e32 v22, 0xbfb8aa3b, v22
	v_mul_f32_e32 v23, 0xbfb8aa3b, v23
	v_mul_f32_e32 v24, 0xbfb8aa3b, v24
	v_mul_f32_e32 v25, 0xbfb8aa3b, v25
	v_mul_f32_e32 v18, 0xbfb8aa3b, v18
	v_mul_f32_e32 v19, 0xbfb8aa3b, v19
	v_mul_f32_e32 v20, 0xbfb8aa3b, v20
	v_mul_f32_e32 v21, 0xbfb8aa3b, v21
	v_exp_f32_e32 v22, v22
	v_exp_f32_e32 v23, v23
	v_exp_f32_e32 v24, v24
	v_exp_f32_e32 v25, v25
	v_exp_f32_e32 v18, v18
	v_exp_f32_e32 v19, v19
	v_exp_f32_e32 v20, v20
	v_exp_f32_e32 v21, v21
	v_add_f32_e32 v22, 1.0, v22
	v_add_f32_e32 v23, 1.0, v23
	v_add_f32_e32 v24, 1.0, v24
	v_add_f32_e32 v25, 1.0, v25
	v_add_f32_e32 v18, 1.0, v18
	v_add_f32_e32 v19, 1.0, v19
	v_add_f32_e32 v20, 1.0, v20
	v_add_f32_e32 v21, 1.0, v21
	v_rcp_f32_e32 v22, v22
	v_rcp_f32_e32 v23, v23
	v_rcp_f32_e32 v24, v24
	v_rcp_f32_e32 v25, v25
	v_rcp_f32_e32 v18, v18
	v_rcp_f32_e32 v19, v19
	v_rcp_f32_e32 v20, v20
	v_rcp_f32_e32 v21, v21
	v_lshlrev_b32_e32 v146, 16, v156
	v_and_b32_e32 v147, 0xffff0000, v156
	v_pk_mul_f32 v[22:23], v[22:23], v[146:147]
	v_lshlrev_b32_e32 v190, 16, v157
	v_and_b32_e32 v191, 0xffff0000, v157
	v_pk_mul_f32 v[24:25], v[24:25], v[190:191]
	v_lshlrev_b32_e32 v146, 16, v158
	v_and_b32_e32 v147, 0xffff0000, v158
	v_pk_mul_f32 v[18:19], v[18:19], v[146:147]
	v_lshlrev_b32_e32 v190, 16, v159
	v_and_b32_e32 v191, 0xffff0000, v159
	v_pk_mul_f32 v[20:21], v[20:21], v[190:191]
	v_cvt_pk_bf16_f32 v156, v22, v23
	v_cvt_pk_bf16_f32 v157, v24, v25
	v_cvt_pk_bf16_f32 v158, v18, v19
	v_cvt_pk_bf16_f32 v159, v20, v21
	global_store_dwordx4 v[176:177], v[156:159], off offset:64
	s_waitcnt vmcnt(4)
; #define GAS __attribute__((address_space(1)))
; DI unsigned pk2(float lo, float hi) { f32x2 v = {lo, hi}; bf16x2_t b = __builtin_convertvector(v, bf16x2_t); return __builtin_bit_cast(unsigned, b); }
; DI float fast_exp2(float x) { return __builtin_amdgcn_exp2f(x); }
; DI float fast_rcp(float x) { return __builtin_amdgcn_rcpf(x); }
;     DI void operator()(const f32x4 (&acc)[2][2][4][2], const Unit& u, int wr, int wc, int fr, int fq) const {
;     ...
;                     for (int bj = 0; bj < 2; ++bj) { brv[bj] = *(const GAS u32x4*)(BR + offb + bj * 32); mgv[bj] = (gi > 0) ? *(const GAS u32x4*)(MG + offb + bj * 32) : (u32x4){0, 0, 0, 0}; }
; #pragma unroll
;                     for (int bj = 0; bj < 2; ++bj) { const size_t off = offb + bj * 32; const u32x4 br = brv[bj], mg = mgv[bj];
;                         f32x4 x0 = acc[ai][bj][m][0] + bb[bj][0], x1 = acc[ai][bj][m][1] + bb[bj][1]; float v[8];
;                         const float bv[8] = {__uint_as_float(br.x << 16), __uint_as_float(br.x & 0xffff0000u), __uint_as_float(br.y << 16), __uint_as_float(br.y & 0xffff0000u),
;                                              __uint_as_float(br.z << 16), __uint_as_float(br.z & 0xffff0000u), __uint_as_float(br.w << 16), __uint_as_float(br.w & 0xffff0000u)};
; #pragma unroll
;                         for (int j = 0; j < 4; ++j) { v[j] = fast_rcp(1.0f + fast_exp2(-x0[j] * LOG2E)) * bv[j]; v[4 + j] = fast_rcp(1.0f + fast_exp2(-x1[j] * LOG2E)) * bv[4 + j]; }
;                         v[0] += __uint_as_float(mg.x << 16); v[1] += __uint_as_float(mg.x & 0xffff0000u); v[2] += __uint_as_float(mg.y << 16); v[3] += __uint_as_float(mg.y & 0xffff0000u);
;                         v[4] += __uint_as_float(mg.z << 16); v[5] += __uint_as_float(mg.z & 0xffff0000u); v[6] += __uint_as_float(mg.w << 16); v[7] += __uint_as_float(mg.w & 0xffff0000u);
;                         u32x4 w; w.x = pk2(v[0], v[1]); w.y = pk2(v[2], v[3]); w.z = pk2(v[4], v[5]); w.w = pk2(v[6], v[7]);
;                         if (gi < 3) *(GAS u32x4*)(MG + off) = w; else *(GAS u32x4*)(BR + off) = w; } }
	s_add_u32 s40, s0, 0x58000
	s_addc_u32 s41, s1, 0
	v_lshl_add_u64 v[176:177], v[164:165], 0, s[40:41]
	v_add_f32_e32 v14, v14, v130
	v_add_f32_e32 v15, v15, v131
	v_add_f32_e32 v16, v16, v132
	v_add_f32_e32 v17, v17, v133
	v_add_f32_e32 v10, v10, v134
	v_add_f32_e32 v11, v11, v135
	v_add_f32_e32 v12, v12, v136
	v_add_f32_e32 v13, v13, v137
	v_mul_f32_e32 v14, 0xbfb8aa3b, v14
	v_mul_f32_e32 v15, 0xbfb8aa3b, v15
	v_mul_f32_e32 v16, 0xbfb8aa3b, v16
	v_mul_f32_e32 v17, 0xbfb8aa3b, v17
	v_mul_f32_e32 v10, 0xbfb8aa3b, v10
	v_mul_f32_e32 v11, 0xbfb8aa3b, v11
	v_mul_f32_e32 v12, 0xbfb8aa3b, v12
	v_mul_f32_e32 v13, 0xbfb8aa3b, v13
	v_exp_f32_e32 v14, v14
	v_exp_f32_e32 v15, v15
	v_exp_f32_e32 v16, v16
	v_exp_f32_e32 v17, v17
	v_exp_f32_e32 v10, v10
	v_exp_f32_e32 v11, v11
	v_exp_f32_e32 v12, v12
	v_exp_f32_e32 v13, v13
	v_add_f32_e32 v14, 1.0, v14
	v_add_f32_e32 v15, 1.0, v15
	v_add_f32_e32 v16, 1.0, v16
	v_add_f32_e32 v17, 1.0, v17
	v_add_f32_e32 v10, 1.0, v10
	v_add_f32_e32 v11, 1.0, v11
	v_add_f32_e32 v12, 1.0, v12
	v_add_f32_e32 v13, 1.0, v13
	v_rcp_f32_e32 v14, v14
	v_rcp_f32_e32 v15, v15
	v_rcp_f32_e32 v16, v16
	v_rcp_f32_e32 v17, v17
	v_rcp_f32_e32 v10, v10
	v_rcp_f32_e32 v11, v11
	v_rcp_f32_e32 v12, v12
	v_rcp_f32_e32 v13, v13
	v_lshlrev_b32_e32 v146, 16, v236
	v_and_b32_e32 v147, 0xffff0000, v236
	v_pk_mul_f32 v[14:15], v[14:15], v[146:147]
	v_lshlrev_b32_e32 v190, 16, v237
	v_and_b32_e32 v191, 0xffff0000, v237
	v_pk_mul_f32 v[16:17], v[16:17], v[190:191]
	v_lshlrev_b32_e32 v146, 16, v238
	v_and_b32_e32 v147, 0xffff0000, v238
	v_pk_mul_f32 v[10:11], v[10:11], v[146:147]
	v_lshlrev_b32_e32 v190, 16, v239
	v_and_b32_e32 v191, 0xffff0000, v239
	v_pk_mul_f32 v[12:13], v[12:13], v[190:191]
	v_cvt_pk_bf16_f32 v236, v14, v15
	v_cvt_pk_bf16_f32 v237, v16, v17
	v_cvt_pk_bf16_f32 v238, v10, v11
	v_cvt_pk_bf16_f32 v239, v12, v13
	global_store_dwordx4 v[176:177], v[236:239], off
	v_add_f32_e32 v6, v6, v138
	v_add_f32_e32 v7, v7, v139
	v_add_f32_e32 v8, v8, v140
	v_add_f32_e32 v9, v9, v141
	v_add_f32_e32 v2, v2, v142
	v_add_f32_e32 v3, v3, v143
	v_add_f32_e32 v4, v4, v144
	v_add_f32_e32 v5, v5, v145
	v_mul_f32_e32 v6, 0xbfb8aa3b, v6
	v_mul_f32_e32 v7, 0xbfb8aa3b, v7
	v_mul_f32_e32 v8, 0xbfb8aa3b, v8
	v_mul_f32_e32 v9, 0xbfb8aa3b, v9
	v_mul_f32_e32 v2, 0xbfb8aa3b, v2
	v_mul_f32_e32 v3, 0xbfb8aa3b, v3
	v_mul_f32_e32 v4, 0xbfb8aa3b, v4
	v_mul_f32_e32 v5, 0xbfb8aa3b, v5
	v_exp_f32_e32 v6, v6
	v_exp_f32_e32 v7, v7
	v_exp_f32_e32 v8, v8
	v_exp_f32_e32 v9, v9
	v_exp_f32_e32 v2, v2
	v_exp_f32_e32 v3, v3
	v_exp_f32_e32 v4, v4
	v_exp_f32_e32 v5, v5
	v_add_f32_e32 v6, 1.0, v6
	v_add_f32_e32 v7, 1.0, v7
	v_add_f32_e32 v8, 1.0, v8
	v_add_f32_e32 v9, 1.0, v9
	v_add_f32_e32 v2, 1.0, v2
	v_add_f32_e32 v3, 1.0, v3
	v_add_f32_e32 v4, 1.0, v4
	v_add_f32_e32 v5, 1.0, v5
	v_rcp_f32_e32 v6, v6
	v_rcp_f32_e32 v7, v7
	v_rcp_f32_e32 v8, v8
	v_rcp_f32_e32 v9, v9
	v_rcp_f32_e32 v2, v2
	v_rcp_f32_e32 v3, v3
	v_rcp_f32_e32 v4, v4
	v_rcp_f32_e32 v5, v5
	v_lshlrev_b32_e32 v146, 16, v244
	v_and_b32_e32 v147, 0xffff0000, v244
	v_pk_mul_f32 v[6:7], v[6:7], v[146:147]
	v_lshlrev_b32_e32 v190, 16, v245
	v_and_b32_e32 v191, 0xffff0000, v245
	v_pk_mul_f32 v[8:9], v[8:9], v[190:191]
	v_lshlrev_b32_e32 v146, 16, v246
	v_and_b32_e32 v147, 0xffff0000, v246
	v_pk_mul_f32 v[2:3], v[2:3], v[146:147]
	v_lshlrev_b32_e32 v190, 16, v247
	v_and_b32_e32 v191, 0xffff0000, v247
	v_pk_mul_f32 v[4:5], v[4:5], v[190:191]
	v_cvt_pk_bf16_f32 v244, v6, v7
	v_cvt_pk_bf16_f32 v245, v8, v9
	v_cvt_pk_bf16_f32 v246, v2, v3
	v_cvt_pk_bf16_f32 v247, v4, v5
	global_store_dwordx4 v[176:177], v[244:247], off offset:64
